# GEMM loops: LDS-DMA M0 bases folded to m0 = stride + const, 8 intermediate scalar instructions per iteration removed
# baseline (speedup 1.0000x reference)
.LBB0_58:
	s_add_u32 s44, s42, 0x100
	s_addc_u32 s45, s43, 0
	ds_read_b128 v[146:149], v194
	ds_read_b128 v[150:153], v194 offset:1024
	ds_read_b128 v[154:157], v194 offset:2048
	ds_read_b128 v[158:161], v194 offset:3072
	s_cmp_eq_u32 s22, 40
	s_cselect_b32 s49, s1, s45
	s_cselect_b32 s48, s0, s44
	s_cselect_b32 s47, s41, s21
	s_cselect_b32 s46, s40, s20
	s_add_i32 m0, s52, 0xc000
	ds_read_b128 v[162:165], v144
	ds_read_b128 v[166:169], v144 offset:1024
	ds_read_b128 v[170:173], v144 offset:2048
	ds_read_b128 v[174:177], v144 offset:3072
	ds_read_b128 v[178:181], v144 offset:4096
	ds_read_b128 v[182:185], v144 offset:5120
	ds_read_b128 v[186:189], v144 offset:6144
	global_load_lds_dwordx4 v138, s[42:43]
	s_add_i32 m0, s52, 0xe000
	ds_read_b128 v[190:193], v144 offset:7168
	global_load_lds_dwordx4 v140, s[42:43]
	s_waitcnt lgkmcnt(8)
	s_barrier
	s_waitcnt lgkmcnt(0)
	v_mfma_f32_16x16x32_bf16 v[128:131], v[146:149], v[162:165], v[128:131]
	v_mfma_f32_16x16x32_bf16 v[124:127], v[154:157], v[162:165], v[124:127]
	v_mfma_f32_16x16x32_bf16 v[120:123], v[146:149], v[170:173], v[120:123]
	v_mfma_f32_16x16x32_bf16 v[116:119], v[154:157], v[170:173], v[116:119]
	v_mfma_f32_16x16x32_bf16 v[104:107], v[146:149], v[178:181], v[104:107]
	v_mfma_f32_16x16x32_bf16 v[100:103], v[154:157], v[178:181], v[100:103]
	v_mfma_f32_16x16x32_bf16 v[88:91], v[146:149], v[186:189], v[88:91]
	v_mfma_f32_16x16x32_bf16 v[84:87], v[154:157], v[186:189], v[84:87]
	v_mfma_f32_16x16x32_bf16 v[128:131], v[150:153], v[166:169], v[128:131]
	v_mfma_f32_16x16x32_bf16 v[124:127], v[158:161], v[166:169], v[124:127]
	v_mfma_f32_16x16x32_bf16 v[120:123], v[150:153], v[174:177], v[120:123]
	v_mfma_f32_16x16x32_bf16 v[116:119], v[158:161], v[174:177], v[116:119]
	v_mfma_f32_16x16x32_bf16 v[104:107], v[150:153], v[182:185], v[104:107]
	v_mfma_f32_16x16x32_bf16 v[100:103], v[158:161], v[182:185], v[100:103]
	v_mfma_f32_16x16x32_bf16 v[88:91], v[150:153], v[190:193], v[88:91]
	v_mfma_f32_16x16x32_bf16 v[84:87], v[158:161], v[190:193], v[84:87]
	s_barrier
	s_add_i32 m0, s37, 0x10000
	ds_read_b128 v[202:205], v194 offset:16384
	ds_read_b128 v[206:209], v194 offset:17408
	ds_read_b128 v[210:213], v194 offset:18432
	global_load_lds_dwordx4 v132, s[46:47]
	s_add_i32 m0, s37, 0x12000
	ds_read_b128 v[214:217], v194 offset:19456
	global_load_lds_dwordx4 v136, s[46:47]
	s_barrier
	s_waitcnt lgkmcnt(0)
	v_mfma_f32_16x16x32_bf16 v[112:115], v[202:205], v[162:165], v[112:115]
	v_mfma_f32_16x16x32_bf16 v[108:111], v[210:213], v[162:165], v[108:111]
	v_mfma_f32_16x16x32_bf16 v[96:99], v[202:205], v[170:173], v[96:99]
	v_mfma_f32_16x16x32_bf16 v[92:95], v[210:213], v[170:173], v[92:95]
	v_mfma_f32_16x16x32_bf16 v[80:83], v[202:205], v[178:181], v[80:83]
	v_mfma_f32_16x16x32_bf16 v[76:79], v[210:213], v[178:181], v[76:79]
	v_mfma_f32_16x16x32_bf16 v[72:75], v[202:205], v[186:189], v[72:75]
	v_mfma_f32_16x16x32_bf16 v[68:71], v[210:213], v[186:189], v[68:71]
	v_mfma_f32_16x16x32_bf16 v[112:115], v[206:209], v[166:169], v[112:115]
	v_mfma_f32_16x16x32_bf16 v[108:111], v[214:217], v[166:169], v[108:111]
	v_mfma_f32_16x16x32_bf16 v[96:99], v[206:209], v[174:177], v[96:99]
	v_mfma_f32_16x16x32_bf16 v[92:95], v[214:217], v[174:177], v[92:95]
	v_mfma_f32_16x16x32_bf16 v[80:83], v[206:209], v[182:185], v[80:83]
	v_mfma_f32_16x16x32_bf16 v[76:79], v[214:217], v[182:185], v[76:79]
	v_mfma_f32_16x16x32_bf16 v[72:75], v[206:209], v[190:193], v[72:75]
	v_mfma_f32_16x16x32_bf16 v[68:71], v[214:217], v[190:193], v[68:71]
	s_mov_b32 m0, s52
	s_barrier
	ds_read_b128 v[162:165], v144 offset:16384
	ds_read_b128 v[166:169], v144 offset:17408
	ds_read_b128 v[170:173], v144 offset:18432
	ds_read_b128 v[174:177], v144 offset:19456
	ds_read_b128 v[178:181], v144 offset:20480
	ds_read_b128 v[182:185], v144 offset:21504
	ds_read_b128 v[186:189], v144 offset:22528
	global_load_lds_dwordx4 v0, s[48:49]
	s_mov_b32 m0, s53
	ds_read_b128 v[190:193], v144 offset:23552
	global_load_lds_dwordx4 v134, s[48:49]
	s_barrier
	s_waitcnt lgkmcnt(0)
	v_mfma_f32_16x16x32_bf16 v[64:67], v[146:149], v[162:165], v[64:67]
	v_mfma_f32_16x16x32_bf16 v[60:63], v[154:157], v[162:165], v[60:63]
	v_mfma_f32_16x16x32_bf16 v[56:59], v[146:149], v[170:173], v[56:59]
	v_mfma_f32_16x16x32_bf16 v[52:55], v[154:157], v[170:173], v[52:55]
	v_mfma_f32_16x16x32_bf16 v[40:43], v[146:149], v[178:181], v[40:43]
	v_mfma_f32_16x16x32_bf16 v[36:39], v[154:157], v[178:181], v[36:39]
	v_mfma_f32_16x16x32_bf16 v[24:27], v[146:149], v[186:189], v[24:27]
	v_mfma_f32_16x16x32_bf16 v[16:19], v[154:157], v[186:189], v[16:19]
	v_mfma_f32_16x16x32_bf16 v[64:67], v[150:153], v[166:169], v[64:67]
	v_mfma_f32_16x16x32_bf16 v[60:63], v[158:161], v[166:169], v[60:63]
	v_mfma_f32_16x16x32_bf16 v[56:59], v[150:153], v[174:177], v[56:59]
	v_mfma_f32_16x16x32_bf16 v[52:55], v[158:161], v[174:177], v[52:55]
	v_mfma_f32_16x16x32_bf16 v[40:43], v[150:153], v[182:185], v[40:43]
	v_mfma_f32_16x16x32_bf16 v[36:39], v[158:161], v[182:185], v[36:39]
	v_mfma_f32_16x16x32_bf16 v[24:27], v[150:153], v[190:193], v[24:27]
	v_mfma_f32_16x16x32_bf16 v[16:19], v[158:161], v[190:193], v[16:19]
	s_barrier
	s_add_i32 m0, s37, 0x14000
	s_add_u32 s24, s46, 0xb0000
	s_addc_u32 s25, s47, 0
	global_load_lds_dwordx4 v132, s[24:25]
	s_add_i32 m0, s37, 0x16000
	s_waitcnt vmcnt(5)
	global_load_lds_dwordx4 v136, s[24:25]
	s_barrier
	v_mfma_f32_16x16x32_bf16 v[48:51], v[202:205], v[162:165], v[48:51]
	v_mfma_f32_16x16x32_bf16 v[44:47], v[210:213], v[162:165], v[44:47]
	v_mfma_f32_16x16x32_bf16 v[32:35], v[202:205], v[170:173], v[32:35]
	v_mfma_f32_16x16x32_bf16 v[28:31], v[210:213], v[170:173], v[28:31]
	v_mfma_f32_16x16x32_bf16 v[20:23], v[202:205], v[178:181], v[20:23]
	v_mfma_f32_16x16x32_bf16 v[12:15], v[210:213], v[178:181], v[12:15]
	v_mfma_f32_16x16x32_bf16 v[8:11], v[202:205], v[186:189], v[8:11]
	v_mfma_f32_16x16x32_bf16 v[4:7], v[210:213], v[186:189], v[4:7]
	v_mfma_f32_16x16x32_bf16 v[48:51], v[206:209], v[166:169], v[48:51]
	v_mfma_f32_16x16x32_bf16 v[44:47], v[214:217], v[166:169], v[44:47]
	v_mfma_f32_16x16x32_bf16 v[32:35], v[206:209], v[174:177], v[32:35]
	v_mfma_f32_16x16x32_bf16 v[28:31], v[214:217], v[174:177], v[28:31]
	v_mfma_f32_16x16x32_bf16 v[20:23], v[206:209], v[182:185], v[20:23]
	v_mfma_f32_16x16x32_bf16 v[12:15], v[214:217], v[182:185], v[12:15]
	v_mfma_f32_16x16x32_bf16 v[8:11], v[206:209], v[190:193], v[8:11]
	v_mfma_f32_16x16x32_bf16 v[4:7], v[214:217], v[190:193], v[4:7]
	s_barrier
	ds_read_b128 v[146:149], v194 offset:32768
	ds_read_b128 v[150:153], v194 offset:33792
	ds_read_b128 v[154:157], v194 offset:34816
	ds_read_b128 v[158:161], v194 offset:35840
	s_add_u32 s24, s48, 0xb0000
	s_addc_u32 s25, s49, 0
	s_mov_b32 m0, s54
	ds_read_b128 v[162:165], v144 offset:32768
	ds_read_b128 v[166:169], v144 offset:33792
	ds_read_b128 v[170:173], v144 offset:34816
	ds_read_b128 v[174:177], v144 offset:35840
	ds_read_b128 v[178:181], v144 offset:36864
	ds_read_b128 v[182:185], v144 offset:37888
	ds_read_b128 v[186:189], v144 offset:38912
	global_load_lds_dwordx4 v0, s[24:25]
	s_mov_b32 m0, s55
	ds_read_b128 v[190:193], v144 offset:39936
	global_load_lds_dwordx4 v134, s[24:25]
	s_waitcnt lgkmcnt(8)
	s_barrier
	s_waitcnt lgkmcnt(0)
	v_mfma_f32_16x16x32_bf16 v[128:131], v[146:149], v[162:165], v[128:131]
	v_mfma_f32_16x16x32_bf16 v[124:127], v[154:157], v[162:165], v[124:127]
	v_mfma_f32_16x16x32_bf16 v[120:123], v[146:149], v[170:173], v[120:123]
	v_mfma_f32_16x16x32_bf16 v[116:119], v[154:157], v[170:173], v[116:119]
	v_mfma_f32_16x16x32_bf16 v[104:107], v[146:149], v[178:181], v[104:107]
	v_mfma_f32_16x16x32_bf16 v[100:103], v[154:157], v[178:181], v[100:103]
	v_mfma_f32_16x16x32_bf16 v[88:91], v[146:149], v[186:189], v[88:91]
	v_mfma_f32_16x16x32_bf16 v[84:87], v[154:157], v[186:189], v[84:87]
	v_mfma_f32_16x16x32_bf16 v[128:131], v[150:153], v[166:169], v[128:131]
	v_mfma_f32_16x16x32_bf16 v[124:127], v[158:161], v[166:169], v[124:127]
	v_mfma_f32_16x16x32_bf16 v[120:123], v[150:153], v[174:177], v[120:123]
	v_mfma_f32_16x16x32_bf16 v[116:119], v[158:161], v[174:177], v[116:119]
	v_mfma_f32_16x16x32_bf16 v[104:107], v[150:153], v[182:185], v[104:107]
	v_mfma_f32_16x16x32_bf16 v[100:103], v[158:161], v[182:185], v[100:103]
	v_mfma_f32_16x16x32_bf16 v[88:91], v[150:153], v[190:193], v[88:91]
	v_mfma_f32_16x16x32_bf16 v[84:87], v[158:161], v[190:193], v[84:87]
	s_barrier
	s_add_i32 m0, s37, 0x18000
	ds_read_b128 v[202:205], v194 offset:49152
	ds_read_b128 v[206:209], v194 offset:50176
	ds_read_b128 v[210:213], v194 offset:51200
	s_add_u32 s98, s46, 0x80
	s_addc_u32 s99, s47, 0
	global_load_lds_dwordx4 v132, s[98:99]
	s_add_i32 m0, s37, 0x1a000
	ds_read_b128 v[214:217], v194 offset:52224
	global_load_lds_dwordx4 v136, s[98:99]
	s_barrier
	s_waitcnt lgkmcnt(0)
	v_mfma_f32_16x16x32_bf16 v[112:115], v[202:205], v[162:165], v[112:115]
	v_mfma_f32_16x16x32_bf16 v[108:111], v[210:213], v[162:165], v[108:111]
	v_mfma_f32_16x16x32_bf16 v[96:99], v[202:205], v[170:173], v[96:99]
	v_mfma_f32_16x16x32_bf16 v[92:95], v[210:213], v[170:173], v[92:95]
	v_mfma_f32_16x16x32_bf16 v[80:83], v[202:205], v[178:181], v[80:83]
	v_mfma_f32_16x16x32_bf16 v[76:79], v[210:213], v[178:181], v[76:79]
	v_mfma_f32_16x16x32_bf16 v[72:75], v[202:205], v[186:189], v[72:75]
	v_mfma_f32_16x16x32_bf16 v[68:71], v[210:213], v[186:189], v[68:71]
	v_mfma_f32_16x16x32_bf16 v[112:115], v[206:209], v[166:169], v[112:115]
	v_mfma_f32_16x16x32_bf16 v[108:111], v[214:217], v[166:169], v[108:111]
	v_mfma_f32_16x16x32_bf16 v[96:99], v[206:209], v[174:177], v[96:99]
	v_mfma_f32_16x16x32_bf16 v[92:95], v[214:217], v[174:177], v[92:95]
	v_mfma_f32_16x16x32_bf16 v[80:83], v[206:209], v[182:185], v[80:83]
	v_mfma_f32_16x16x32_bf16 v[76:79], v[214:217], v[182:185], v[76:79]
	v_mfma_f32_16x16x32_bf16 v[72:75], v[206:209], v[190:193], v[72:75]
	v_mfma_f32_16x16x32_bf16 v[68:71], v[214:217], v[190:193], v[68:71]
	s_mov_b32 m0, s56
	s_barrier
	ds_read_b128 v[162:165], v144 offset:49152
	ds_read_b128 v[166:169], v144 offset:50176
	ds_read_b128 v[170:173], v144 offset:51200
	ds_read_b128 v[174:177], v144 offset:52224
	ds_read_b128 v[178:181], v144 offset:53248
	ds_read_b128 v[182:185], v144 offset:54272
	ds_read_b128 v[186:189], v144 offset:55296
	s_add_u32 s98, s48, 0x80
	s_addc_u32 s99, s49, 0
	global_load_lds_dwordx4 v0, s[98:99]
	s_mov_b32 m0, s57
	ds_read_b128 v[190:193], v144 offset:56320
	global_load_lds_dwordx4 v134, s[98:99]
	s_barrier
	s_waitcnt lgkmcnt(0)
	v_mfma_f32_16x16x32_bf16 v[64:67], v[146:149], v[162:165], v[64:67]
	v_mfma_f32_16x16x32_bf16 v[60:63], v[154:157], v[162:165], v[60:63]
	v_mfma_f32_16x16x32_bf16 v[56:59], v[146:149], v[170:173], v[56:59]
	v_mfma_f32_16x16x32_bf16 v[52:55], v[154:157], v[170:173], v[52:55]
	v_mfma_f32_16x16x32_bf16 v[40:43], v[146:149], v[178:181], v[40:43]
	v_mfma_f32_16x16x32_bf16 v[36:39], v[154:157], v[178:181], v[36:39]
	v_mfma_f32_16x16x32_bf16 v[24:27], v[146:149], v[186:189], v[24:27]
	v_mfma_f32_16x16x32_bf16 v[16:19], v[154:157], v[186:189], v[16:19]
	v_mfma_f32_16x16x32_bf16 v[64:67], v[150:153], v[166:169], v[64:67]
	v_mfma_f32_16x16x32_bf16 v[60:63], v[158:161], v[166:169], v[60:63]
	v_mfma_f32_16x16x32_bf16 v[56:59], v[150:153], v[174:177], v[56:59]
	v_mfma_f32_16x16x32_bf16 v[52:55], v[158:161], v[174:177], v[52:55]
	v_mfma_f32_16x16x32_bf16 v[40:43], v[150:153], v[182:185], v[40:43]
	v_mfma_f32_16x16x32_bf16 v[36:39], v[158:161], v[182:185], v[36:39]
	v_mfma_f32_16x16x32_bf16 v[24:27], v[150:153], v[190:193], v[24:27]
	v_mfma_f32_16x16x32_bf16 v[16:19], v[158:161], v[190:193], v[16:19]
	s_barrier
	s_add_i32 m0, s37, 0x1c000
	s_add_u32 s24, s46, 0xb0080
	s_addc_u32 s25, s47, 0
	global_load_lds_dwordx4 v132, s[24:25]
	s_add_i32 m0, s37, 0x1e000
	s_waitcnt vmcnt(5)
	global_load_lds_dwordx4 v136, s[24:25]
	s_barrier
	v_mfma_f32_16x16x32_bf16 v[48:51], v[202:205], v[162:165], v[48:51]
	v_mfma_f32_16x16x32_bf16 v[44:47], v[210:213], v[162:165], v[44:47]
	v_mfma_f32_16x16x32_bf16 v[32:35], v[202:205], v[170:173], v[32:35]
	v_mfma_f32_16x16x32_bf16 v[28:31], v[210:213], v[170:173], v[28:31]
	v_mfma_f32_16x16x32_bf16 v[20:23], v[202:205], v[178:181], v[20:23]
	v_mfma_f32_16x16x32_bf16 v[12:15], v[210:213], v[178:181], v[12:15]
	v_mfma_f32_16x16x32_bf16 v[8:11], v[202:205], v[186:189], v[8:11]
	v_mfma_f32_16x16x32_bf16 v[4:7], v[210:213], v[186:189], v[4:7]
	v_mfma_f32_16x16x32_bf16 v[48:51], v[206:209], v[166:169], v[48:51]
	v_mfma_f32_16x16x32_bf16 v[44:47], v[214:217], v[166:169], v[44:47]
	v_mfma_f32_16x16x32_bf16 v[32:35], v[206:209], v[174:177], v[32:35]
	v_mfma_f32_16x16x32_bf16 v[28:31], v[214:217], v[174:177], v[28:31]
	v_mfma_f32_16x16x32_bf16 v[20:23], v[206:209], v[182:185], v[20:23]
	v_mfma_f32_16x16x32_bf16 v[12:15], v[214:217], v[182:185], v[12:15]
	v_mfma_f32_16x16x32_bf16 v[8:11], v[206:209], v[190:193], v[8:11]
	v_mfma_f32_16x16x32_bf16 v[4:7], v[214:217], v[190:193], v[4:7]
	s_add_i32 s22, s22, 2
	s_add_u32 s20, s20, 0x100
	s_addc_u32 s21, s21, 0
	s_cmp_gt_u32 s22, 41
	s_mov_b64 s[42:43], s[44:45]
	s_barrier
	s_cbranch_scc0 .LBB0_58
	v_lshl_add_u32 v146, s61, 8, v142
	v_cvt_pk_bf16_f32 v72, v72, v73
	v_cvt_pk_bf16_f32 v73, v74, v75
	v_cvt_pk_bf16_f32 v74, v68, v69
	v_add_u32_e32 v68, 0x80, v146
	s_lshl_b32 s20, s62, 8
	v_ashrrev_i32_e32 v147, 31, v146
	v_readlane_b32 s22, v252, 10
	v_cvt_pk_bf16_f32 v112, v112, v113
	v_cvt_pk_bf16_f32 v113, v114, v115
	v_cvt_pk_bf16_f32 v114, v108, v109
	v_or_b32_e32 v108, 16, v146
	v_ashrrev_i32_e32 v69, 31, v68
	v_cvt_pk_bf16_f32 v48, v48, v49
	v_cvt_pk_bf16_f32 v49, v50, v51
	v_cvt_pk_bf16_f32 v50, v44, v45
	v_add_u32_e32 v44, 0x90, v146
	s_ashr_i32 s21, s20, 31
	v_lshlrev_b64 v[148:149], 11, v[146:147]
	v_readlane_b32 s23, v252, 11
	v_ashrrev_i32_e32 v109, 31, v108
	v_cvt_pk_bf16_f32 v96, v96, v97
	v_cvt_pk_bf16_f32 v97, v98, v99
	v_cvt_pk_bf16_f32 v98, v92, v93
	v_or_b32_e32 v92, 32, v146
	v_lshlrev_b64 v[68:69], 11, v[68:69]
	v_ashrrev_i32_e32 v45, 31, v44
	v_cvt_pk_bf16_f32 v32, v32, v33
	v_cvt_pk_bf16_f32 v33, v34, v35
	v_cvt_pk_bf16_f32 v34, v28, v29
	v_add_u32_e32 v28, 0xa0, v146
	v_lshl_add_u64 v[148:149], s[22:23], 0, v[148:149]
	s_lshl_b64 s[42:43], s[20:21], 1
	v_lshlrev_b64 v[108:109], 11, v[108:109]
	v_ashrrev_i32_e32 v93, 31, v92
	v_cvt_pk_bf16_f32 v80, v80, v81
	v_cvt_pk_bf16_f32 v81, v82, v83
	v_cvt_pk_bf16_f32 v82, v76, v77
	v_or_b32_e32 v76, 48, v146
	v_lshl_add_u64 v[68:69], s[22:23], 0, v[68:69]
	v_lshlrev_b64 v[44:45], 11, v[44:45]
	v_ashrrev_i32_e32 v29, 31, v28
	v_cvt_pk_bf16_f32 v20, v20, v21
	v_cvt_pk_bf16_f32 v21, v22, v23
	v_cvt_pk_bf16_f32 v22, v12, v13
	v_add_u32_e32 v12, 0xb0, v146
	v_lshl_add_u64 v[148:149], v[148:149], 0, s[42:43]
	v_lshl_add_u64 v[108:109], s[22:23], 0, v[108:109]
	v_lshlrev_b64 v[92:93], 11, v[92:93]
	v_ashrrev_i32_e32 v77, 31, v76
	v_lshl_add_u64 v[68:69], v[68:69], 0, s[42:43]
	v_lshl_add_u64 v[44:45], s[22:23], 0, v[44:45]
	v_lshlrev_b64 v[28:29], 11, v[28:29]
	v_ashrrev_i32_e32 v13, 31, v12
	v_lshl_add_u64 v[148:149], v[148:149], 0, s[72:73]
	v_lshl_add_u64 v[108:109], v[108:109], 0, s[42:43]
	v_lshl_add_u64 v[92:93], s[22:23], 0, v[92:93]
	v_lshlrev_b64 v[76:77], 11, v[76:77]
	v_lshl_add_u64 v[68:69], v[68:69], 0, s[72:73]
	v_lshl_add_u64 v[44:45], v[44:45], 0, s[42:43]
	v_lshl_add_u64 v[28:29], s[22:23], 0, v[28:29]
	v_lshlrev_b64 v[12:13], 11, v[12:13]
	v_lshl_add_u64 v[148:149], v[148:149], 0, v[2:3]
	v_cvt_pk_bf16_f32 v115, v110, v111
	v_lshl_add_u64 v[108:109], v[108:109], 0, s[72:73]
	v_lshl_add_u64 v[92:93], v[92:93], 0, s[42:43]
	v_lshl_add_u64 v[76:77], s[22:23], 0, v[76:77]
	v_lshl_add_u64 v[68:69], v[68:69], 0, v[2:3]
	v_cvt_pk_bf16_f32 v51, v46, v47
	v_lshl_add_u64 v[44:45], v[44:45], 0, s[72:73]
	v_lshl_add_u64 v[28:29], v[28:29], 0, s[42:43]
	v_lshl_add_u64 v[12:13], s[22:23], 0, v[12:13]
	global_store_dwordx4 v[148:149], v[112:115], off offset:256
	v_cvt_pk_bf16_f32 v99, v94, v95
	v_lshl_add_u64 v[92:93], v[92:93], 0, s[72:73]
	v_lshl_add_u64 v[112:113], v[108:109], 0, v[2:3]
	v_lshl_add_u64 v[76:77], v[76:77], 0, s[42:43]
	global_store_dwordx4 v[68:69], v[48:51], off offset:256
	v_cvt_pk_bf16_f32 v35, v30, v31
	v_lshl_add_u64 v[28:29], v[28:29], 0, s[72:73]
	v_lshl_add_u64 v[48:49], v[44:45], 0, v[2:3]
	v_lshl_add_u64 v[12:13], v[12:13], 0, s[42:43]
	global_store_dwordx4 v[112:113], v[96:99], off offset:256
	v_cvt_pk_bf16_f32 v83, v78, v79
	v_lshl_add_u64 v[76:77], v[76:77], 0, s[72:73]
	v_lshl_add_u64 v[96:97], v[92:93], 0, v[2:3]
	global_store_dwordx4 v[48:49], v[32:35], off offset:256
	v_cvt_pk_bf16_f32 v23, v14, v15
	v_lshl_add_u64 v[12:13], v[12:13], 0, s[72:73]
	v_lshl_add_u64 v[32:33], v[28:29], 0, v[2:3]
	v_cvt_pk_bf16_f32 v128, v128, v129
	v_cvt_pk_bf16_f32 v129, v130, v131
	v_cvt_pk_bf16_f32 v130, v124, v125
	v_cvt_pk_bf16_f32 v131, v126, v127
	v_cvt_pk_bf16_f32 v108, v120, v121
	v_cvt_pk_bf16_f32 v109, v122, v123
	v_cvt_pk_bf16_f32 v110, v116, v117
	v_cvt_pk_bf16_f32 v111, v118, v119
	v_cvt_pk_bf16_f32 v92, v104, v105
	v_cvt_pk_bf16_f32 v93, v106, v107
	v_cvt_pk_bf16_f32 v94, v100, v101
	v_cvt_pk_bf16_f32 v95, v102, v103
	global_store_dwordx4 v[96:97], v[80:83], off offset:256
	v_cvt_pk_bf16_f32 v78, v84, v85
	v_cvt_pk_bf16_f32 v79, v86, v87
	v_lshl_add_u64 v[80:81], v[76:77], 0, v[2:3]
	v_cvt_pk_bf16_f32 v76, v88, v89
	v_cvt_pk_bf16_f32 v77, v90, v91
	v_cvt_pk_bf16_f32 v75, v70, v71
	v_cvt_pk_bf16_f32 v64, v64, v65
	v_cvt_pk_bf16_f32 v65, v66, v67
	v_cvt_pk_bf16_f32 v66, v60, v61
	v_cvt_pk_bf16_f32 v67, v62, v63
	v_cvt_pk_bf16_f32 v44, v56, v57
	v_cvt_pk_bf16_f32 v45, v58, v59
	v_cvt_pk_bf16_f32 v46, v52, v53
	v_cvt_pk_bf16_f32 v47, v54, v55
	v_cvt_pk_bf16_f32 v28, v40, v41
	v_cvt_pk_bf16_f32 v29, v42, v43
	v_cvt_pk_bf16_f32 v30, v36, v37
	v_cvt_pk_bf16_f32 v31, v38, v39
	global_store_dwordx4 v[32:33], v[20:23], off offset:256
	v_cvt_pk_bf16_f32 v14, v16, v17
	v_cvt_pk_bf16_f32 v15, v18, v19
	v_lshl_add_u64 v[20:21], v[12:13], 0, v[2:3]
	v_cvt_pk_bf16_f32 v12, v24, v25
	v_cvt_pk_bf16_f32 v13, v26, v27
	v_cvt_pk_bf16_f32 v8, v8, v9
	v_cvt_pk_bf16_f32 v9, v10, v11
	v_cvt_pk_bf16_f32 v10, v4, v5
	v_cvt_pk_bf16_f32 v11, v6, v7
	s_and_b64 vcc, exec, s[38:39]
	s_mov_b32 s62, s59
	s_mov_b32 s61, s60
	s_mov_b64 s[44:45], s[40:41]
	s_mov_b64 s[42:43], s[0:1]
	global_store_dwordx4 v[148:149], v[128:131], off
	global_store_dwordx4 v[112:113], v[108:111], off
	global_store_dwordx4 v[96:97], v[92:95], off
	global_store_dwordx4 v[80:81], v[76:79], off
	global_store_dwordx4 v[80:81], v[72:75], off offset:256
	global_store_dwordx4 v[68:69], v[64:67], off
	global_store_dwordx4 v[48:49], v[44:47], off
	global_store_dwordx4 v[32:33], v[28:31], off
	global_store_dwordx4 v[20:21], v[12:15], off
	global_store_dwordx4 v[20:21], v[8:11], off offset:256
	s_cbranch_vccz .LBB0_51
	s_waitcnt vmcnt(0)
	s_cmpk_gt_u32 s36, 0xff
	s_cbranch_scc1 .LBB0_62
	s_barrier

.LBB0_80:
	s_add_u32 s22, s52, 0xfffc0080
	s_addc_u32 s23, s53, -1
	ds_read_b128 v[52:55], v198
	ds_read_b128 v[56:59], v198 offset:1024
	ds_read_b128 v[60:63], v198 offset:2048
	ds_read_b128 v[64:67], v198 offset:3072
	s_cmp_eq_u32 s21, 12
	s_cselect_b32 s57, s47, s23
	s_cselect_b32 s56, s46, s22
	s_cselect_b32 s55, s49, s20
	s_cselect_b32 s54, s48, s1
	s_add_i32 m0, s62, 0xc000
	ds_read_b128 v[76:79], v239
	ds_read_b128 v[80:83], v239 offset:1024
	ds_read_b128 v[84:87], v239 offset:2048
	ds_read_b128 v[88:91], v239 offset:3072
	ds_read_b128 v[92:95], v239 offset:4096
	ds_read_b128 v[96:99], v239 offset:5120
	ds_read_b128 v[100:103], v239 offset:6144
	global_load_lds_dwordx4 v206, s[52:53]
	s_add_i32 m0, s62, 0xe000
	ds_read_b128 v[104:107], v239 offset:7168
	global_load_lds_dwordx4 v208, s[52:53]
	s_waitcnt lgkmcnt(8)
	s_barrier
	s_waitcnt lgkmcnt(0)
	v_mfma_f32_16x16x32_bf16 v[160:163], v[52:55], v[92:95], v[160:163]
	v_mfma_f32_16x16x32_bf16 v[152:155], v[60:63], v[92:95], v[152:155]
	v_mfma_f32_16x16x32_bf16 v[144:147], v[52:55], v[100:103], v[144:147]
	v_mfma_f32_16x16x32_bf16 v[140:143], v[60:63], v[100:103], v[140:143]
	v_mfma_f32_16x16x32_bf16 v[116:119], v[52:55], v[76:79], v[192:195]
	v_mfma_f32_16x16x32_bf16 v[120:123], v[60:63], v[76:79], v[184:187]
	v_mfma_f32_16x16x32_bf16 v[124:127], v[52:55], v[84:87], v[176:179]
	v_mfma_f32_16x16x32_bf16 v[128:131], v[60:63], v[84:87], v[168:171]
	v_mfma_f32_16x16x32_bf16 v[160:163], v[56:59], v[96:99], v[160:163]
	v_mfma_f32_16x16x32_bf16 v[152:155], v[64:67], v[96:99], v[152:155]
	v_mfma_f32_16x16x32_bf16 v[144:147], v[56:59], v[104:107], v[144:147]
	v_mfma_f32_16x16x32_bf16 v[140:143], v[64:67], v[104:107], v[140:143]
	v_mfma_f32_16x16x32_bf16 v[116:119], v[56:59], v[80:83], v[116:119]
	v_mfma_f32_16x16x32_bf16 v[120:123], v[64:67], v[80:83], v[120:123]
	v_mfma_f32_16x16x32_bf16 v[124:127], v[56:59], v[88:91], v[124:127]
	v_mfma_f32_16x16x32_bf16 v[128:131], v[64:67], v[88:91], v[128:131]
	s_barrier
	s_add_i32 m0, s60, 0x10000
	ds_read_b128 v[168:171], v198 offset:16384
	ds_read_b128 v[176:179], v198 offset:17408
	ds_read_b128 v[184:187], v198 offset:18432
	global_load_lds_dwordx4 v2, s[54:55]
	s_add_i32 m0, s60, 0x12000
	ds_read_b128 v[192:195], v198 offset:19456
	global_load_lds_dwordx4 v0, s[54:55]
	s_barrier
	s_waitcnt lgkmcnt(0)
	v_mfma_f32_16x16x32_bf16 v[188:191], v[168:171], v[76:79], v[188:191]
	v_mfma_f32_16x16x32_bf16 v[76:79], v[184:187], v[76:79], v[180:183]
	v_mfma_f32_16x16x32_bf16 v[188:191], v[176:179], v[80:83], v[188:191]
	v_mfma_f32_16x16x32_bf16 v[76:79], v[192:195], v[80:83], v[76:79]
	v_mfma_f32_16x16x32_bf16 v[80:83], v[168:171], v[84:87], v[172:175]
	v_mfma_f32_16x16x32_bf16 v[84:87], v[184:187], v[84:87], v[164:167]
	v_mfma_f32_16x16x32_bf16 v[80:83], v[176:179], v[88:91], v[80:83]
	v_mfma_f32_16x16x32_bf16 v[84:87], v[192:195], v[88:91], v[84:87]
	v_mfma_f32_16x16x32_bf16 v[88:91], v[168:171], v[92:95], v[156:159]
	v_mfma_f32_16x16x32_bf16 v[92:95], v[184:187], v[92:95], v[148:151]
	v_mfma_f32_16x16x32_bf16 v[88:91], v[176:179], v[96:99], v[88:91]
	v_mfma_f32_16x16x32_bf16 v[92:95], v[192:195], v[96:99], v[92:95]
	v_mfma_f32_16x16x32_bf16 v[96:99], v[168:171], v[100:103], v[136:139]
	v_mfma_f32_16x16x32_bf16 v[100:103], v[184:187], v[100:103], v[132:135]
	v_mfma_f32_16x16x32_bf16 v[96:99], v[176:179], v[104:107], v[96:99]
	v_mfma_f32_16x16x32_bf16 v[100:103], v[192:195], v[104:107], v[100:103]
	s_mov_b32 m0, s62
	s_barrier
	ds_read_b128 v[104:107], v239 offset:16384
	ds_read_b128 v[132:135], v239 offset:17408
	ds_read_b128 v[136:139], v239 offset:18432
	ds_read_b128 v[148:151], v239 offset:19456
	ds_read_b128 v[156:159], v239 offset:20480
	ds_read_b128 v[164:167], v239 offset:21504
	ds_read_b128 v[172:175], v239 offset:22528
	global_load_lds_dwordx4 v204, s[56:57]
	s_mov_b32 m0, s63
	ds_read_b128 v[180:183], v239 offset:23552
	global_load_lds_dwordx4 v202, s[56:57]
	s_barrier
	s_waitcnt lgkmcnt(0)
	v_mfma_f32_16x16x32_bf16 v[112:115], v[52:55], v[104:107], v[112:115]
	v_mfma_f32_16x16x32_bf16 v[72:75], v[60:63], v[104:107], v[72:75]
	v_mfma_f32_16x16x32_bf16 v[48:51], v[52:55], v[136:139], v[48:51]
	v_mfma_f32_16x16x32_bf16 v[40:43], v[60:63], v[136:139], v[40:43]
	v_mfma_f32_16x16x32_bf16 v[32:35], v[52:55], v[156:159], v[32:35]
	v_mfma_f32_16x16x32_bf16 v[24:27], v[60:63], v[156:159], v[24:27]
	v_mfma_f32_16x16x32_bf16 v[16:19], v[52:55], v[172:175], v[16:19]
	v_mfma_f32_16x16x32_bf16 v[12:15], v[60:63], v[172:175], v[12:15]
	v_mfma_f32_16x16x32_bf16 v[112:115], v[56:59], v[132:135], v[112:115]
	v_mfma_f32_16x16x32_bf16 v[72:75], v[64:67], v[132:135], v[72:75]
	v_mfma_f32_16x16x32_bf16 v[48:51], v[56:59], v[148:151], v[48:51]
	v_mfma_f32_16x16x32_bf16 v[40:43], v[64:67], v[148:151], v[40:43]
	v_mfma_f32_16x16x32_bf16 v[32:35], v[56:59], v[164:167], v[32:35]
	v_mfma_f32_16x16x32_bf16 v[24:27], v[64:67], v[164:167], v[24:27]
	v_mfma_f32_16x16x32_bf16 v[16:19], v[56:59], v[180:183], v[16:19]
	v_mfma_f32_16x16x32_bf16 v[12:15], v[64:67], v[180:183], v[12:15]
	s_barrier
	s_add_i32 m0, s60, 0x14000
	s_add_u32 s22, s54, 0x40000
	s_addc_u32 s23, s55, 0
	global_load_lds_dwordx4 v2, s[22:23]
	s_add_i32 m0, s60, 0x16000
	s_waitcnt vmcnt(5)
	global_load_lds_dwordx4 v0, s[22:23]
	s_barrier
	v_mfma_f32_16x16x32_bf16 v[44:47], v[168:171], v[136:139], v[44:47]
	v_mfma_f32_16x16x32_bf16 v[36:39], v[184:187], v[136:139], v[36:39]
	v_mfma_f32_16x16x32_bf16 v[28:31], v[168:171], v[156:159], v[28:31]
	v_mfma_f32_16x16x32_bf16 v[20:23], v[184:187], v[156:159], v[20:23]
	v_mfma_f32_16x16x32_bf16 v[8:11], v[168:171], v[172:175], v[8:11]
	v_mfma_f32_16x16x32_bf16 v[4:7], v[184:187], v[172:175], v[4:7]
	v_mfma_f32_16x16x32_bf16 v[52:55], v[168:171], v[104:107], v[108:111]
	v_mfma_f32_16x16x32_bf16 v[56:59], v[184:187], v[104:107], v[68:71]
	v_mfma_f32_16x16x32_bf16 v[44:47], v[176:179], v[148:151], v[44:47]
	v_mfma_f32_16x16x32_bf16 v[36:39], v[192:195], v[148:151], v[36:39]
	v_mfma_f32_16x16x32_bf16 v[28:31], v[176:179], v[164:167], v[28:31]
	v_mfma_f32_16x16x32_bf16 v[20:23], v[192:195], v[164:167], v[20:23]
	v_mfma_f32_16x16x32_bf16 v[8:11], v[176:179], v[180:183], v[8:11]
	v_mfma_f32_16x16x32_bf16 v[4:7], v[192:195], v[180:183], v[4:7]
	v_mfma_f32_16x16x32_bf16 v[52:55], v[176:179], v[132:135], v[52:55]
	v_mfma_f32_16x16x32_bf16 v[56:59], v[192:195], v[132:135], v[56:59]
	s_barrier
	ds_read_b128 v[60:63], v198 offset:32768
	ds_read_b128 v[64:67], v198 offset:33792
	ds_read_b128 v[68:71], v198 offset:34816
	ds_read_b128 v[104:107], v198 offset:35840
	s_add_u32 s22, s56, 0x40000
	s_addc_u32 s23, s57, 0
	s_mov_b32 m0, s64
	ds_read_b128 v[108:111], v239 offset:32768
	ds_read_b128 v[132:135], v239 offset:33792
	ds_read_b128 v[136:139], v239 offset:34816
	ds_read_b128 v[148:151], v239 offset:35840
	ds_read_b128 v[210:213], v239 offset:36864
	ds_read_b128 v[214:217], v239 offset:37888
	ds_read_b128 v[240:243], v239 offset:38912
	global_load_lds_dwordx4 v204, s[22:23]
	s_mov_b32 m0, s65
	ds_read_b128 v[244:247], v239 offset:39936
	global_load_lds_dwordx4 v202, s[22:23]
	s_waitcnt lgkmcnt(8)
	s_barrier
	s_waitcnt lgkmcnt(0)
	v_mfma_f32_16x16x32_bf16 v[116:119], v[60:63], v[108:111], v[116:119]
	v_mfma_f32_16x16x32_bf16 v[192:195], v[64:67], v[132:135], v[116:119]
	v_mfma_f32_16x16x32_bf16 v[116:119], v[68:71], v[108:111], v[120:123]
	v_mfma_f32_16x16x32_bf16 v[184:187], v[104:107], v[132:135], v[116:119]
	v_mfma_f32_16x16x32_bf16 v[116:119], v[60:63], v[136:139], v[124:127]
	v_mfma_f32_16x16x32_bf16 v[176:179], v[64:67], v[148:151], v[116:119]
	v_mfma_f32_16x16x32_bf16 v[116:119], v[68:71], v[136:139], v[128:131]
	v_mfma_f32_16x16x32_bf16 v[168:171], v[104:107], v[148:151], v[116:119]
	v_mfma_f32_16x16x32_bf16 v[116:119], v[60:63], v[210:213], v[160:163]
	v_mfma_f32_16x16x32_bf16 v[160:163], v[64:67], v[214:217], v[116:119]
	v_mfma_f32_16x16x32_bf16 v[116:119], v[68:71], v[210:213], v[152:155]
	v_mfma_f32_16x16x32_bf16 v[152:155], v[104:107], v[214:217], v[116:119]
	v_mfma_f32_16x16x32_bf16 v[116:119], v[60:63], v[240:243], v[144:147]
	v_mfma_f32_16x16x32_bf16 v[144:147], v[64:67], v[244:247], v[116:119]
	v_mfma_f32_16x16x32_bf16 v[116:119], v[68:71], v[240:243], v[140:143]
	v_mfma_f32_16x16x32_bf16 v[140:143], v[104:107], v[244:247], v[116:119]
	s_barrier
	s_add_i32 m0, s60, 0x18000
	ds_read_b128 v[116:119], v198 offset:49152
	ds_read_b128 v[120:123], v198 offset:50176
	ds_read_b128 v[124:127], v198 offset:51200
	s_add_u32 s98, s54, 0x80
	s_addc_u32 s99, s55, 0
	global_load_lds_dwordx4 v2, s[98:99]
	s_add_i32 m0, s60, 0x1a000
	ds_read_b128 v[128:131], v198 offset:52224
	global_load_lds_dwordx4 v0, s[98:99]
	s_barrier
	s_waitcnt lgkmcnt(0)
	v_mfma_f32_16x16x32_bf16 v[76:79], v[124:127], v[108:111], v[76:79]
	v_mfma_f32_16x16x32_bf16 v[180:183], v[128:131], v[132:135], v[76:79]
	v_mfma_f32_16x16x32_bf16 v[76:79], v[116:119], v[136:139], v[80:83]
	v_mfma_f32_16x16x32_bf16 v[172:175], v[120:123], v[148:151], v[76:79]
	v_mfma_f32_16x16x32_bf16 v[76:79], v[124:127], v[136:139], v[84:87]
	v_mfma_f32_16x16x32_bf16 v[156:159], v[116:119], v[108:111], v[188:191]
	v_mfma_f32_16x16x32_bf16 v[164:167], v[128:131], v[148:151], v[76:79]
	v_mfma_f32_16x16x32_bf16 v[76:79], v[116:119], v[210:213], v[88:91]
	v_mfma_f32_16x16x32_bf16 v[188:191], v[120:123], v[132:135], v[156:159]
	v_mfma_f32_16x16x32_bf16 v[156:159], v[120:123], v[214:217], v[76:79]
	v_mfma_f32_16x16x32_bf16 v[76:79], v[124:127], v[210:213], v[92:95]
	v_mfma_f32_16x16x32_bf16 v[148:151], v[128:131], v[214:217], v[76:79]
	v_mfma_f32_16x16x32_bf16 v[76:79], v[116:119], v[240:243], v[96:99]
	v_mfma_f32_16x16x32_bf16 v[136:139], v[120:123], v[244:247], v[76:79]
	v_mfma_f32_16x16x32_bf16 v[76:79], v[124:127], v[240:243], v[100:103]
	v_mfma_f32_16x16x32_bf16 v[132:135], v[128:131], v[244:247], v[76:79]
	s_mov_b32 m0, s72
	s_barrier
	s_nop 2
	ds_read_b128 v[76:79], v239 offset:49152
	ds_read_b128 v[80:83], v239 offset:50176
	ds_read_b128 v[84:87], v239 offset:51200
	ds_read_b128 v[88:91], v239 offset:52224
	ds_read_b128 v[92:95], v239 offset:53248
	ds_read_b128 v[96:99], v239 offset:54272
	ds_read_b128 v[100:103], v239 offset:55296
	s_add_u32 s98, s56, 0x80
	s_addc_u32 s99, s57, 0
	global_load_lds_dwordx4 v204, s[98:99]
	s_mov_b32 m0, s74
	ds_read_b128 v[210:213], v239 offset:56320
	global_load_lds_dwordx4 v202, s[98:99]
	s_barrier
	s_waitcnt lgkmcnt(0)
	v_mfma_f32_16x16x32_bf16 v[108:111], v[60:63], v[76:79], v[112:115]
	v_mfma_f32_16x16x32_bf16 v[72:75], v[68:71], v[76:79], v[72:75]
	v_mfma_f32_16x16x32_bf16 v[48:51], v[60:63], v[84:87], v[48:51]
	v_mfma_f32_16x16x32_bf16 v[40:43], v[68:71], v[84:87], v[40:43]
	v_mfma_f32_16x16x32_bf16 v[32:35], v[60:63], v[92:95], v[32:35]
	v_mfma_f32_16x16x32_bf16 v[24:27], v[68:71], v[92:95], v[24:27]
	v_mfma_f32_16x16x32_bf16 v[16:19], v[60:63], v[100:103], v[16:19]
	v_mfma_f32_16x16x32_bf16 v[12:15], v[68:71], v[100:103], v[12:15]
	v_mfma_f32_16x16x32_bf16 v[112:115], v[64:67], v[80:83], v[108:111]
	v_mfma_f32_16x16x32_bf16 v[72:75], v[104:107], v[80:83], v[72:75]
	v_mfma_f32_16x16x32_bf16 v[48:51], v[64:67], v[88:91], v[48:51]
	v_mfma_f32_16x16x32_bf16 v[40:43], v[104:107], v[88:91], v[40:43]
	v_mfma_f32_16x16x32_bf16 v[32:35], v[64:67], v[96:99], v[32:35]
	v_mfma_f32_16x16x32_bf16 v[24:27], v[104:107], v[96:99], v[24:27]
	v_mfma_f32_16x16x32_bf16 v[16:19], v[64:67], v[210:213], v[16:19]
	v_mfma_f32_16x16x32_bf16 v[12:15], v[104:107], v[210:213], v[12:15]
	s_barrier
	s_add_i32 m0, s60, 0x1c000
	s_add_u32 s22, s54, 0x40080
	s_addc_u32 s23, s55, 0
	global_load_lds_dwordx4 v2, s[22:23]
	s_add_i32 m0, s60, 0x1e000
	s_waitcnt vmcnt(5)
	global_load_lds_dwordx4 v0, s[22:23]
	s_barrier
	v_mfma_f32_16x16x32_bf16 v[52:55], v[116:119], v[76:79], v[52:55]
	v_mfma_f32_16x16x32_bf16 v[108:111], v[120:123], v[80:83], v[52:55]
	v_mfma_f32_16x16x32_bf16 v[52:55], v[124:127], v[76:79], v[56:59]
	v_mfma_f32_16x16x32_bf16 v[44:47], v[116:119], v[84:87], v[44:47]
	v_mfma_f32_16x16x32_bf16 v[36:39], v[124:127], v[84:87], v[36:39]
	v_mfma_f32_16x16x32_bf16 v[28:31], v[116:119], v[92:95], v[28:31]
	v_mfma_f32_16x16x32_bf16 v[20:23], v[124:127], v[92:95], v[20:23]
	v_mfma_f32_16x16x32_bf16 v[8:11], v[116:119], v[100:103], v[8:11]
	v_mfma_f32_16x16x32_bf16 v[4:7], v[124:127], v[100:103], v[4:7]
	v_mfma_f32_16x16x32_bf16 v[68:71], v[128:131], v[80:83], v[52:55]
	v_mfma_f32_16x16x32_bf16 v[44:47], v[120:123], v[88:91], v[44:47]
	v_mfma_f32_16x16x32_bf16 v[36:39], v[128:131], v[88:91], v[36:39]
	v_mfma_f32_16x16x32_bf16 v[28:31], v[120:123], v[96:99], v[28:31]
	v_mfma_f32_16x16x32_bf16 v[20:23], v[128:131], v[96:99], v[20:23]
	v_mfma_f32_16x16x32_bf16 v[8:11], v[120:123], v[210:213], v[8:11]
	v_mfma_f32_16x16x32_bf16 v[4:7], v[128:131], v[210:213], v[4:7]
	s_add_i32 s21, s21, 2
	s_add_u32 s52, s52, 0x100
	s_addc_u32 s53, s53, 0
	s_add_u32 s1, s1, 0x100
	s_addc_u32 s20, s20, 0
	s_cmp_gt_u32 s21, 13
	s_barrier
	s_cbranch_scc0 .LBB0_80
	v_lshl_or_b32 v210, s30, 7, v238
	s_lshl_b32 s1, s50, 8
	s_add_i32 s1, s1, s67
	v_lshlrev_b32_e32 v211, 2, v210
	v_lshlrev_b32_e32 v219, 1, v210
	v_readlane_b32 s2, v252, 4
	v_readlane_b32 s3, v252, 5
	v_readlane_b32 s20, v252, 20
	v_readlane_b32 s21, v252, 21
	v_readlane_b32 s22, v252, 2
	v_readlane_b32 s23, v252, 3
	v_readlane_b32 s24, v252, 22
	v_readlane_b32 s25, v252, 23
	v_readlane_b32 s26, v252, 24
	v_readlane_b32 s27, v252, 25
	v_readlane_b32 s50, v252, 26
	v_readlane_b32 s51, v252, 27
	v_readlane_b32 s56, v252, 28
	v_readlane_b32 s57, v252, 29
	v_readlane_b32 s98, v252, 30
	v_readlane_b32 s99, v252, 31
	v_lshl_add_u32 v240, v201, 2, s1
	v_mul_u32_u24_e32 v240, 0x1600, v240
	v_add_u32_e32 v240, v240, v219
	global_load_dwordx4 v[120:123], v211, s[2:3]
	global_load_dwordx4 v[80:83], v211, s[2:3] offset:16
	global_load_dwordx4 v[116:119], v211, s[20:21]
	global_load_dwordx4 v[76:79], v211, s[20:21] offset:16
	global_load_dwordx4 v[96:99], v211, s[22:23]
	global_load_dwordx4 v[56:59], v211, s[22:23] offset:16
	global_load_dwordx4 v[92:95], v211, s[24:25]
	global_load_dwordx4 v[52:55], v211, s[24:25] offset:16
	global_load_dwordx4 v[104:107], v211, s[26:27]
	global_load_dwordx4 v[64:67], v211, s[26:27] offset:16
	global_load_dwordx4 v[100:103], v211, s[50:51]
	global_load_dwordx4 v[60:63], v211, s[50:51] offset:16
	global_load_dwordx4 v[124:127], v211, s[56:57]
	global_load_dwordx4 v[84:87], v211, s[56:57] offset:16
	global_load_dwordx4 v[128:131], v211, s[98:99]
	global_load_dwordx4 v[88:91], v211, s[98:99] offset:16
	v_readlane_b32 s56, v254, 63
	v_readlane_b32 s57, v255, 0
	v_cmp_eq_u32_e64 s[2:3], 0, v201
	v_cmp_eq_u32_e64 s[26:27], 15, v201
	s_lshr_b32 s24, s1, 4
	s_mov_b64 exec, s[2:3]
	v_cvt_pk_bf16_f32 v212, v192, v193
	v_cvt_pk_bf16_f32 v213, v194, v195
	v_cvt_pk_bf16_f32 v214, v184, v185
	v_cvt_pk_bf16_f32 v215, v186, v187
	s_add_i32 s20, s24, 2
	s_mulk_i32 s20, 0x2c00
	s_add_u32 s22, s56, s20
	s_addc_u32 s23, s57, 0
	global_store_dwordx4 v219, v[212:215], s[22:23]
	v_cvt_pk_bf16_f32 v242, v188, v189
	v_cvt_pk_bf16_f32 v243, v190, v191
	v_cvt_pk_bf16_f32 v244, v180, v181
	v_cvt_pk_bf16_f32 v245, v182, v183
	s_add_u32 s22, s22, 0x1600
	s_addc_u32 s23, s23, 0
	global_store_dwordx4 v219, v[242:245], s[22:23]
	v_cvt_pk_bf16_f32 v246, v176, v177
	v_cvt_pk_bf16_f32 v247, v178, v179
	v_cvt_pk_bf16_f32 v248, v168, v169
	v_cvt_pk_bf16_f32 v249, v170, v171
	s_add_i32 s20, s24, 3
	s_mulk_i32 s20, 0x2c00
	s_add_u32 s22, s56, s20
	s_addc_u32 s23, s57, 0
	global_store_dwordx4 v219, v[246:249], s[22:23]
	v_cvt_pk_bf16_f32 v212, v172, v173
	v_cvt_pk_bf16_f32 v213, v174, v175
	v_cvt_pk_bf16_f32 v214, v164, v165
	v_cvt_pk_bf16_f32 v215, v166, v167
	s_add_u32 s22, s22, 0x1600
	s_addc_u32 s23, s23, 0
	global_store_dwordx4 v219, v[212:215], s[22:23]
	s_mov_b64 exec, s[26:27]
	v_cvt_pk_bf16_f32 v242, v160, v161
	v_cvt_pk_bf16_f32 v243, v162, v163
	v_cvt_pk_bf16_f32 v244, v152, v153
	v_cvt_pk_bf16_f32 v245, v154, v155
	s_add_i32 s20, s24, 0
	s_mulk_i32 s20, 0x2c00
	s_add_u32 s22, s56, s20
	s_addc_u32 s23, s57, 0
	global_store_dwordx4 v219, v[242:245], s[22:23]
	v_cvt_pk_bf16_f32 v246, v156, v157
	v_cvt_pk_bf16_f32 v247, v158, v159
	v_cvt_pk_bf16_f32 v248, v148, v149
	v_cvt_pk_bf16_f32 v249, v150, v151
	s_add_u32 s22, s22, 0x1600
	s_addc_u32 s23, s23, 0
	global_store_dwordx4 v219, v[246:249], s[22:23]
	v_cvt_pk_bf16_f32 v212, v144, v145
	v_cvt_pk_bf16_f32 v213, v146, v147
	v_cvt_pk_bf16_f32 v214, v140, v141
	v_cvt_pk_bf16_f32 v215, v142, v143
	s_add_i32 s20, s24, 1
	s_mulk_i32 s20, 0x2c00
	s_add_u32 s22, s56, s20
	s_addc_u32 s23, s57, 0
	global_store_dwordx4 v219, v[212:215], s[22:23]
	v_cvt_pk_bf16_f32 v242, v136, v137
	v_cvt_pk_bf16_f32 v243, v138, v139
	v_cvt_pk_bf16_f32 v244, v132, v133
	v_cvt_pk_bf16_f32 v245, v134, v135
	s_add_u32 s22, s22, 0x1600
	s_addc_u32 s23, s23, 0
	global_store_dwordx4 v219, v[242:245], s[22:23]
	s_mov_b64 exec, s[2:3]
	v_cvt_pk_bf16_f32 v246, v112, v113
	v_cvt_pk_bf16_f32 v247, v114, v115
	v_cvt_pk_bf16_f32 v248, v72, v73
	v_cvt_pk_bf16_f32 v249, v74, v75
	s_add_i32 s20, s24, 10
	s_mulk_i32 s20, 0x2c00
	s_add_u32 s22, s56, s20
	s_addc_u32 s23, s57, 0
	global_store_dwordx4 v219, v[246:249], s[22:23]
	v_cvt_pk_bf16_f32 v212, v108, v109
	v_cvt_pk_bf16_f32 v213, v110, v111
	v_cvt_pk_bf16_f32 v214, v68, v69
	v_cvt_pk_bf16_f32 v215, v70, v71
	s_add_u32 s22, s22, 0x1600
	s_addc_u32 s23, s23, 0
	global_store_dwordx4 v219, v[212:215], s[22:23]
	v_cvt_pk_bf16_f32 v242, v48, v49
	v_cvt_pk_bf16_f32 v243, v50, v51
	v_cvt_pk_bf16_f32 v244, v40, v41
	v_cvt_pk_bf16_f32 v245, v42, v43
	s_add_i32 s20, s24, 11
	s_mulk_i32 s20, 0x2c00
	s_add_u32 s22, s56, s20
	s_addc_u32 s23, s57, 0
	global_store_dwordx4 v219, v[242:245], s[22:23]
	v_cvt_pk_bf16_f32 v246, v44, v45
	v_cvt_pk_bf16_f32 v247, v46, v47
	v_cvt_pk_bf16_f32 v248, v36, v37
	v_cvt_pk_bf16_f32 v249, v38, v39
	s_add_u32 s22, s22, 0x1600
	s_addc_u32 s23, s23, 0
	global_store_dwordx4 v219, v[246:249], s[22:23]
	s_mov_b64 exec, s[26:27]
	v_cvt_pk_bf16_f32 v212, v32, v33
	v_cvt_pk_bf16_f32 v213, v34, v35
	v_cvt_pk_bf16_f32 v214, v24, v25
	v_cvt_pk_bf16_f32 v215, v26, v27
	s_add_i32 s20, s24, 8
	s_mulk_i32 s20, 0x2c00
	s_add_u32 s22, s56, s20
	s_addc_u32 s23, s57, 0
	global_store_dwordx4 v219, v[212:215], s[22:23]
	v_cvt_pk_bf16_f32 v242, v28, v29
	v_cvt_pk_bf16_f32 v243, v30, v31
	v_cvt_pk_bf16_f32 v244, v20, v21
	v_cvt_pk_bf16_f32 v245, v22, v23
	s_add_u32 s22, s22, 0x1600
	s_addc_u32 s23, s23, 0
	global_store_dwordx4 v219, v[242:245], s[22:23]
	v_cvt_pk_bf16_f32 v246, v16, v17
	v_cvt_pk_bf16_f32 v247, v18, v19
	v_cvt_pk_bf16_f32 v248, v12, v13
	v_cvt_pk_bf16_f32 v249, v14, v15
	s_add_i32 s20, s24, 9
	s_mulk_i32 s20, 0x2c00
	s_add_u32 s22, s56, s20
	s_addc_u32 s23, s57, 0
	global_store_dwordx4 v219, v[246:249], s[22:23]
	v_cvt_pk_bf16_f32 v212, v8, v9
	v_cvt_pk_bf16_f32 v213, v10, v11
	v_cvt_pk_bf16_f32 v214, v4, v5
	v_cvt_pk_bf16_f32 v215, v6, v7
	s_add_u32 s22, s22, 0x1600
	s_addc_u32 s23, s23, 0
	global_store_dwordx4 v219, v[212:215], s[22:23]
	s_mov_b64 exec, -1
	s_mov_b32 s50, 0xbfb8aa3b
	s_mov_b32 s51, 0xbfb8aa3b
	s_waitcnt vmcnt(16)
	v_mov_b32_dpp v198, v144 row_shr:1 row_mask:0xf bank_mask:0xf bound_ctrl:1
	v_mov_b32_dpp v199, v145 row_shr:1 row_mask:0xf bank_mask:0xf bound_ctrl:1
	v_mov_b32_dpp v214, v136 row_shr:1 row_mask:0xf bank_mask:0xf bound_ctrl:1
	v_mov_b32_dpp v215, v137 row_shr:1 row_mask:0xf bank_mask:0xf bound_ctrl:1
	v_mov_b32_dpp v212, v160 row_shr:1 row_mask:0xf bank_mask:0xf bound_ctrl:1
	v_mov_b32_dpp v213, v161 row_shr:1 row_mask:0xf bank_mask:0xf bound_ctrl:1
	v_mov_b32_dpp v216, v156 row_shr:1 row_mask:0xf bank_mask:0xf bound_ctrl:1
	v_mov_b32_dpp v217, v157 row_shr:1 row_mask:0xf bank_mask:0xf bound_ctrl:1
	v_pk_fma_f32 v[144:145], v[144:145], v[124:125], v[120:121]
	v_pk_fma_f32 v[136:137], v[136:137], v[128:129], v[116:117]
	v_pk_fma_f32 v[144:145], v[160:161], v[104:105], v[144:145]
	v_pk_fma_f32 v[136:137], v[156:157], v[100:101], v[136:137]
	v_pk_fma_f32 v[144:145], v[176:177], v[96:97], v[144:145]
	v_pk_fma_f32 v[136:137], v[172:173], v[92:93], v[136:137]
	v_pk_fma_f32 v[160:161], v[160:161], v[124:125], v[120:121]
	v_pk_fma_f32 v[156:157], v[156:157], v[128:129], v[116:117]
	v_pk_fma_f32 v[160:161], v[176:177], v[104:105], v[160:161]
	v_pk_fma_f32 v[156:157], v[172:173], v[100:101], v[156:157]
	v_pk_fma_f32 v[160:161], v[192:193], v[96:97], v[160:161]
	v_pk_fma_f32 v[156:157], v[188:189], v[92:93], v[156:157]
	v_pk_fma_f32 v[176:177], v[176:177], v[124:125], v[120:121]
	v_pk_fma_f32 v[172:173], v[172:173], v[128:129], v[116:117]
	v_pk_fma_f32 v[176:177], v[192:193], v[104:105], v[176:177]
	v_pk_fma_f32 v[172:173], v[188:189], v[100:101], v[172:173]
	v_pk_fma_f32 v[176:177], v[198:199], v[96:97], v[176:177]
	v_pk_fma_f32 v[172:173], v[214:215], v[92:93], v[172:173]
	v_pk_fma_f32 v[192:193], v[192:193], v[124:125], v[120:121]
	v_pk_fma_f32 v[188:189], v[188:189], v[128:129], v[116:117]
	v_pk_fma_f32 v[192:193], v[198:199], v[104:105], v[192:193]
	v_pk_fma_f32 v[188:189], v[214:215], v[100:101], v[188:189]
	v_pk_fma_f32 v[192:193], v[212:213], v[96:97], v[192:193]
	v_pk_fma_f32 v[188:189], v[216:217], v[92:93], v[188:189]
	v_pk_mul_f32 v[222:223], v[192:193], s[50:51]
	v_pk_mul_f32 v[242:243], v[176:177], s[50:51]
	v_pk_mul_f32 v[244:245], v[160:161], s[50:51]
	v_pk_mul_f32 v[246:247], v[144:145], s[50:51]
	v_exp_f32_e32 v222, v222
	v_exp_f32_e32 v223, v223
	v_exp_f32_e32 v242, v242
	v_exp_f32_e32 v243, v243
	v_exp_f32_e32 v244, v244
	v_exp_f32_e32 v245, v245
	v_exp_f32_e32 v246, v246
	v_exp_f32_e32 v247, v247
	v_pk_add_f32 v[222:223], v[222:223], 1.0 op_sel_hi:[1,0]
	v_pk_add_f32 v[242:243], v[242:243], 1.0 op_sel_hi:[1,0]
	v_pk_add_f32 v[244:245], v[244:245], 1.0 op_sel_hi:[1,0]
	v_pk_add_f32 v[246:247], v[246:247], 1.0 op_sel_hi:[1,0]
	v_rcp_f32_e32 v222, v222
	v_rcp_f32_e32 v223, v223
	v_rcp_f32_e32 v242, v242
	v_rcp_f32_e32 v243, v243
	v_rcp_f32_e32 v244, v244
	v_rcp_f32_e32 v245, v245
	v_rcp_f32_e32 v246, v246
	v_rcp_f32_e32 v247, v247
	v_pk_mul_f32 v[192:193], v[192:193], v[222:223]
	v_pk_mul_f32 v[176:177], v[176:177], v[242:243]
	v_pk_mul_f32 v[160:161], v[160:161], v[244:245]
	v_pk_mul_f32 v[144:145], v[144:145], v[246:247]
	v_pk_mul_f32 v[192:193], v[192:193], v[188:189]
	v_pk_mul_f32 v[176:177], v[176:177], v[172:173]
	v_pk_mul_f32 v[160:161], v[160:161], v[156:157]
	v_pk_mul_f32 v[144:145], v[144:145], v[136:137]
	v_cvt_pk_bf16_f32 v192, v192, v193
	v_cvt_pk_bf16_f32 v176, v176, v177
	v_cvt_pk_bf16_f32 v160, v160, v161
	v_cvt_pk_bf16_f32 v144, v144, v145
	v_mov_b32_dpp v198, v146 row_shr:1 row_mask:0xf bank_mask:0xf bound_ctrl:1
	v_mov_b32_dpp v199, v147 row_shr:1 row_mask:0xf bank_mask:0xf bound_ctrl:1
	v_mov_b32_dpp v214, v138 row_shr:1 row_mask:0xf bank_mask:0xf bound_ctrl:1
	v_mov_b32_dpp v215, v139 row_shr:1 row_mask:0xf bank_mask:0xf bound_ctrl:1
	v_mov_b32_dpp v212, v162 row_shr:1 row_mask:0xf bank_mask:0xf bound_ctrl:1
	v_mov_b32_dpp v213, v163 row_shr:1 row_mask:0xf bank_mask:0xf bound_ctrl:1
	v_mov_b32_dpp v216, v158 row_shr:1 row_mask:0xf bank_mask:0xf bound_ctrl:1
	v_mov_b32_dpp v217, v159 row_shr:1 row_mask:0xf bank_mask:0xf bound_ctrl:1
	v_pk_fma_f32 v[146:147], v[146:147], v[126:127], v[122:123]
	v_pk_fma_f32 v[138:139], v[138:139], v[130:131], v[118:119]
	v_pk_fma_f32 v[146:147], v[162:163], v[106:107], v[146:147]
	v_pk_fma_f32 v[138:139], v[158:159], v[102:103], v[138:139]
	v_pk_fma_f32 v[146:147], v[178:179], v[98:99], v[146:147]
	v_pk_fma_f32 v[138:139], v[174:175], v[94:95], v[138:139]
	v_pk_fma_f32 v[162:163], v[162:163], v[126:127], v[122:123]
	v_pk_fma_f32 v[158:159], v[158:159], v[130:131], v[118:119]
	v_pk_fma_f32 v[162:163], v[178:179], v[106:107], v[162:163]
	v_pk_fma_f32 v[158:159], v[174:175], v[102:103], v[158:159]
	v_pk_fma_f32 v[162:163], v[194:195], v[98:99], v[162:163]
	v_pk_fma_f32 v[158:159], v[190:191], v[94:95], v[158:159]
	v_pk_fma_f32 v[178:179], v[178:179], v[126:127], v[122:123]
	v_pk_fma_f32 v[174:175], v[174:175], v[130:131], v[118:119]
	v_pk_fma_f32 v[178:179], v[194:195], v[106:107], v[178:179]
	v_pk_fma_f32 v[174:175], v[190:191], v[102:103], v[174:175]
	v_pk_fma_f32 v[178:179], v[198:199], v[98:99], v[178:179]
	v_pk_fma_f32 v[174:175], v[214:215], v[94:95], v[174:175]
	v_pk_fma_f32 v[194:195], v[194:195], v[126:127], v[122:123]
	v_pk_fma_f32 v[190:191], v[190:191], v[130:131], v[118:119]
	v_pk_fma_f32 v[194:195], v[198:199], v[106:107], v[194:195]
	v_pk_fma_f32 v[190:191], v[214:215], v[102:103], v[190:191]
	v_pk_fma_f32 v[194:195], v[212:213], v[98:99], v[194:195]
	v_pk_fma_f32 v[190:191], v[216:217], v[94:95], v[190:191]
	v_pk_mul_f32 v[222:223], v[194:195], s[50:51]
	v_pk_mul_f32 v[242:243], v[178:179], s[50:51]
	v_pk_mul_f32 v[244:245], v[162:163], s[50:51]
	v_pk_mul_f32 v[246:247], v[146:147], s[50:51]
	v_exp_f32_e32 v222, v222
	v_exp_f32_e32 v223, v223
	v_exp_f32_e32 v242, v242
	v_exp_f32_e32 v243, v243
	v_exp_f32_e32 v244, v244
	v_exp_f32_e32 v245, v245
	v_exp_f32_e32 v246, v246
	v_exp_f32_e32 v247, v247
	v_pk_add_f32 v[222:223], v[222:223], 1.0 op_sel_hi:[1,0]
	v_pk_add_f32 v[242:243], v[242:243], 1.0 op_sel_hi:[1,0]
	v_pk_add_f32 v[244:245], v[244:245], 1.0 op_sel_hi:[1,0]
	v_pk_add_f32 v[246:247], v[246:247], 1.0 op_sel_hi:[1,0]
	v_rcp_f32_e32 v222, v222
	v_rcp_f32_e32 v223, v223
	v_rcp_f32_e32 v242, v242
	v_rcp_f32_e32 v243, v243
	v_rcp_f32_e32 v244, v244
	v_rcp_f32_e32 v245, v245
	v_rcp_f32_e32 v246, v246
	v_rcp_f32_e32 v247, v247
	v_pk_mul_f32 v[194:195], v[194:195], v[222:223]
	v_pk_mul_f32 v[178:179], v[178:179], v[242:243]
	v_pk_mul_f32 v[162:163], v[162:163], v[244:245]
	v_pk_mul_f32 v[146:147], v[146:147], v[246:247]
	v_pk_mul_f32 v[194:195], v[194:195], v[190:191]
	v_pk_mul_f32 v[178:179], v[178:179], v[174:175]
	v_pk_mul_f32 v[162:163], v[162:163], v[158:159]
	v_pk_mul_f32 v[146:147], v[146:147], v[138:139]
	v_cvt_pk_bf16_f32 v193, v194, v195
	v_cvt_pk_bf16_f32 v177, v178, v179
	v_cvt_pk_bf16_f32 v161, v162, v163
	v_cvt_pk_bf16_f32 v145, v146, v147
	v_mov_b32_dpp v198, v140 row_shr:1 row_mask:0xf bank_mask:0xf bound_ctrl:1
	v_mov_b32_dpp v199, v141 row_shr:1 row_mask:0xf bank_mask:0xf bound_ctrl:1
	v_mov_b32_dpp v214, v132 row_shr:1 row_mask:0xf bank_mask:0xf bound_ctrl:1
	v_mov_b32_dpp v215, v133 row_shr:1 row_mask:0xf bank_mask:0xf bound_ctrl:1
	v_mov_b32_dpp v212, v152 row_shr:1 row_mask:0xf bank_mask:0xf bound_ctrl:1
	v_mov_b32_dpp v213, v153 row_shr:1 row_mask:0xf bank_mask:0xf bound_ctrl:1
	v_mov_b32_dpp v216, v148 row_shr:1 row_mask:0xf bank_mask:0xf bound_ctrl:1
	v_mov_b32_dpp v217, v149 row_shr:1 row_mask:0xf bank_mask:0xf bound_ctrl:1
	v_pk_fma_f32 v[140:141], v[140:141], v[84:85], v[80:81]
	v_pk_fma_f32 v[132:133], v[132:133], v[88:89], v[76:77]
	v_pk_fma_f32 v[140:141], v[152:153], v[64:65], v[140:141]
	v_pk_fma_f32 v[132:133], v[148:149], v[60:61], v[132:133]
	v_pk_fma_f32 v[140:141], v[168:169], v[56:57], v[140:141]
	v_pk_fma_f32 v[132:133], v[164:165], v[52:53], v[132:133]
	v_pk_fma_f32 v[152:153], v[152:153], v[84:85], v[80:81]
	v_pk_fma_f32 v[148:149], v[148:149], v[88:89], v[76:77]
	v_pk_fma_f32 v[152:153], v[168:169], v[64:65], v[152:153]
	v_pk_fma_f32 v[148:149], v[164:165], v[60:61], v[148:149]
	v_pk_fma_f32 v[152:153], v[184:185], v[56:57], v[152:153]
	v_pk_fma_f32 v[148:149], v[180:181], v[52:53], v[148:149]
	v_pk_fma_f32 v[168:169], v[168:169], v[84:85], v[80:81]
	v_pk_fma_f32 v[164:165], v[164:165], v[88:89], v[76:77]
	v_pk_fma_f32 v[168:169], v[184:185], v[64:65], v[168:169]
	v_pk_fma_f32 v[164:165], v[180:181], v[60:61], v[164:165]
	v_pk_fma_f32 v[168:169], v[198:199], v[56:57], v[168:169]
	v_pk_fma_f32 v[164:165], v[214:215], v[52:53], v[164:165]
	v_pk_fma_f32 v[184:185], v[184:185], v[84:85], v[80:81]
	v_pk_fma_f32 v[180:181], v[180:181], v[88:89], v[76:77]
	v_pk_fma_f32 v[184:185], v[198:199], v[64:65], v[184:185]
	v_pk_fma_f32 v[180:181], v[214:215], v[60:61], v[180:181]
	v_pk_fma_f32 v[184:185], v[212:213], v[56:57], v[184:185]
	v_pk_fma_f32 v[180:181], v[216:217], v[52:53], v[180:181]
	v_pk_mul_f32 v[222:223], v[184:185], s[50:51]
	v_pk_mul_f32 v[242:243], v[168:169], s[50:51]
	v_pk_mul_f32 v[244:245], v[152:153], s[50:51]
	v_pk_mul_f32 v[246:247], v[140:141], s[50:51]
	v_exp_f32_e32 v222, v222
	v_exp_f32_e32 v223, v223
	v_exp_f32_e32 v242, v242
	v_exp_f32_e32 v243, v243
	v_exp_f32_e32 v244, v244
	v_exp_f32_e32 v245, v245
	v_exp_f32_e32 v246, v246
	v_exp_f32_e32 v247, v247
	v_pk_add_f32 v[222:223], v[222:223], 1.0 op_sel_hi:[1,0]
	v_pk_add_f32 v[242:243], v[242:243], 1.0 op_sel_hi:[1,0]
	v_pk_add_f32 v[244:245], v[244:245], 1.0 op_sel_hi:[1,0]
	v_pk_add_f32 v[246:247], v[246:247], 1.0 op_sel_hi:[1,0]
	v_rcp_f32_e32 v222, v222
	v_rcp_f32_e32 v223, v223
	v_rcp_f32_e32 v242, v242
	v_rcp_f32_e32 v243, v243
	v_rcp_f32_e32 v244, v244
	v_rcp_f32_e32 v245, v245
	v_rcp_f32_e32 v246, v246
	v_rcp_f32_e32 v247, v247
	v_pk_mul_f32 v[184:185], v[184:185], v[222:223]
	v_pk_mul_f32 v[168:169], v[168:169], v[242:243]
	v_pk_mul_f32 v[152:153], v[152:153], v[244:245]
	v_pk_mul_f32 v[140:141], v[140:141], v[246:247]
	v_pk_mul_f32 v[184:185], v[184:185], v[180:181]
	v_pk_mul_f32 v[168:169], v[168:169], v[164:165]
	v_pk_mul_f32 v[152:153], v[152:153], v[148:149]
	v_pk_mul_f32 v[140:141], v[140:141], v[132:133]
	v_cvt_pk_bf16_f32 v194, v184, v185
	v_cvt_pk_bf16_f32 v178, v168, v169
	v_cvt_pk_bf16_f32 v162, v152, v153
	v_cvt_pk_bf16_f32 v146, v140, v141
	v_mov_b32_dpp v198, v142 row_shr:1 row_mask:0xf bank_mask:0xf bound_ctrl:1
	v_mov_b32_dpp v199, v143 row_shr:1 row_mask:0xf bank_mask:0xf bound_ctrl:1
	v_mov_b32_dpp v214, v134 row_shr:1 row_mask:0xf bank_mask:0xf bound_ctrl:1
	v_mov_b32_dpp v215, v135 row_shr:1 row_mask:0xf bank_mask:0xf bound_ctrl:1
	v_mov_b32_dpp v212, v154 row_shr:1 row_mask:0xf bank_mask:0xf bound_ctrl:1
	v_mov_b32_dpp v213, v155 row_shr:1 row_mask:0xf bank_mask:0xf bound_ctrl:1
	v_mov_b32_dpp v216, v150 row_shr:1 row_mask:0xf bank_mask:0xf bound_ctrl:1
	v_mov_b32_dpp v217, v151 row_shr:1 row_mask:0xf bank_mask:0xf bound_ctrl:1
	v_pk_fma_f32 v[142:143], v[142:143], v[86:87], v[82:83]
	v_pk_fma_f32 v[134:135], v[134:135], v[90:91], v[78:79]
	v_pk_fma_f32 v[142:143], v[154:155], v[66:67], v[142:143]
	v_pk_fma_f32 v[134:135], v[150:151], v[62:63], v[134:135]
	v_pk_fma_f32 v[142:143], v[170:171], v[58:59], v[142:143]
	v_pk_fma_f32 v[134:135], v[166:167], v[54:55], v[134:135]
	v_pk_fma_f32 v[154:155], v[154:155], v[86:87], v[82:83]
	v_pk_fma_f32 v[150:151], v[150:151], v[90:91], v[78:79]
	v_pk_fma_f32 v[154:155], v[170:171], v[66:67], v[154:155]
	v_pk_fma_f32 v[150:151], v[166:167], v[62:63], v[150:151]
	v_pk_fma_f32 v[154:155], v[186:187], v[58:59], v[154:155]
	v_pk_fma_f32 v[150:151], v[182:183], v[54:55], v[150:151]
	v_pk_fma_f32 v[170:171], v[170:171], v[86:87], v[82:83]
	v_pk_fma_f32 v[166:167], v[166:167], v[90:91], v[78:79]
	v_pk_fma_f32 v[170:171], v[186:187], v[66:67], v[170:171]
	v_pk_fma_f32 v[166:167], v[182:183], v[62:63], v[166:167]
	v_pk_fma_f32 v[170:171], v[198:199], v[58:59], v[170:171]
	v_pk_fma_f32 v[166:167], v[214:215], v[54:55], v[166:167]
	v_pk_fma_f32 v[186:187], v[186:187], v[86:87], v[82:83]
	v_pk_fma_f32 v[182:183], v[182:183], v[90:91], v[78:79]
	v_pk_fma_f32 v[186:187], v[198:199], v[66:67], v[186:187]
	v_pk_fma_f32 v[182:183], v[214:215], v[62:63], v[182:183]
	v_pk_fma_f32 v[186:187], v[212:213], v[58:59], v[186:187]
	v_pk_fma_f32 v[182:183], v[216:217], v[54:55], v[182:183]
	v_pk_mul_f32 v[222:223], v[186:187], s[50:51]
	v_pk_mul_f32 v[242:243], v[170:171], s[50:51]
	v_pk_mul_f32 v[244:245], v[154:155], s[50:51]
	v_pk_mul_f32 v[246:247], v[142:143], s[50:51]
	v_exp_f32_e32 v222, v222
	v_exp_f32_e32 v223, v223
	v_exp_f32_e32 v242, v242
	v_exp_f32_e32 v243, v243
	v_exp_f32_e32 v244, v244
	v_exp_f32_e32 v245, v245
	v_exp_f32_e32 v246, v246
	v_exp_f32_e32 v247, v247
	v_pk_add_f32 v[222:223], v[222:223], 1.0 op_sel_hi:[1,0]
	v_pk_add_f32 v[242:243], v[242:243], 1.0 op_sel_hi:[1,0]
	v_pk_add_f32 v[244:245], v[244:245], 1.0 op_sel_hi:[1,0]
	v_pk_add_f32 v[246:247], v[246:247], 1.0 op_sel_hi:[1,0]
	v_rcp_f32_e32 v222, v222
	v_rcp_f32_e32 v223, v223
	v_rcp_f32_e32 v242, v242
	v_rcp_f32_e32 v243, v243
	v_rcp_f32_e32 v244, v244
	v_rcp_f32_e32 v245, v245
	v_rcp_f32_e32 v246, v246
	v_rcp_f32_e32 v247, v247
	v_pk_mul_f32 v[186:187], v[186:187], v[222:223]
	v_pk_mul_f32 v[170:171], v[170:171], v[242:243]
	v_pk_mul_f32 v[154:155], v[154:155], v[244:245]
	v_pk_mul_f32 v[142:143], v[142:143], v[246:247]
	v_pk_mul_f32 v[186:187], v[186:187], v[182:183]
	v_pk_mul_f32 v[170:171], v[170:171], v[166:167]
	v_pk_mul_f32 v[154:155], v[154:155], v[150:151]
	v_pk_mul_f32 v[142:143], v[142:143], v[134:135]
	v_cvt_pk_bf16_f32 v195, v186, v187
	v_cvt_pk_bf16_f32 v179, v170, v171
	v_cvt_pk_bf16_f32 v163, v154, v155
	v_cvt_pk_bf16_f32 v147, v142, v143
	s_mov_b64 s[20:21], s[82:83]
	global_store_dwordx4 v240, v[192:195], s[20:21]
	s_add_u32 s20, s82, 0x1600
	s_addc_u32 s21, s83, 0
	global_store_dwordx4 v240, v[176:179], s[20:21]
	s_add_u32 s20, s82, 0x2c00
	s_addc_u32 s21, s83, 0
	global_store_dwordx4 v240, v[160:163], s[20:21]
	s_add_u32 s20, s82, 0x4200
	s_addc_u32 s21, s83, 0
	global_store_dwordx4 v240, v[144:147], s[20:21]
	v_mov_b32_dpp v198, v16 row_shr:1 row_mask:0xf bank_mask:0xf bound_ctrl:1
	v_mov_b32_dpp v199, v17 row_shr:1 row_mask:0xf bank_mask:0xf bound_ctrl:1
	v_mov_b32_dpp v214, v8 row_shr:1 row_mask:0xf bank_mask:0xf bound_ctrl:1
	v_mov_b32_dpp v215, v9 row_shr:1 row_mask:0xf bank_mask:0xf bound_ctrl:1
	v_mov_b32_dpp v212, v32 row_shr:1 row_mask:0xf bank_mask:0xf bound_ctrl:1
	v_mov_b32_dpp v213, v33 row_shr:1 row_mask:0xf bank_mask:0xf bound_ctrl:1
	v_mov_b32_dpp v216, v28 row_shr:1 row_mask:0xf bank_mask:0xf bound_ctrl:1
	v_mov_b32_dpp v217, v29 row_shr:1 row_mask:0xf bank_mask:0xf bound_ctrl:1
	v_pk_fma_f32 v[16:17], v[16:17], v[124:125], v[120:121]
	v_pk_fma_f32 v[8:9], v[8:9], v[128:129], v[116:117]
	v_pk_fma_f32 v[16:17], v[32:33], v[104:105], v[16:17]
	v_pk_fma_f32 v[8:9], v[28:29], v[100:101], v[8:9]
	v_pk_fma_f32 v[16:17], v[48:49], v[96:97], v[16:17]
	v_pk_fma_f32 v[8:9], v[44:45], v[92:93], v[8:9]
	v_pk_fma_f32 v[32:33], v[32:33], v[124:125], v[120:121]
	v_pk_fma_f32 v[28:29], v[28:29], v[128:129], v[116:117]
	v_pk_fma_f32 v[32:33], v[48:49], v[104:105], v[32:33]
	v_pk_fma_f32 v[28:29], v[44:45], v[100:101], v[28:29]
	v_pk_fma_f32 v[32:33], v[112:113], v[96:97], v[32:33]
	v_pk_fma_f32 v[28:29], v[108:109], v[92:93], v[28:29]
	v_pk_fma_f32 v[48:49], v[48:49], v[124:125], v[120:121]
	v_pk_fma_f32 v[44:45], v[44:45], v[128:129], v[116:117]
	v_pk_fma_f32 v[48:49], v[112:113], v[104:105], v[48:49]
	v_pk_fma_f32 v[44:45], v[108:109], v[100:101], v[44:45]
	v_pk_fma_f32 v[48:49], v[198:199], v[96:97], v[48:49]
	v_pk_fma_f32 v[44:45], v[214:215], v[92:93], v[44:45]
	v_pk_fma_f32 v[112:113], v[112:113], v[124:125], v[120:121]
	v_pk_fma_f32 v[108:109], v[108:109], v[128:129], v[116:117]
	v_pk_fma_f32 v[112:113], v[198:199], v[104:105], v[112:113]
	v_pk_fma_f32 v[108:109], v[214:215], v[100:101], v[108:109]
	v_pk_fma_f32 v[112:113], v[212:213], v[96:97], v[112:113]
	v_pk_fma_f32 v[108:109], v[216:217], v[92:93], v[108:109]
	v_pk_mul_f32 v[222:223], v[112:113], s[50:51]
	v_pk_mul_f32 v[242:243], v[48:49], s[50:51]
	v_pk_mul_f32 v[244:245], v[32:33], s[50:51]
	v_pk_mul_f32 v[246:247], v[16:17], s[50:51]
	v_exp_f32_e32 v222, v222
	v_exp_f32_e32 v223, v223
	v_exp_f32_e32 v242, v242
	v_exp_f32_e32 v243, v243
	v_exp_f32_e32 v244, v244
	v_exp_f32_e32 v245, v245
	v_exp_f32_e32 v246, v246
	v_exp_f32_e32 v247, v247
	v_pk_add_f32 v[222:223], v[222:223], 1.0 op_sel_hi:[1,0]
	v_pk_add_f32 v[242:243], v[242:243], 1.0 op_sel_hi:[1,0]
	v_pk_add_f32 v[244:245], v[244:245], 1.0 op_sel_hi:[1,0]
	v_pk_add_f32 v[246:247], v[246:247], 1.0 op_sel_hi:[1,0]
	v_rcp_f32_e32 v222, v222
	v_rcp_f32_e32 v223, v223
	v_rcp_f32_e32 v242, v242
	v_rcp_f32_e32 v243, v243
	v_rcp_f32_e32 v244, v244
	v_rcp_f32_e32 v245, v245
	v_rcp_f32_e32 v246, v246
	v_rcp_f32_e32 v247, v247
	v_pk_mul_f32 v[112:113], v[112:113], v[222:223]
	v_pk_mul_f32 v[48:49], v[48:49], v[242:243]
	v_pk_mul_f32 v[32:33], v[32:33], v[244:245]
	v_pk_mul_f32 v[16:17], v[16:17], v[246:247]
	v_pk_mul_f32 v[112:113], v[112:113], v[108:109]
	v_pk_mul_f32 v[48:49], v[48:49], v[44:45]
	v_pk_mul_f32 v[32:33], v[32:33], v[28:29]
	v_pk_mul_f32 v[16:17], v[16:17], v[8:9]
	v_cvt_pk_bf16_f32 v112, v112, v113
	v_cvt_pk_bf16_f32 v48, v48, v49
	v_cvt_pk_bf16_f32 v32, v32, v33
	v_cvt_pk_bf16_f32 v16, v16, v17
	v_mov_b32_dpp v198, v18 row_shr:1 row_mask:0xf bank_mask:0xf bound_ctrl:1
	v_mov_b32_dpp v199, v19 row_shr:1 row_mask:0xf bank_mask:0xf bound_ctrl:1
	v_mov_b32_dpp v214, v10 row_shr:1 row_mask:0xf bank_mask:0xf bound_ctrl:1
	v_mov_b32_dpp v215, v11 row_shr:1 row_mask:0xf bank_mask:0xf bound_ctrl:1
	v_mov_b32_dpp v212, v34 row_shr:1 row_mask:0xf bank_mask:0xf bound_ctrl:1
	v_mov_b32_dpp v213, v35 row_shr:1 row_mask:0xf bank_mask:0xf bound_ctrl:1
	v_mov_b32_dpp v216, v30 row_shr:1 row_mask:0xf bank_mask:0xf bound_ctrl:1
	v_mov_b32_dpp v217, v31 row_shr:1 row_mask:0xf bank_mask:0xf bound_ctrl:1
	v_pk_fma_f32 v[18:19], v[18:19], v[126:127], v[122:123]
	v_pk_fma_f32 v[10:11], v[10:11], v[130:131], v[118:119]
	v_pk_fma_f32 v[18:19], v[34:35], v[106:107], v[18:19]
	v_pk_fma_f32 v[10:11], v[30:31], v[102:103], v[10:11]
	v_pk_fma_f32 v[18:19], v[50:51], v[98:99], v[18:19]
	v_pk_fma_f32 v[10:11], v[46:47], v[94:95], v[10:11]
	v_pk_fma_f32 v[34:35], v[34:35], v[126:127], v[122:123]
	v_pk_fma_f32 v[30:31], v[30:31], v[130:131], v[118:119]
	v_pk_fma_f32 v[34:35], v[50:51], v[106:107], v[34:35]
	v_pk_fma_f32 v[30:31], v[46:47], v[102:103], v[30:31]
	v_pk_fma_f32 v[34:35], v[114:115], v[98:99], v[34:35]
	v_pk_fma_f32 v[30:31], v[110:111], v[94:95], v[30:31]
	v_pk_fma_f32 v[50:51], v[50:51], v[126:127], v[122:123]
	v_pk_fma_f32 v[46:47], v[46:47], v[130:131], v[118:119]
	v_pk_fma_f32 v[50:51], v[114:115], v[106:107], v[50:51]
	v_pk_fma_f32 v[46:47], v[110:111], v[102:103], v[46:47]
	v_pk_fma_f32 v[50:51], v[198:199], v[98:99], v[50:51]
	v_pk_fma_f32 v[46:47], v[214:215], v[94:95], v[46:47]
	v_pk_fma_f32 v[114:115], v[114:115], v[126:127], v[122:123]
	v_pk_fma_f32 v[110:111], v[110:111], v[130:131], v[118:119]
	v_pk_fma_f32 v[114:115], v[198:199], v[106:107], v[114:115]
	v_pk_fma_f32 v[110:111], v[214:215], v[102:103], v[110:111]
	v_pk_fma_f32 v[114:115], v[212:213], v[98:99], v[114:115]
	v_pk_fma_f32 v[110:111], v[216:217], v[94:95], v[110:111]
	v_pk_mul_f32 v[222:223], v[114:115], s[50:51]
	v_pk_mul_f32 v[242:243], v[50:51], s[50:51]
	v_pk_mul_f32 v[244:245], v[34:35], s[50:51]
	v_pk_mul_f32 v[246:247], v[18:19], s[50:51]
	v_exp_f32_e32 v222, v222
	v_exp_f32_e32 v223, v223
	v_exp_f32_e32 v242, v242
	v_exp_f32_e32 v243, v243
	v_exp_f32_e32 v244, v244
	v_exp_f32_e32 v245, v245
	v_exp_f32_e32 v246, v246
	v_exp_f32_e32 v247, v247
	v_pk_add_f32 v[222:223], v[222:223], 1.0 op_sel_hi:[1,0]
	v_pk_add_f32 v[242:243], v[242:243], 1.0 op_sel_hi:[1,0]
	v_pk_add_f32 v[244:245], v[244:245], 1.0 op_sel_hi:[1,0]
	v_pk_add_f32 v[246:247], v[246:247], 1.0 op_sel_hi:[1,0]
	v_rcp_f32_e32 v222, v222
	v_rcp_f32_e32 v223, v223
	v_rcp_f32_e32 v242, v242
	v_rcp_f32_e32 v243, v243
	v_rcp_f32_e32 v244, v244
	v_rcp_f32_e32 v245, v245
	v_rcp_f32_e32 v246, v246
	v_rcp_f32_e32 v247, v247
	v_pk_mul_f32 v[114:115], v[114:115], v[222:223]
	v_pk_mul_f32 v[50:51], v[50:51], v[242:243]
	v_pk_mul_f32 v[34:35], v[34:35], v[244:245]
	v_pk_mul_f32 v[18:19], v[18:19], v[246:247]
	v_pk_mul_f32 v[114:115], v[114:115], v[110:111]
	v_pk_mul_f32 v[50:51], v[50:51], v[46:47]
	v_pk_mul_f32 v[34:35], v[34:35], v[30:31]
	v_pk_mul_f32 v[18:19], v[18:19], v[10:11]
	v_cvt_pk_bf16_f32 v113, v114, v115
	v_cvt_pk_bf16_f32 v49, v50, v51
	v_cvt_pk_bf16_f32 v33, v34, v35
	v_cvt_pk_bf16_f32 v17, v18, v19
	v_mov_b32_dpp v198, v12 row_shr:1 row_mask:0xf bank_mask:0xf bound_ctrl:1
	v_mov_b32_dpp v199, v13 row_shr:1 row_mask:0xf bank_mask:0xf bound_ctrl:1
	v_mov_b32_dpp v214, v4 row_shr:1 row_mask:0xf bank_mask:0xf bound_ctrl:1
	v_mov_b32_dpp v215, v5 row_shr:1 row_mask:0xf bank_mask:0xf bound_ctrl:1
	v_mov_b32_dpp v212, v24 row_shr:1 row_mask:0xf bank_mask:0xf bound_ctrl:1
	v_mov_b32_dpp v213, v25 row_shr:1 row_mask:0xf bank_mask:0xf bound_ctrl:1
	v_mov_b32_dpp v216, v20 row_shr:1 row_mask:0xf bank_mask:0xf bound_ctrl:1
	v_mov_b32_dpp v217, v21 row_shr:1 row_mask:0xf bank_mask:0xf bound_ctrl:1
	v_pk_fma_f32 v[12:13], v[12:13], v[84:85], v[80:81]
	v_pk_fma_f32 v[4:5], v[4:5], v[88:89], v[76:77]
	v_pk_fma_f32 v[12:13], v[24:25], v[64:65], v[12:13]
	v_pk_fma_f32 v[4:5], v[20:21], v[60:61], v[4:5]
	v_pk_fma_f32 v[12:13], v[40:41], v[56:57], v[12:13]
	v_pk_fma_f32 v[4:5], v[36:37], v[52:53], v[4:5]
	v_pk_fma_f32 v[24:25], v[24:25], v[84:85], v[80:81]
	v_pk_fma_f32 v[20:21], v[20:21], v[88:89], v[76:77]
	v_pk_fma_f32 v[24:25], v[40:41], v[64:65], v[24:25]
	v_pk_fma_f32 v[20:21], v[36:37], v[60:61], v[20:21]
	v_pk_fma_f32 v[24:25], v[72:73], v[56:57], v[24:25]
	v_pk_fma_f32 v[20:21], v[68:69], v[52:53], v[20:21]
	v_pk_fma_f32 v[40:41], v[40:41], v[84:85], v[80:81]
	v_pk_fma_f32 v[36:37], v[36:37], v[88:89], v[76:77]
	v_pk_fma_f32 v[40:41], v[72:73], v[64:65], v[40:41]
	v_pk_fma_f32 v[36:37], v[68:69], v[60:61], v[36:37]
	v_pk_fma_f32 v[40:41], v[198:199], v[56:57], v[40:41]
	v_pk_fma_f32 v[36:37], v[214:215], v[52:53], v[36:37]
	v_pk_fma_f32 v[72:73], v[72:73], v[84:85], v[80:81]
	v_pk_fma_f32 v[68:69], v[68:69], v[88:89], v[76:77]
	v_pk_fma_f32 v[72:73], v[198:199], v[64:65], v[72:73]
	v_pk_fma_f32 v[68:69], v[214:215], v[60:61], v[68:69]
	v_pk_fma_f32 v[72:73], v[212:213], v[56:57], v[72:73]
	v_pk_fma_f32 v[68:69], v[216:217], v[52:53], v[68:69]
	v_pk_mul_f32 v[222:223], v[72:73], s[50:51]
	v_pk_mul_f32 v[242:243], v[40:41], s[50:51]
	v_pk_mul_f32 v[244:245], v[24:25], s[50:51]
	v_pk_mul_f32 v[246:247], v[12:13], s[50:51]
	v_exp_f32_e32 v222, v222
	v_exp_f32_e32 v223, v223
	v_exp_f32_e32 v242, v242
	v_exp_f32_e32 v243, v243
	v_exp_f32_e32 v244, v244
	v_exp_f32_e32 v245, v245
	v_exp_f32_e32 v246, v246
	v_exp_f32_e32 v247, v247
	v_pk_add_f32 v[222:223], v[222:223], 1.0 op_sel_hi:[1,0]
	v_pk_add_f32 v[242:243], v[242:243], 1.0 op_sel_hi:[1,0]
	v_pk_add_f32 v[244:245], v[244:245], 1.0 op_sel_hi:[1,0]
	v_pk_add_f32 v[246:247], v[246:247], 1.0 op_sel_hi:[1,0]
	v_rcp_f32_e32 v222, v222
	v_rcp_f32_e32 v223, v223
	v_rcp_f32_e32 v242, v242
	v_rcp_f32_e32 v243, v243
	v_rcp_f32_e32 v244, v244
	v_rcp_f32_e32 v245, v245
	v_rcp_f32_e32 v246, v246
	v_rcp_f32_e32 v247, v247
	v_pk_mul_f32 v[72:73], v[72:73], v[222:223]
	v_pk_mul_f32 v[40:41], v[40:41], v[242:243]
	v_pk_mul_f32 v[24:25], v[24:25], v[244:245]
	v_pk_mul_f32 v[12:13], v[12:13], v[246:247]
	v_pk_mul_f32 v[72:73], v[72:73], v[68:69]
	v_pk_mul_f32 v[40:41], v[40:41], v[36:37]
	v_pk_mul_f32 v[24:25], v[24:25], v[20:21]
	v_pk_mul_f32 v[12:13], v[12:13], v[4:5]
	v_cvt_pk_bf16_f32 v114, v72, v73
	v_cvt_pk_bf16_f32 v50, v40, v41
	v_cvt_pk_bf16_f32 v34, v24, v25
	v_cvt_pk_bf16_f32 v18, v12, v13
	v_mov_b32_dpp v198, v14 row_shr:1 row_mask:0xf bank_mask:0xf bound_ctrl:1
	v_mov_b32_dpp v199, v15 row_shr:1 row_mask:0xf bank_mask:0xf bound_ctrl:1
	v_mov_b32_dpp v214, v6 row_shr:1 row_mask:0xf bank_mask:0xf bound_ctrl:1
	v_mov_b32_dpp v215, v7 row_shr:1 row_mask:0xf bank_mask:0xf bound_ctrl:1
	v_mov_b32_dpp v212, v26 row_shr:1 row_mask:0xf bank_mask:0xf bound_ctrl:1
	v_mov_b32_dpp v213, v27 row_shr:1 row_mask:0xf bank_mask:0xf bound_ctrl:1
	v_mov_b32_dpp v216, v22 row_shr:1 row_mask:0xf bank_mask:0xf bound_ctrl:1
	v_mov_b32_dpp v217, v23 row_shr:1 row_mask:0xf bank_mask:0xf bound_ctrl:1
	v_pk_fma_f32 v[14:15], v[14:15], v[86:87], v[82:83]
	v_pk_fma_f32 v[6:7], v[6:7], v[90:91], v[78:79]
	v_pk_fma_f32 v[14:15], v[26:27], v[66:67], v[14:15]
	v_pk_fma_f32 v[6:7], v[22:23], v[62:63], v[6:7]
	v_pk_fma_f32 v[14:15], v[42:43], v[58:59], v[14:15]
	v_pk_fma_f32 v[6:7], v[38:39], v[54:55], v[6:7]
	v_pk_fma_f32 v[26:27], v[26:27], v[86:87], v[82:83]
	v_pk_fma_f32 v[22:23], v[22:23], v[90:91], v[78:79]
	v_pk_fma_f32 v[26:27], v[42:43], v[66:67], v[26:27]
	v_pk_fma_f32 v[22:23], v[38:39], v[62:63], v[22:23]
	v_pk_fma_f32 v[26:27], v[74:75], v[58:59], v[26:27]
	v_pk_fma_f32 v[22:23], v[70:71], v[54:55], v[22:23]
	v_pk_fma_f32 v[42:43], v[42:43], v[86:87], v[82:83]
	v_pk_fma_f32 v[38:39], v[38:39], v[90:91], v[78:79]
	v_pk_fma_f32 v[42:43], v[74:75], v[66:67], v[42:43]
	v_pk_fma_f32 v[38:39], v[70:71], v[62:63], v[38:39]
	v_pk_fma_f32 v[42:43], v[198:199], v[58:59], v[42:43]
	v_pk_fma_f32 v[38:39], v[214:215], v[54:55], v[38:39]
	v_pk_fma_f32 v[74:75], v[74:75], v[86:87], v[82:83]
	v_pk_fma_f32 v[70:71], v[70:71], v[90:91], v[78:79]
	v_pk_fma_f32 v[74:75], v[198:199], v[66:67], v[74:75]
	v_pk_fma_f32 v[70:71], v[214:215], v[62:63], v[70:71]
	v_pk_fma_f32 v[74:75], v[212:213], v[58:59], v[74:75]
	v_pk_fma_f32 v[70:71], v[216:217], v[54:55], v[70:71]
	v_pk_mul_f32 v[222:223], v[74:75], s[50:51]
	v_pk_mul_f32 v[242:243], v[42:43], s[50:51]
	v_pk_mul_f32 v[244:245], v[26:27], s[50:51]
	v_pk_mul_f32 v[246:247], v[14:15], s[50:51]
	v_exp_f32_e32 v222, v222
	v_exp_f32_e32 v223, v223
	v_exp_f32_e32 v242, v242
	v_exp_f32_e32 v243, v243
	v_exp_f32_e32 v244, v244
	v_exp_f32_e32 v245, v245
	v_exp_f32_e32 v246, v246
	v_exp_f32_e32 v247, v247
	v_pk_add_f32 v[222:223], v[222:223], 1.0 op_sel_hi:[1,0]
	v_pk_add_f32 v[242:243], v[242:243], 1.0 op_sel_hi:[1,0]
	v_pk_add_f32 v[244:245], v[244:245], 1.0 op_sel_hi:[1,0]
	v_pk_add_f32 v[246:247], v[246:247], 1.0 op_sel_hi:[1,0]
	v_rcp_f32_e32 v222, v222
	v_rcp_f32_e32 v223, v223
	v_rcp_f32_e32 v242, v242
	v_rcp_f32_e32 v243, v243
	v_rcp_f32_e32 v244, v244
	v_rcp_f32_e32 v245, v245
	v_rcp_f32_e32 v246, v246
	v_rcp_f32_e32 v247, v247
	v_pk_mul_f32 v[74:75], v[74:75], v[222:223]
	v_pk_mul_f32 v[42:43], v[42:43], v[242:243]
	v_pk_mul_f32 v[26:27], v[26:27], v[244:245]
	v_pk_mul_f32 v[14:15], v[14:15], v[246:247]
	v_pk_mul_f32 v[74:75], v[74:75], v[70:71]
	v_pk_mul_f32 v[42:43], v[42:43], v[38:39]
	v_pk_mul_f32 v[26:27], v[26:27], v[22:23]
	v_pk_mul_f32 v[14:15], v[14:15], v[6:7]
	v_cvt_pk_bf16_f32 v115, v74, v75
	v_cvt_pk_bf16_f32 v51, v42, v43
	v_cvt_pk_bf16_f32 v35, v26, v27
	v_cvt_pk_bf16_f32 v19, v14, v15
	s_add_u32 s20, s82, 0xb0000
	s_addc_u32 s21, s83, 0
	global_store_dwordx4 v240, v[112:115], s[20:21]
	s_add_u32 s20, s82, 0xb1600
	s_addc_u32 s21, s83, 0
	global_store_dwordx4 v240, v[48:51], s[20:21]
	s_add_u32 s20, s82, 0xb2c00
	s_addc_u32 s21, s83, 0
	global_store_dwordx4 v240, v[32:35], s[20:21]
	s_add_u32 s20, s82, 0xb4200
	s_addc_u32 s21, s83, 0
	global_store_dwordx4 v240, v[16:19], s[20:21]
	s_mov_b64 s[50:51], -1
	s_branch .LBB0_76

.LBB0_136:
	s_add_u32 s23, s48, 0xfffc0080
	s_addc_u32 s24, s49, -1
	ds_read_b128 v[146:149], v194
	ds_read_b128 v[150:153], v194 offset:1024
	ds_read_b128 v[154:157], v194 offset:2048
	ds_read_b128 v[158:161], v194 offset:3072
	s_cmp_eq_u32 s22, 12
	s_cselect_b32 s53, s45, s24
	s_cselect_b32 s52, s44, s23
	s_cselect_b32 s51, s47, s21
	s_cselect_b32 s50, s46, s20
	s_add_i32 m0, s54, 0xc000
	ds_read_b128 v[162:165], v144
	ds_read_b128 v[166:169], v144 offset:1024
	ds_read_b128 v[170:173], v144 offset:2048
	ds_read_b128 v[174:177], v144 offset:3072
	ds_read_b128 v[178:181], v144 offset:4096
	ds_read_b128 v[182:185], v144 offset:5120
	ds_read_b128 v[186:189], v144 offset:6144
	global_load_lds_dwordx4 v138, s[48:49]
	s_add_i32 m0, s54, 0xe000
	ds_read_b128 v[190:193], v144 offset:7168
	global_load_lds_dwordx4 v140, s[48:49]
	s_waitcnt lgkmcnt(8)
	s_barrier
	s_waitcnt lgkmcnt(0)
	v_mfma_f32_16x16x32_bf16 v[128:131], v[146:149], v[162:165], v[128:131]
	v_mfma_f32_16x16x32_bf16 v[124:127], v[154:157], v[162:165], v[124:127]
	v_mfma_f32_16x16x32_bf16 v[120:123], v[146:149], v[170:173], v[120:123]
	v_mfma_f32_16x16x32_bf16 v[116:119], v[154:157], v[170:173], v[116:119]
	v_mfma_f32_16x16x32_bf16 v[104:107], v[146:149], v[178:181], v[104:107]
	v_mfma_f32_16x16x32_bf16 v[100:103], v[154:157], v[178:181], v[100:103]
	v_mfma_f32_16x16x32_bf16 v[88:91], v[146:149], v[186:189], v[88:91]
	v_mfma_f32_16x16x32_bf16 v[84:87], v[154:157], v[186:189], v[84:87]
	v_mfma_f32_16x16x32_bf16 v[128:131], v[150:153], v[166:169], v[128:131]
	v_mfma_f32_16x16x32_bf16 v[124:127], v[158:161], v[166:169], v[124:127]
	v_mfma_f32_16x16x32_bf16 v[120:123], v[150:153], v[174:177], v[120:123]
	v_mfma_f32_16x16x32_bf16 v[116:119], v[158:161], v[174:177], v[116:119]
	v_mfma_f32_16x16x32_bf16 v[104:107], v[150:153], v[182:185], v[104:107]
	v_mfma_f32_16x16x32_bf16 v[100:103], v[158:161], v[182:185], v[100:103]
	v_mfma_f32_16x16x32_bf16 v[88:91], v[150:153], v[190:193], v[88:91]
	v_mfma_f32_16x16x32_bf16 v[84:87], v[158:161], v[190:193], v[84:87]
	s_barrier
	s_add_i32 m0, s37, 0x10000
	ds_read_b128 v[202:205], v194 offset:16384
	ds_read_b128 v[206:209], v194 offset:17408
	ds_read_b128 v[210:213], v194 offset:18432
	global_load_lds_dwordx4 v132, s[50:51]
	s_add_i32 m0, s37, 0x12000
	ds_read_b128 v[214:217], v194 offset:19456
	global_load_lds_dwordx4 v136, s[50:51]
	s_barrier
	s_waitcnt lgkmcnt(0)
	v_mfma_f32_16x16x32_bf16 v[112:115], v[202:205], v[162:165], v[112:115]
	v_mfma_f32_16x16x32_bf16 v[108:111], v[210:213], v[162:165], v[108:111]
	v_mfma_f32_16x16x32_bf16 v[96:99], v[202:205], v[170:173], v[96:99]
	v_mfma_f32_16x16x32_bf16 v[92:95], v[210:213], v[170:173], v[92:95]
	v_mfma_f32_16x16x32_bf16 v[80:83], v[202:205], v[178:181], v[80:83]
	v_mfma_f32_16x16x32_bf16 v[76:79], v[210:213], v[178:181], v[76:79]
	v_mfma_f32_16x16x32_bf16 v[72:75], v[202:205], v[186:189], v[72:75]
	v_mfma_f32_16x16x32_bf16 v[68:71], v[210:213], v[186:189], v[68:71]
	v_mfma_f32_16x16x32_bf16 v[112:115], v[206:209], v[166:169], v[112:115]
	v_mfma_f32_16x16x32_bf16 v[108:111], v[214:217], v[166:169], v[108:111]
	v_mfma_f32_16x16x32_bf16 v[96:99], v[206:209], v[174:177], v[96:99]
	v_mfma_f32_16x16x32_bf16 v[92:95], v[214:217], v[174:177], v[92:95]
	v_mfma_f32_16x16x32_bf16 v[80:83], v[206:209], v[182:185], v[80:83]
	v_mfma_f32_16x16x32_bf16 v[76:79], v[214:217], v[182:185], v[76:79]
	v_mfma_f32_16x16x32_bf16 v[72:75], v[206:209], v[190:193], v[72:75]
	v_mfma_f32_16x16x32_bf16 v[68:71], v[214:217], v[190:193], v[68:71]
	s_mov_b32 m0, s54
	s_barrier
	ds_read_b128 v[162:165], v144 offset:16384
	ds_read_b128 v[166:169], v144 offset:17408
	ds_read_b128 v[170:173], v144 offset:18432
	ds_read_b128 v[174:177], v144 offset:19456
	ds_read_b128 v[178:181], v144 offset:20480
	ds_read_b128 v[182:185], v144 offset:21504
	ds_read_b128 v[186:189], v144 offset:22528
	global_load_lds_dwordx4 v0, s[52:53]
	s_mov_b32 m0, s55
	ds_read_b128 v[190:193], v144 offset:23552
	global_load_lds_dwordx4 v134, s[52:53]
	s_barrier
	s_waitcnt lgkmcnt(0)
	v_mfma_f32_16x16x32_bf16 v[64:67], v[146:149], v[162:165], v[64:67]
	v_mfma_f32_16x16x32_bf16 v[60:63], v[154:157], v[162:165], v[60:63]
	v_mfma_f32_16x16x32_bf16 v[56:59], v[146:149], v[170:173], v[56:59]
	v_mfma_f32_16x16x32_bf16 v[52:55], v[154:157], v[170:173], v[52:55]
	v_mfma_f32_16x16x32_bf16 v[40:43], v[146:149], v[178:181], v[40:43]
	v_mfma_f32_16x16x32_bf16 v[36:39], v[154:157], v[178:181], v[36:39]
	v_mfma_f32_16x16x32_bf16 v[24:27], v[146:149], v[186:189], v[24:27]
	v_mfma_f32_16x16x32_bf16 v[16:19], v[154:157], v[186:189], v[16:19]
	v_mfma_f32_16x16x32_bf16 v[64:67], v[150:153], v[166:169], v[64:67]
	v_mfma_f32_16x16x32_bf16 v[60:63], v[158:161], v[166:169], v[60:63]
	v_mfma_f32_16x16x32_bf16 v[56:59], v[150:153], v[174:177], v[56:59]
	v_mfma_f32_16x16x32_bf16 v[52:55], v[158:161], v[174:177], v[52:55]
	v_mfma_f32_16x16x32_bf16 v[40:43], v[150:153], v[182:185], v[40:43]
	v_mfma_f32_16x16x32_bf16 v[36:39], v[158:161], v[182:185], v[36:39]
	v_mfma_f32_16x16x32_bf16 v[24:27], v[150:153], v[190:193], v[24:27]
	v_mfma_f32_16x16x32_bf16 v[16:19], v[158:161], v[190:193], v[16:19]
	s_barrier
	s_add_i32 m0, s37, 0x14000
	s_add_u32 s24, s50, 0x40000
	s_addc_u32 s25, s51, 0
	global_load_lds_dwordx4 v132, s[24:25]
	s_add_i32 m0, s37, 0x16000
	s_waitcnt vmcnt(5)
	global_load_lds_dwordx4 v136, s[24:25]
	s_barrier
	v_mfma_f32_16x16x32_bf16 v[48:51], v[202:205], v[162:165], v[48:51]
	v_mfma_f32_16x16x32_bf16 v[44:47], v[210:213], v[162:165], v[44:47]
	v_mfma_f32_16x16x32_bf16 v[32:35], v[202:205], v[170:173], v[32:35]
	v_mfma_f32_16x16x32_bf16 v[28:31], v[210:213], v[170:173], v[28:31]
	v_mfma_f32_16x16x32_bf16 v[20:23], v[202:205], v[178:181], v[20:23]
	v_mfma_f32_16x16x32_bf16 v[12:15], v[210:213], v[178:181], v[12:15]
	v_mfma_f32_16x16x32_bf16 v[8:11], v[202:205], v[186:189], v[8:11]
	v_mfma_f32_16x16x32_bf16 v[4:7], v[210:213], v[186:189], v[4:7]
	v_mfma_f32_16x16x32_bf16 v[48:51], v[206:209], v[166:169], v[48:51]
	v_mfma_f32_16x16x32_bf16 v[44:47], v[214:217], v[166:169], v[44:47]
	v_mfma_f32_16x16x32_bf16 v[32:35], v[206:209], v[174:177], v[32:35]
	v_mfma_f32_16x16x32_bf16 v[28:31], v[214:217], v[174:177], v[28:31]
	v_mfma_f32_16x16x32_bf16 v[20:23], v[206:209], v[182:185], v[20:23]
	v_mfma_f32_16x16x32_bf16 v[12:15], v[214:217], v[182:185], v[12:15]
	v_mfma_f32_16x16x32_bf16 v[8:11], v[206:209], v[190:193], v[8:11]
	v_mfma_f32_16x16x32_bf16 v[4:7], v[214:217], v[190:193], v[4:7]
	s_barrier
	ds_read_b128 v[146:149], v194 offset:32768
	ds_read_b128 v[150:153], v194 offset:33792
	ds_read_b128 v[154:157], v194 offset:34816
	ds_read_b128 v[158:161], v194 offset:35840
	s_add_u32 s24, s52, 0x40000
	s_addc_u32 s25, s53, 0
	s_mov_b32 m0, s56
	ds_read_b128 v[162:165], v144 offset:32768
	ds_read_b128 v[166:169], v144 offset:33792
	ds_read_b128 v[170:173], v144 offset:34816
	ds_read_b128 v[174:177], v144 offset:35840
	ds_read_b128 v[178:181], v144 offset:36864
	ds_read_b128 v[182:185], v144 offset:37888
	ds_read_b128 v[186:189], v144 offset:38912
	global_load_lds_dwordx4 v0, s[24:25]
	s_mov_b32 m0, s57
	ds_read_b128 v[190:193], v144 offset:39936
	global_load_lds_dwordx4 v134, s[24:25]
	s_waitcnt lgkmcnt(8)
	s_barrier
	s_waitcnt lgkmcnt(0)
	v_mfma_f32_16x16x32_bf16 v[128:131], v[146:149], v[162:165], v[128:131]
	v_mfma_f32_16x16x32_bf16 v[124:127], v[154:157], v[162:165], v[124:127]
	v_mfma_f32_16x16x32_bf16 v[120:123], v[146:149], v[170:173], v[120:123]
	v_mfma_f32_16x16x32_bf16 v[116:119], v[154:157], v[170:173], v[116:119]
	v_mfma_f32_16x16x32_bf16 v[104:107], v[146:149], v[178:181], v[104:107]
	v_mfma_f32_16x16x32_bf16 v[100:103], v[154:157], v[178:181], v[100:103]
	v_mfma_f32_16x16x32_bf16 v[88:91], v[146:149], v[186:189], v[88:91]
	v_mfma_f32_16x16x32_bf16 v[84:87], v[154:157], v[186:189], v[84:87]
	v_mfma_f32_16x16x32_bf16 v[128:131], v[150:153], v[166:169], v[128:131]
	v_mfma_f32_16x16x32_bf16 v[124:127], v[158:161], v[166:169], v[124:127]
	v_mfma_f32_16x16x32_bf16 v[120:123], v[150:153], v[174:177], v[120:123]
	v_mfma_f32_16x16x32_bf16 v[116:119], v[158:161], v[174:177], v[116:119]
	v_mfma_f32_16x16x32_bf16 v[104:107], v[150:153], v[182:185], v[104:107]
	v_mfma_f32_16x16x32_bf16 v[100:103], v[158:161], v[182:185], v[100:103]
	v_mfma_f32_16x16x32_bf16 v[88:91], v[150:153], v[190:193], v[88:91]
	v_mfma_f32_16x16x32_bf16 v[84:87], v[158:161], v[190:193], v[84:87]
	s_barrier
	s_add_i32 m0, s37, 0x18000
	ds_read_b128 v[202:205], v194 offset:49152
	ds_read_b128 v[206:209], v194 offset:50176
	ds_read_b128 v[210:213], v194 offset:51200
	s_add_u32 s98, s50, 0x80
	s_addc_u32 s99, s51, 0
	global_load_lds_dwordx4 v132, s[98:99]
	s_add_i32 m0, s37, 0x1a000
	ds_read_b128 v[214:217], v194 offset:52224
	global_load_lds_dwordx4 v136, s[98:99]
	s_barrier
	s_waitcnt lgkmcnt(0)
	v_mfma_f32_16x16x32_bf16 v[112:115], v[202:205], v[162:165], v[112:115]
	v_mfma_f32_16x16x32_bf16 v[108:111], v[210:213], v[162:165], v[108:111]
	v_mfma_f32_16x16x32_bf16 v[96:99], v[202:205], v[170:173], v[96:99]
	v_mfma_f32_16x16x32_bf16 v[92:95], v[210:213], v[170:173], v[92:95]
	v_mfma_f32_16x16x32_bf16 v[80:83], v[202:205], v[178:181], v[80:83]
	v_mfma_f32_16x16x32_bf16 v[76:79], v[210:213], v[178:181], v[76:79]
	v_mfma_f32_16x16x32_bf16 v[72:75], v[202:205], v[186:189], v[72:75]
	v_mfma_f32_16x16x32_bf16 v[68:71], v[210:213], v[186:189], v[68:71]
	v_mfma_f32_16x16x32_bf16 v[112:115], v[206:209], v[166:169], v[112:115]
	v_mfma_f32_16x16x32_bf16 v[108:111], v[214:217], v[166:169], v[108:111]
	v_mfma_f32_16x16x32_bf16 v[96:99], v[206:209], v[174:177], v[96:99]
	v_mfma_f32_16x16x32_bf16 v[92:95], v[214:217], v[174:177], v[92:95]
	v_mfma_f32_16x16x32_bf16 v[80:83], v[206:209], v[182:185], v[80:83]
	v_mfma_f32_16x16x32_bf16 v[76:79], v[214:217], v[182:185], v[76:79]
	v_mfma_f32_16x16x32_bf16 v[72:75], v[206:209], v[190:193], v[72:75]
	v_mfma_f32_16x16x32_bf16 v[68:71], v[214:217], v[190:193], v[68:71]
	s_mov_b32 m0, s59
	s_barrier
	ds_read_b128 v[162:165], v144 offset:49152
	ds_read_b128 v[166:169], v144 offset:50176
	ds_read_b128 v[170:173], v144 offset:51200
	ds_read_b128 v[174:177], v144 offset:52224
	ds_read_b128 v[178:181], v144 offset:53248
	ds_read_b128 v[182:185], v144 offset:54272
	ds_read_b128 v[186:189], v144 offset:55296
	s_add_u32 s98, s52, 0x80
	s_addc_u32 s99, s53, 0
	global_load_lds_dwordx4 v0, s[98:99]
	s_mov_b32 m0, s60
	ds_read_b128 v[190:193], v144 offset:56320
	global_load_lds_dwordx4 v134, s[98:99]
	s_barrier
	s_waitcnt lgkmcnt(0)
	v_mfma_f32_16x16x32_bf16 v[64:67], v[146:149], v[162:165], v[64:67]
	v_mfma_f32_16x16x32_bf16 v[60:63], v[154:157], v[162:165], v[60:63]
	v_mfma_f32_16x16x32_bf16 v[56:59], v[146:149], v[170:173], v[56:59]
	v_mfma_f32_16x16x32_bf16 v[52:55], v[154:157], v[170:173], v[52:55]
	v_mfma_f32_16x16x32_bf16 v[40:43], v[146:149], v[178:181], v[40:43]
	v_mfma_f32_16x16x32_bf16 v[36:39], v[154:157], v[178:181], v[36:39]
	v_mfma_f32_16x16x32_bf16 v[24:27], v[146:149], v[186:189], v[24:27]
	v_mfma_f32_16x16x32_bf16 v[16:19], v[154:157], v[186:189], v[16:19]
	v_mfma_f32_16x16x32_bf16 v[64:67], v[150:153], v[166:169], v[64:67]
	v_mfma_f32_16x16x32_bf16 v[60:63], v[158:161], v[166:169], v[60:63]
	v_mfma_f32_16x16x32_bf16 v[56:59], v[150:153], v[174:177], v[56:59]
	v_mfma_f32_16x16x32_bf16 v[52:55], v[158:161], v[174:177], v[52:55]
	v_mfma_f32_16x16x32_bf16 v[40:43], v[150:153], v[182:185], v[40:43]
	v_mfma_f32_16x16x32_bf16 v[36:39], v[158:161], v[182:185], v[36:39]
	v_mfma_f32_16x16x32_bf16 v[24:27], v[150:153], v[190:193], v[24:27]
	v_mfma_f32_16x16x32_bf16 v[16:19], v[158:161], v[190:193], v[16:19]
	s_barrier
	s_add_i32 m0, s37, 0x1c000
	s_add_u32 s24, s50, 0x40080
	s_addc_u32 s25, s51, 0
	global_load_lds_dwordx4 v132, s[24:25]
	s_add_i32 m0, s37, 0x1e000
	s_waitcnt vmcnt(5)
	global_load_lds_dwordx4 v136, s[24:25]
	s_barrier
	v_mfma_f32_16x16x32_bf16 v[48:51], v[202:205], v[162:165], v[48:51]
	v_mfma_f32_16x16x32_bf16 v[44:47], v[210:213], v[162:165], v[44:47]
	v_mfma_f32_16x16x32_bf16 v[32:35], v[202:205], v[170:173], v[32:35]
	v_mfma_f32_16x16x32_bf16 v[28:31], v[210:213], v[170:173], v[28:31]
	v_mfma_f32_16x16x32_bf16 v[20:23], v[202:205], v[178:181], v[20:23]
	v_mfma_f32_16x16x32_bf16 v[12:15], v[210:213], v[178:181], v[12:15]
	v_mfma_f32_16x16x32_bf16 v[8:11], v[202:205], v[186:189], v[8:11]
	v_mfma_f32_16x16x32_bf16 v[4:7], v[210:213], v[186:189], v[4:7]
	v_mfma_f32_16x16x32_bf16 v[48:51], v[206:209], v[166:169], v[48:51]
	v_mfma_f32_16x16x32_bf16 v[44:47], v[214:217], v[166:169], v[44:47]
	v_mfma_f32_16x16x32_bf16 v[32:35], v[206:209], v[174:177], v[32:35]
	v_mfma_f32_16x16x32_bf16 v[28:31], v[214:217], v[174:177], v[28:31]
	v_mfma_f32_16x16x32_bf16 v[20:23], v[206:209], v[182:185], v[20:23]
	v_mfma_f32_16x16x32_bf16 v[12:15], v[214:217], v[182:185], v[12:15]
	v_mfma_f32_16x16x32_bf16 v[8:11], v[206:209], v[190:193], v[8:11]
	v_mfma_f32_16x16x32_bf16 v[4:7], v[214:217], v[190:193], v[4:7]
	s_add_i32 s22, s22, 2
	s_add_u32 s48, s48, 0x100
	s_addc_u32 s49, s49, 0
	s_add_u32 s20, s20, 0x100
	s_addc_u32 s21, s21, 0
	s_cmp_gt_u32 s22, 13
	s_barrier
	s_cbranch_scc0 .LBB0_136
	v_lshl_add_u32 v146, s0, 8, v142
	v_cvt_pk_bf16_f32 v72, v72, v73
	v_cvt_pk_bf16_f32 v73, v74, v75
	v_cvt_pk_bf16_f32 v74, v68, v69
	v_add_u32_e32 v68, 0x80, v146
	s_lshl_b32 s0, s1, 8
	v_ashrrev_i32_e32 v147, 31, v146
	v_readlane_b32 s20, v252, 12
	v_cvt_pk_bf16_f32 v112, v112, v113
	v_cvt_pk_bf16_f32 v113, v114, v115
	v_cvt_pk_bf16_f32 v114, v108, v109
	v_or_b32_e32 v108, 16, v146
	v_ashrrev_i32_e32 v69, 31, v68
	v_cvt_pk_bf16_f32 v48, v48, v49
	v_cvt_pk_bf16_f32 v49, v50, v51
	v_cvt_pk_bf16_f32 v50, v44, v45
	v_add_u32_e32 v44, 0x90, v146
	s_ashr_i32 s1, s0, 31
	v_lshlrev_b64 v[148:149], 11, v[146:147]
	v_readlane_b32 s21, v252, 13
	v_ashrrev_i32_e32 v109, 31, v108
	v_cvt_pk_bf16_f32 v96, v96, v97
	v_cvt_pk_bf16_f32 v97, v98, v99
	v_cvt_pk_bf16_f32 v98, v92, v93
	v_or_b32_e32 v92, 32, v146
	v_lshlrev_b64 v[68:69], 11, v[68:69]
	v_ashrrev_i32_e32 v45, 31, v44
	v_cvt_pk_bf16_f32 v32, v32, v33
	v_cvt_pk_bf16_f32 v33, v34, v35
	v_cvt_pk_bf16_f32 v34, v28, v29
	v_add_u32_e32 v28, 0xa0, v146
	v_lshl_add_u64 v[148:149], s[20:21], 0, v[148:149]
	s_lshl_b64 s[0:1], s[0:1], 1
	v_lshlrev_b64 v[108:109], 11, v[108:109]
	v_ashrrev_i32_e32 v93, 31, v92
	v_cvt_pk_bf16_f32 v80, v80, v81
	v_cvt_pk_bf16_f32 v81, v82, v83
	v_cvt_pk_bf16_f32 v82, v76, v77
	v_or_b32_e32 v76, 48, v146
	v_lshl_add_u64 v[68:69], s[20:21], 0, v[68:69]
	v_lshlrev_b64 v[44:45], 11, v[44:45]
	v_ashrrev_i32_e32 v29, 31, v28
	v_cvt_pk_bf16_f32 v20, v20, v21
	v_cvt_pk_bf16_f32 v21, v22, v23
	v_cvt_pk_bf16_f32 v22, v12, v13
	v_add_u32_e32 v12, 0xb0, v146
	v_lshl_add_u64 v[148:149], v[148:149], 0, s[0:1]
	v_lshl_add_u64 v[108:109], s[20:21], 0, v[108:109]
	v_lshlrev_b64 v[92:93], 11, v[92:93]
	v_ashrrev_i32_e32 v77, 31, v76
	v_lshl_add_u64 v[68:69], v[68:69], 0, s[0:1]
	v_lshl_add_u64 v[44:45], s[20:21], 0, v[44:45]
	v_lshlrev_b64 v[28:29], 11, v[28:29]
	v_ashrrev_i32_e32 v13, 31, v12
	v_lshl_add_u64 v[148:149], v[148:149], 0, s[72:73]
	v_lshl_add_u64 v[108:109], v[108:109], 0, s[0:1]
	v_lshl_add_u64 v[92:93], s[20:21], 0, v[92:93]
	v_lshlrev_b64 v[76:77], 11, v[76:77]
	v_lshl_add_u64 v[68:69], v[68:69], 0, s[72:73]
	v_lshl_add_u64 v[44:45], v[44:45], 0, s[0:1]
	v_lshl_add_u64 v[28:29], s[20:21], 0, v[28:29]
	v_lshlrev_b64 v[12:13], 11, v[12:13]
	v_lshl_add_u64 v[148:149], v[148:149], 0, v[2:3]
	v_cvt_pk_bf16_f32 v115, v110, v111
	v_lshl_add_u64 v[108:109], v[108:109], 0, s[72:73]
	v_lshl_add_u64 v[92:93], v[92:93], 0, s[0:1]
	v_lshl_add_u64 v[76:77], s[20:21], 0, v[76:77]
	v_lshl_add_u64 v[68:69], v[68:69], 0, v[2:3]
	v_cvt_pk_bf16_f32 v51, v46, v47
	v_lshl_add_u64 v[44:45], v[44:45], 0, s[72:73]
	v_lshl_add_u64 v[28:29], v[28:29], 0, s[0:1]
	v_lshl_add_u64 v[12:13], s[20:21], 0, v[12:13]
	global_store_dwordx4 v[148:149], v[112:115], off offset:256
	v_cvt_pk_bf16_f32 v99, v94, v95
	v_lshl_add_u64 v[92:93], v[92:93], 0, s[72:73]
	v_lshl_add_u64 v[112:113], v[108:109], 0, v[2:3]
	v_lshl_add_u64 v[76:77], v[76:77], 0, s[0:1]
	global_store_dwordx4 v[68:69], v[48:51], off offset:256
	v_cvt_pk_bf16_f32 v35, v30, v31
	v_lshl_add_u64 v[28:29], v[28:29], 0, s[72:73]
	v_lshl_add_u64 v[48:49], v[44:45], 0, v[2:3]
	v_lshl_add_u64 v[12:13], v[12:13], 0, s[0:1]
	global_store_dwordx4 v[112:113], v[96:99], off offset:256
	v_cvt_pk_bf16_f32 v83, v78, v79
	v_lshl_add_u64 v[76:77], v[76:77], 0, s[72:73]
	v_lshl_add_u64 v[96:97], v[92:93], 0, v[2:3]
	global_store_dwordx4 v[48:49], v[32:35], off offset:256
	v_cvt_pk_bf16_f32 v23, v14, v15
	v_lshl_add_u64 v[12:13], v[12:13], 0, s[72:73]
	v_lshl_add_u64 v[32:33], v[28:29], 0, v[2:3]
	v_cvt_pk_bf16_f32 v128, v128, v129
	v_cvt_pk_bf16_f32 v129, v130, v131
	v_cvt_pk_bf16_f32 v130, v124, v125
	v_cvt_pk_bf16_f32 v131, v126, v127
	v_cvt_pk_bf16_f32 v108, v120, v121
	v_cvt_pk_bf16_f32 v109, v122, v123
	v_cvt_pk_bf16_f32 v110, v116, v117
	v_cvt_pk_bf16_f32 v111, v118, v119
	v_cvt_pk_bf16_f32 v92, v104, v105
	v_cvt_pk_bf16_f32 v93, v106, v107
	v_cvt_pk_bf16_f32 v94, v100, v101
	v_cvt_pk_bf16_f32 v95, v102, v103
	global_store_dwordx4 v[96:97], v[80:83], off offset:256
	v_cvt_pk_bf16_f32 v78, v84, v85
	v_cvt_pk_bf16_f32 v79, v86, v87
	v_lshl_add_u64 v[80:81], v[76:77], 0, v[2:3]
	v_cvt_pk_bf16_f32 v76, v88, v89
	v_cvt_pk_bf16_f32 v77, v90, v91
	v_cvt_pk_bf16_f32 v75, v70, v71
	v_cvt_pk_bf16_f32 v64, v64, v65
	v_cvt_pk_bf16_f32 v65, v66, v67
	v_cvt_pk_bf16_f32 v66, v60, v61
	v_cvt_pk_bf16_f32 v67, v62, v63
	v_cvt_pk_bf16_f32 v44, v56, v57
	v_cvt_pk_bf16_f32 v45, v58, v59
	v_cvt_pk_bf16_f32 v46, v52, v53
	v_cvt_pk_bf16_f32 v47, v54, v55
	v_cvt_pk_bf16_f32 v28, v40, v41
	v_cvt_pk_bf16_f32 v29, v42, v43
	v_cvt_pk_bf16_f32 v30, v36, v37
	v_cvt_pk_bf16_f32 v31, v38, v39
	global_store_dwordx4 v[32:33], v[20:23], off offset:256
	v_cvt_pk_bf16_f32 v14, v16, v17
	v_cvt_pk_bf16_f32 v15, v18, v19
	v_lshl_add_u64 v[20:21], v[12:13], 0, v[2:3]
	v_cvt_pk_bf16_f32 v12, v24, v25
	v_cvt_pk_bf16_f32 v13, v26, v27
	v_cvt_pk_bf16_f32 v8, v8, v9
	v_cvt_pk_bf16_f32 v9, v10, v11
	v_cvt_pk_bf16_f32 v10, v4, v5
	v_cvt_pk_bf16_f32 v11, v6, v7
	s_and_b64 vcc, exec, s[38:39]
	s_mov_b32 s1, s40
	s_mov_b32 s0, s42
	s_mov_b64 s[50:51], s[46:47]
	s_mov_b64 s[48:49], s[44:45]
	global_store_dwordx4 v[148:149], v[128:131], off
	global_store_dwordx4 v[112:113], v[108:111], off
	global_store_dwordx4 v[96:97], v[92:95], off
	global_store_dwordx4 v[80:81], v[76:79], off
	global_store_dwordx4 v[80:81], v[72:75], off offset:256
	global_store_dwordx4 v[68:69], v[64:67], off
	global_store_dwordx4 v[48:49], v[44:47], off
	global_store_dwordx4 v[32:33], v[28:31], off
	global_store_dwordx4 v[20:21], v[12:15], off
	global_store_dwordx4 v[20:21], v[8:11], off offset:256
	s_cbranch_vccz .LBB0_129
	s_waitcnt vmcnt(0)
	s_cmpk_gt_u32 s31, 0xff
	s_cbranch_scc1 .LBB0_140
	s_barrier

.LBB0_175:
	s_add_i32 s26, s27, 2
	s_add_u32 s44, s40, 0x100
	s_addc_u32 s45, s41, 0
	ds_read_b128 v[132:135], v1
	ds_read_b128 v[164:167], v1 offset:1024
	ds_read_b128 v[168:171], v1 offset:2048
	ds_read_b128 v[174:177], v1 offset:3072
	s_cmp_eq_u32 s23, s27
	s_cselect_b32 s49, s1, s45
	s_cselect_b32 s48, s0, s44
	s_cselect_b32 s47, s43, s25
	s_cselect_b32 s46, s42, s24
	s_add_i32 m0, s53, 0xc000
	ds_read_b128 v[178:181], v172
	ds_read_b128 v[182:185], v172 offset:1024
	ds_read_b128 v[186:189], v172 offset:2048
	ds_read_b128 v[190:193], v172 offset:3072
	ds_read_b128 v[202:205], v172 offset:4096
	ds_read_b128 v[206:209], v172 offset:5120
	ds_read_b128 v[210:213], v172 offset:6144
	global_load_lds_dwordx4 v160, s[40:41]
	s_add_i32 m0, s53, 0xe000
	ds_read_b128 v[214:217], v172 offset:7168
	global_load_lds_dwordx4 v162, s[40:41]
	s_waitcnt lgkmcnt(8)
	s_barrier
	s_waitcnt lgkmcnt(0)
	v_mfma_f32_16x16x32_bf16 v[4:7], v[132:135], v[178:181], v[4:7]
	v_mfma_f32_16x16x32_bf16 v[8:11], v[168:171], v[178:181], v[8:11]
	v_mfma_f32_16x16x32_bf16 v[128:131], v[132:135], v[186:189], v[128:131]
	v_mfma_f32_16x16x32_bf16 v[124:127], v[168:171], v[186:189], v[124:127]
	v_mfma_f32_16x16x32_bf16 v[120:123], v[132:135], v[202:205], v[120:123]
	v_mfma_f32_16x16x32_bf16 v[116:119], v[168:171], v[202:205], v[116:119]
	v_mfma_f32_16x16x32_bf16 v[112:115], v[132:135], v[210:213], v[112:115]
	v_mfma_f32_16x16x32_bf16 v[108:111], v[168:171], v[210:213], v[108:111]
	v_mfma_f32_16x16x32_bf16 v[4:7], v[164:167], v[182:185], v[4:7]
	v_mfma_f32_16x16x32_bf16 v[8:11], v[174:177], v[182:185], v[8:11]
	v_mfma_f32_16x16x32_bf16 v[128:131], v[164:167], v[190:193], v[128:131]
	v_mfma_f32_16x16x32_bf16 v[124:127], v[174:177], v[190:193], v[124:127]
	v_mfma_f32_16x16x32_bf16 v[120:123], v[164:167], v[206:209], v[120:123]
	v_mfma_f32_16x16x32_bf16 v[116:119], v[174:177], v[206:209], v[116:119]
	v_mfma_f32_16x16x32_bf16 v[112:115], v[164:167], v[214:217], v[112:115]
	v_mfma_f32_16x16x32_bf16 v[108:111], v[174:177], v[214:217], v[108:111]
	s_barrier
	ds_read_b128 v[236:239], v1 offset:16384
	ds_read_b128 v[240:243], v1 offset:17408
	s_add_i32 m0, s52, 0x10000
	ds_read_b128 v[244:247], v1 offset:18432
	global_load_lds_dwordx4 v138, s[46:47]
	s_add_i32 m0, s52, 0x12000
	ds_read_b128 v[248:251], v1 offset:19456
	global_load_lds_dwordx4 v142, s[46:47]
	s_barrier
	s_waitcnt lgkmcnt(0)
	v_mfma_f32_16x16x32_bf16 v[12:15], v[236:239], v[178:181], v[12:15]
	v_mfma_f32_16x16x32_bf16 v[16:19], v[244:247], v[178:181], v[16:19]
	v_mfma_f32_16x16x32_bf16 v[104:107], v[236:239], v[186:189], v[104:107]
	v_mfma_f32_16x16x32_bf16 v[100:103], v[244:247], v[186:189], v[100:103]
	v_mfma_f32_16x16x32_bf16 v[96:99], v[236:239], v[202:205], v[96:99]
	v_mfma_f32_16x16x32_bf16 v[92:95], v[244:247], v[202:205], v[92:95]
	v_mfma_f32_16x16x32_bf16 v[88:91], v[236:239], v[210:213], v[88:91]
	v_mfma_f32_16x16x32_bf16 v[84:87], v[244:247], v[210:213], v[84:87]
	v_mfma_f32_16x16x32_bf16 v[12:15], v[240:243], v[182:185], v[12:15]
	v_mfma_f32_16x16x32_bf16 v[16:19], v[248:251], v[182:185], v[16:19]
	v_mfma_f32_16x16x32_bf16 v[104:107], v[240:243], v[190:193], v[104:107]
	v_mfma_f32_16x16x32_bf16 v[100:103], v[248:251], v[190:193], v[100:103]
	v_mfma_f32_16x16x32_bf16 v[96:99], v[240:243], v[206:209], v[96:99]
	v_mfma_f32_16x16x32_bf16 v[92:95], v[248:251], v[206:209], v[92:95]
	v_mfma_f32_16x16x32_bf16 v[88:91], v[240:243], v[214:217], v[88:91]
	v_mfma_f32_16x16x32_bf16 v[84:87], v[248:251], v[214:217], v[84:87]
	s_mov_b32 m0, s53
	s_barrier
	ds_read_b128 v[178:181], v172 offset:16384
	ds_read_b128 v[182:185], v172 offset:17408
	ds_read_b128 v[186:189], v172 offset:18432
	ds_read_b128 v[190:193], v172 offset:19456
	ds_read_b128 v[202:205], v172 offset:20480
	ds_read_b128 v[206:209], v172 offset:21504
	ds_read_b128 v[210:213], v172 offset:22528
	global_load_lds_dwordx4 v136, s[48:49]
	s_mov_b32 m0, s54
	ds_read_b128 v[214:217], v172 offset:23552
	global_load_lds_dwordx4 v140, s[48:49]
	s_barrier
	s_waitcnt lgkmcnt(0)
	v_mfma_f32_16x16x32_bf16 v[80:83], v[132:135], v[178:181], v[80:83]
	v_mfma_f32_16x16x32_bf16 v[76:79], v[168:171], v[178:181], v[76:79]
	v_mfma_f32_16x16x32_bf16 v[72:75], v[132:135], v[186:189], v[72:75]
	v_mfma_f32_16x16x32_bf16 v[68:71], v[168:171], v[186:189], v[68:71]
	v_mfma_f32_16x16x32_bf16 v[64:67], v[132:135], v[202:205], v[64:67]
	v_mfma_f32_16x16x32_bf16 v[60:63], v[168:171], v[202:205], v[60:63]
	v_mfma_f32_16x16x32_bf16 v[56:59], v[132:135], v[210:213], v[56:59]
	v_mfma_f32_16x16x32_bf16 v[52:55], v[168:171], v[210:213], v[52:55]
	v_mfma_f32_16x16x32_bf16 v[80:83], v[164:167], v[182:185], v[80:83]
	v_mfma_f32_16x16x32_bf16 v[76:79], v[174:177], v[182:185], v[76:79]
	v_mfma_f32_16x16x32_bf16 v[72:75], v[164:167], v[190:193], v[72:75]
	v_mfma_f32_16x16x32_bf16 v[68:71], v[174:177], v[190:193], v[68:71]
	v_mfma_f32_16x16x32_bf16 v[64:67], v[164:167], v[206:209], v[64:67]
	v_mfma_f32_16x16x32_bf16 v[60:63], v[174:177], v[206:209], v[60:63]
	v_mfma_f32_16x16x32_bf16 v[56:59], v[164:167], v[214:217], v[56:59]
	v_mfma_f32_16x16x32_bf16 v[52:55], v[174:177], v[214:217], v[52:55]
	s_barrier
	s_add_i32 m0, s52, 0x14000
	s_add_u32 s30, s46, 0xc0000
	s_addc_u32 s31, s47, 0
	global_load_lds_dwordx4 v138, s[30:31]
	s_add_i32 m0, s52, 0x16000
	s_waitcnt vmcnt(5)
	global_load_lds_dwordx4 v142, s[30:31]
	s_barrier
	v_mfma_f32_16x16x32_bf16 v[48:51], v[236:239], v[178:181], v[48:51]
	v_mfma_f32_16x16x32_bf16 v[44:47], v[244:247], v[178:181], v[44:47]
	v_mfma_f32_16x16x32_bf16 v[40:43], v[236:239], v[186:189], v[40:43]
	v_mfma_f32_16x16x32_bf16 v[36:39], v[244:247], v[186:189], v[36:39]
	v_mfma_f32_16x16x32_bf16 v[32:35], v[236:239], v[202:205], v[32:35]
	v_mfma_f32_16x16x32_bf16 v[28:31], v[244:247], v[202:205], v[28:31]
	v_mfma_f32_16x16x32_bf16 v[24:27], v[236:239], v[210:213], v[24:27]
	v_mfma_f32_16x16x32_bf16 v[20:23], v[244:247], v[210:213], v[20:23]
	v_mfma_f32_16x16x32_bf16 v[48:51], v[240:243], v[182:185], v[48:51]
	v_mfma_f32_16x16x32_bf16 v[44:47], v[248:251], v[182:185], v[44:47]
	v_mfma_f32_16x16x32_bf16 v[40:43], v[240:243], v[190:193], v[40:43]
	v_mfma_f32_16x16x32_bf16 v[36:39], v[248:251], v[190:193], v[36:39]
	v_mfma_f32_16x16x32_bf16 v[32:35], v[240:243], v[206:209], v[32:35]
	v_mfma_f32_16x16x32_bf16 v[28:31], v[248:251], v[206:209], v[28:31]
	v_mfma_f32_16x16x32_bf16 v[24:27], v[240:243], v[214:217], v[24:27]
	v_mfma_f32_16x16x32_bf16 v[20:23], v[248:251], v[214:217], v[20:23]
	s_barrier
	ds_read_b128 v[132:135], v1 offset:32768
	ds_read_b128 v[164:167], v1 offset:33792
	ds_read_b128 v[168:171], v1 offset:34816
	ds_read_b128 v[174:177], v1 offset:35840
	s_add_u32 s30, s48, 0x1a0000
	s_addc_u32 s31, s49, 0
	s_mov_b32 m0, s55
	ds_read_b128 v[178:181], v172 offset:32768
	ds_read_b128 v[182:185], v172 offset:33792
	ds_read_b128 v[186:189], v172 offset:34816
	ds_read_b128 v[190:193], v172 offset:35840
	ds_read_b128 v[202:205], v172 offset:36864
	ds_read_b128 v[206:209], v172 offset:37888
	ds_read_b128 v[210:213], v172 offset:38912
	global_load_lds_dwordx4 v136, s[30:31]
	s_mov_b32 m0, s56
	ds_read_b128 v[214:217], v172 offset:39936
	global_load_lds_dwordx4 v140, s[30:31]
	s_waitcnt lgkmcnt(8)
	s_barrier
	s_waitcnt lgkmcnt(0)
	v_mfma_f32_16x16x32_bf16 v[4:7], v[132:135], v[178:181], v[4:7]
	v_mfma_f32_16x16x32_bf16 v[8:11], v[168:171], v[178:181], v[8:11]
	v_mfma_f32_16x16x32_bf16 v[128:131], v[132:135], v[186:189], v[128:131]
	v_mfma_f32_16x16x32_bf16 v[124:127], v[168:171], v[186:189], v[124:127]
	v_mfma_f32_16x16x32_bf16 v[120:123], v[132:135], v[202:205], v[120:123]
	v_mfma_f32_16x16x32_bf16 v[116:119], v[168:171], v[202:205], v[116:119]
	v_mfma_f32_16x16x32_bf16 v[112:115], v[132:135], v[210:213], v[112:115]
	v_mfma_f32_16x16x32_bf16 v[108:111], v[168:171], v[210:213], v[108:111]
	v_mfma_f32_16x16x32_bf16 v[4:7], v[164:167], v[182:185], v[4:7]
	v_mfma_f32_16x16x32_bf16 v[8:11], v[174:177], v[182:185], v[8:11]
	v_mfma_f32_16x16x32_bf16 v[128:131], v[164:167], v[190:193], v[128:131]
	v_mfma_f32_16x16x32_bf16 v[124:127], v[174:177], v[190:193], v[124:127]
	v_mfma_f32_16x16x32_bf16 v[120:123], v[164:167], v[206:209], v[120:123]
	v_mfma_f32_16x16x32_bf16 v[116:119], v[174:177], v[206:209], v[116:119]
	v_mfma_f32_16x16x32_bf16 v[112:115], v[164:167], v[214:217], v[112:115]
	v_mfma_f32_16x16x32_bf16 v[108:111], v[174:177], v[214:217], v[108:111]
	s_barrier
	s_add_i32 m0, s52, 0x18000
	ds_read_b128 v[236:239], v1 offset:49152
	ds_read_b128 v[240:243], v1 offset:50176
	ds_read_b128 v[244:247], v1 offset:51200
	s_add_u32 s98, s46, 0x80
	s_addc_u32 s99, s47, 0
	global_load_lds_dwordx4 v138, s[98:99]
	s_add_i32 m0, s52, 0x1a000
	ds_read_b128 v[248:251], v1 offset:52224
	global_load_lds_dwordx4 v142, s[98:99]
	s_barrier
	s_waitcnt lgkmcnt(0)
	v_mfma_f32_16x16x32_bf16 v[12:15], v[236:239], v[178:181], v[12:15]
	v_mfma_f32_16x16x32_bf16 v[16:19], v[244:247], v[178:181], v[16:19]
	v_mfma_f32_16x16x32_bf16 v[104:107], v[236:239], v[186:189], v[104:107]
	v_mfma_f32_16x16x32_bf16 v[100:103], v[244:247], v[186:189], v[100:103]
	v_mfma_f32_16x16x32_bf16 v[96:99], v[236:239], v[202:205], v[96:99]
	v_mfma_f32_16x16x32_bf16 v[92:95], v[244:247], v[202:205], v[92:95]
	v_mfma_f32_16x16x32_bf16 v[88:91], v[236:239], v[210:213], v[88:91]
	v_mfma_f32_16x16x32_bf16 v[84:87], v[244:247], v[210:213], v[84:87]
	v_mfma_f32_16x16x32_bf16 v[12:15], v[240:243], v[182:185], v[12:15]
	v_mfma_f32_16x16x32_bf16 v[16:19], v[248:251], v[182:185], v[16:19]
	v_mfma_f32_16x16x32_bf16 v[104:107], v[240:243], v[190:193], v[104:107]
	v_mfma_f32_16x16x32_bf16 v[100:103], v[248:251], v[190:193], v[100:103]
	v_mfma_f32_16x16x32_bf16 v[96:99], v[240:243], v[206:209], v[96:99]
	v_mfma_f32_16x16x32_bf16 v[92:95], v[248:251], v[206:209], v[92:95]
	v_mfma_f32_16x16x32_bf16 v[88:91], v[240:243], v[214:217], v[88:91]
	v_mfma_f32_16x16x32_bf16 v[84:87], v[248:251], v[214:217], v[84:87]
	s_mov_b32 m0, s59
	s_barrier
	ds_read_b128 v[178:181], v172 offset:49152
	ds_read_b128 v[182:185], v172 offset:50176
	ds_read_b128 v[186:189], v172 offset:51200
	ds_read_b128 v[190:193], v172 offset:52224
	ds_read_b128 v[202:205], v172 offset:53248
	ds_read_b128 v[206:209], v172 offset:54272
	ds_read_b128 v[210:213], v172 offset:55296
	s_add_u32 s98, s48, 0x80
	s_addc_u32 s99, s49, 0
	global_load_lds_dwordx4 v136, s[98:99]
	s_mov_b32 m0, s60
	ds_read_b128 v[214:217], v172 offset:56320
	global_load_lds_dwordx4 v140, s[98:99]
	s_barrier
	s_waitcnt lgkmcnt(0)
	v_mfma_f32_16x16x32_bf16 v[80:83], v[132:135], v[178:181], v[80:83]
	v_mfma_f32_16x16x32_bf16 v[76:79], v[168:171], v[178:181], v[76:79]
	v_mfma_f32_16x16x32_bf16 v[72:75], v[132:135], v[186:189], v[72:75]
	v_mfma_f32_16x16x32_bf16 v[68:71], v[168:171], v[186:189], v[68:71]
	v_mfma_f32_16x16x32_bf16 v[64:67], v[132:135], v[202:205], v[64:67]
	v_mfma_f32_16x16x32_bf16 v[60:63], v[168:171], v[202:205], v[60:63]
	v_mfma_f32_16x16x32_bf16 v[56:59], v[132:135], v[210:213], v[56:59]
	v_mfma_f32_16x16x32_bf16 v[52:55], v[168:171], v[210:213], v[52:55]
	v_mfma_f32_16x16x32_bf16 v[80:83], v[164:167], v[182:185], v[80:83]
	v_mfma_f32_16x16x32_bf16 v[76:79], v[174:177], v[182:185], v[76:79]
	v_mfma_f32_16x16x32_bf16 v[72:75], v[164:167], v[190:193], v[72:75]
	v_mfma_f32_16x16x32_bf16 v[68:71], v[174:177], v[190:193], v[68:71]
	v_mfma_f32_16x16x32_bf16 v[64:67], v[164:167], v[206:209], v[64:67]
	v_mfma_f32_16x16x32_bf16 v[60:63], v[174:177], v[206:209], v[60:63]
	v_mfma_f32_16x16x32_bf16 v[56:59], v[164:167], v[214:217], v[56:59]
	v_mfma_f32_16x16x32_bf16 v[52:55], v[174:177], v[214:217], v[52:55]
	s_barrier
	s_add_i32 m0, s52, 0x1c000
	s_add_u32 s30, s46, 0xc0080
	s_addc_u32 s31, s47, 0
	global_load_lds_dwordx4 v138, s[30:31]
	s_add_i32 m0, s52, 0x1e000
	s_waitcnt vmcnt(5)
	global_load_lds_dwordx4 v142, s[30:31]
	s_barrier
	v_mfma_f32_16x16x32_bf16 v[48:51], v[236:239], v[178:181], v[48:51]
	v_mfma_f32_16x16x32_bf16 v[44:47], v[244:247], v[178:181], v[44:47]
	v_mfma_f32_16x16x32_bf16 v[40:43], v[236:239], v[186:189], v[40:43]
	v_mfma_f32_16x16x32_bf16 v[36:39], v[244:247], v[186:189], v[36:39]
	v_mfma_f32_16x16x32_bf16 v[32:35], v[236:239], v[202:205], v[32:35]
	v_mfma_f32_16x16x32_bf16 v[28:31], v[244:247], v[202:205], v[28:31]
	v_mfma_f32_16x16x32_bf16 v[24:27], v[236:239], v[210:213], v[24:27]
	v_mfma_f32_16x16x32_bf16 v[20:23], v[244:247], v[210:213], v[20:23]
	v_mfma_f32_16x16x32_bf16 v[48:51], v[240:243], v[182:185], v[48:51]
	v_mfma_f32_16x16x32_bf16 v[44:47], v[248:251], v[182:185], v[44:47]
	v_mfma_f32_16x16x32_bf16 v[40:43], v[240:243], v[190:193], v[40:43]
	v_mfma_f32_16x16x32_bf16 v[36:39], v[248:251], v[190:193], v[36:39]
	v_mfma_f32_16x16x32_bf16 v[32:35], v[240:243], v[206:209], v[32:35]
	v_mfma_f32_16x16x32_bf16 v[28:31], v[248:251], v[206:209], v[28:31]
	v_mfma_f32_16x16x32_bf16 v[24:27], v[240:243], v[214:217], v[24:27]
	v_mfma_f32_16x16x32_bf16 v[20:23], v[248:251], v[214:217], v[20:23]
	s_add_u32 s24, s24, 0x100
	s_addc_u32 s25, s25, 0
	s_cmp_ge_i32 s26, s22
	s_mov_b64 s[40:41], s[44:45]
	s_mov_b32 s27, s26
	s_barrier
	s_cbranch_scc0 .LBB0_175
	s_lshl_b32 s46, s66, 8
	v_lshl_or_b32 v0, s20, 8, v159
	s_mov_b32 s44, 0xbfb8aa3b
	s_mov_b32 s45, 0xbfb8aa3b
	v_lshlrev_b32_e32 v0, 1, v0
	v_add_u32_e32 v0, 0x1000, v0
	s_cmp_lg_u32 s21, 1
	s_cbranch_scc0 .Lg2_kind1
	v_readlane_b32 s22, v252, 34
	v_readlane_b32 s23, v252, 35
	v_add_u32_e32 v2, s46, v144
	v_mad_u32_u24 v2, v2, s29, v0
	global_load_dwordx4 v[132:135], v2, s[96:97] offset:2048
	v_add_u32_e32 v2, s46, v144
	v_mad_u32_u24 v2, v2, s29, v0
	global_load_dwordx4 v[178:181], v2, s[96:97] offset:2304
	v_add_u32_e32 v2, s46, v146
	v_mad_u32_u24 v2, v2, s29, v0
	global_load_dwordx4 v[182:185], v2, s[96:97] offset:2048
	v_add_u32_e32 v2, s46, v146
	v_mad_u32_u24 v2, v2, s29, v0
	global_load_dwordx4 v[186:189], v2, s[96:97] offset:2304
	v_add_u32_e32 v2, s46, v148
	v_mad_u32_u24 v2, v2, s29, v0
	global_load_dwordx4 v[190:193], v2, s[96:97] offset:2048
	v_add_u32_e32 v2, s46, v148
	v_mad_u32_u24 v2, v2, s29, v0
	global_load_dwordx4 v[202:205], v2, s[96:97] offset:2304
	v_add_u32_e32 v2, s46, v150
	v_mad_u32_u24 v2, v2, s29, v0
	global_load_dwordx4 v[206:209], v2, s[96:97] offset:2048
	v_add_u32_e32 v2, s46, v150
	v_mad_u32_u24 v2, v2, s29, v0
	global_load_dwordx4 v[210:213], v2, s[96:97] offset:2304
	v_add_u32_e32 v2, s46, v152
	v_mad_u32_u24 v2, v2, s29, v0
	global_load_dwordx4 v[214:217], v2, s[96:97] offset:2048
	v_add_u32_e32 v2, s46, v152
	v_mad_u32_u24 v2, v2, s29, v0
	global_load_dwordx4 v[236:239], v2, s[96:97] offset:2304
	v_add_u32_e32 v2, s46, v154
	v_mad_u32_u24 v2, v2, s29, v0
	global_load_dwordx4 v[240:243], v2, s[96:97] offset:2048
	v_add_u32_e32 v2, s46, v154
	v_mad_u32_u24 v2, v2, s29, v0
	global_load_dwordx4 v[244:247], v2, s[96:97] offset:2304
	v_add_u32_e32 v2, s46, v156
	v_mad_u32_u24 v2, v2, s29, v0
	global_load_dwordx4 v[248:251], v2, s[96:97] offset:2048
	s_waitcnt vmcnt(12)
	v_lshlrev_b32_e32 v164, 16, v132
	v_and_b32_e32 v165, 0xffff0000, v132
	v_lshlrev_b32_e32 v166, 16, v133
	v_and_b32_e32 v167, 0xffff0000, v133
	v_lshlrev_b32_e32 v168, 16, v134
	v_and_b32_e32 v169, 0xffff0000, v134
	v_lshlrev_b32_e32 v170, 16, v135
	v_and_b32_e32 v171, 0xffff0000, v135
	v_add_u32_e32 v2, s46, v156
	v_mad_u32_u24 v2, v2, s29, v0
	global_load_dwordx4 v[132:135], v2, s[96:97] offset:2304
	v_add_u32_e32 v1, s46, v144
	v_lshl_add_u32 v1, v1, 11, v0
	v_med3_f32 v164, v164, s34, v227
	v_med3_f32 v165, v165, s34, v227
	v_med3_f32 v166, v166, s34, v227
	v_med3_f32 v167, v167, s34, v227
	v_med3_f32 v168, v168, s34, v227
	v_med3_f32 v169, v169, s34, v227
	v_med3_f32 v170, v170, s34, v227
	v_med3_f32 v171, v171, s34, v227
	v_pk_mul_f32 v[164:165], v[164:165], s[44:45]
	v_pk_mul_f32 v[166:167], v[166:167], s[44:45]
	v_pk_mul_f32 v[168:169], v[168:169], s[44:45]
	v_pk_mul_f32 v[170:171], v[170:171], s[44:45]
	v_exp_f32_e32 v164, v164
	v_exp_f32_e32 v165, v165
	v_exp_f32_e32 v166, v166
	v_exp_f32_e32 v167, v167
	v_exp_f32_e32 v168, v168
	v_exp_f32_e32 v169, v169
	v_exp_f32_e32 v170, v170
	v_exp_f32_e32 v171, v171
	v_pk_add_f32 v[164:165], v[164:165], 1.0 op_sel_hi:[1,0]
	v_pk_add_f32 v[166:167], v[166:167], 1.0 op_sel_hi:[1,0]
	v_pk_add_f32 v[168:169], v[168:169], 1.0 op_sel_hi:[1,0]
	v_pk_add_f32 v[170:171], v[170:171], 1.0 op_sel_hi:[1,0]
	v_rcp_f32_e32 v164, v164
	v_rcp_f32_e32 v165, v165
	v_rcp_f32_e32 v166, v166
	v_rcp_f32_e32 v167, v167
	v_rcp_f32_e32 v168, v168
	v_rcp_f32_e32 v169, v169
	v_rcp_f32_e32 v170, v170
	v_rcp_f32_e32 v171, v171
	v_pk_mul_f32 v[164:165], v[4:5], v[164:165]
	v_pk_mul_f32 v[166:167], v[6:7], v[166:167]
	v_pk_mul_f32 v[168:169], v[8:9], v[168:169]
	v_pk_mul_f32 v[170:171], v[10:11], v[170:171]
	v_cvt_pk_bf16_f32 v174, v164, v165
	v_cvt_pk_bf16_f32 v175, v166, v167
	v_cvt_pk_bf16_f32 v176, v168, v169
	v_cvt_pk_bf16_f32 v177, v170, v171
	global_store_dwordx4 v1, v[174:177], s[22:23] offset:-4096
	s_waitcnt vmcnt(13)
	v_lshlrev_b32_e32 v164, 16, v178
	v_and_b32_e32 v165, 0xffff0000, v178
	v_lshlrev_b32_e32 v166, 16, v179
	v_and_b32_e32 v167, 0xffff0000, v179
	v_lshlrev_b32_e32 v168, 16, v180
	v_and_b32_e32 v169, 0xffff0000, v180
	v_lshlrev_b32_e32 v170, 16, v181
	v_and_b32_e32 v171, 0xffff0000, v181
	v_add_u32_e32 v2, s46, v158
	v_mad_u32_u24 v2, v2, s29, v0
	global_load_dwordx4 v[178:181], v2, s[96:97] offset:2048
	v_med3_f32 v164, v164, s34, v227
	v_med3_f32 v165, v165, s34, v227
	v_med3_f32 v166, v166, s34, v227
	v_med3_f32 v167, v167, s34, v227
	v_med3_f32 v168, v168, s34, v227
	v_med3_f32 v169, v169, s34, v227
	v_med3_f32 v170, v170, s34, v227
	v_med3_f32 v171, v171, s34, v227
	v_pk_mul_f32 v[164:165], v[164:165], s[44:45]
	v_pk_mul_f32 v[166:167], v[166:167], s[44:45]
	v_pk_mul_f32 v[168:169], v[168:169], s[44:45]
	v_pk_mul_f32 v[170:171], v[170:171], s[44:45]
	v_exp_f32_e32 v164, v164
	v_exp_f32_e32 v165, v165
	v_exp_f32_e32 v166, v166
	v_exp_f32_e32 v167, v167
	v_exp_f32_e32 v168, v168
	v_exp_f32_e32 v169, v169
	v_exp_f32_e32 v170, v170
	v_exp_f32_e32 v171, v171
	v_pk_add_f32 v[164:165], v[164:165], 1.0 op_sel_hi:[1,0]
	v_pk_add_f32 v[166:167], v[166:167], 1.0 op_sel_hi:[1,0]
	v_pk_add_f32 v[168:169], v[168:169], 1.0 op_sel_hi:[1,0]
	v_pk_add_f32 v[170:171], v[170:171], 1.0 op_sel_hi:[1,0]
	v_rcp_f32_e32 v164, v164
	v_rcp_f32_e32 v165, v165
	v_rcp_f32_e32 v166, v166
	v_rcp_f32_e32 v167, v167
	v_rcp_f32_e32 v168, v168
	v_rcp_f32_e32 v169, v169
	v_rcp_f32_e32 v170, v170
	v_rcp_f32_e32 v171, v171
	v_pk_mul_f32 v[164:165], v[12:13], v[164:165]
	v_pk_mul_f32 v[166:167], v[14:15], v[166:167]
	v_pk_mul_f32 v[168:169], v[16:17], v[168:169]
	v_pk_mul_f32 v[170:171], v[18:19], v[170:171]
	v_cvt_pk_bf16_f32 v174, v164, v165
	v_cvt_pk_bf16_f32 v175, v166, v167
	v_cvt_pk_bf16_f32 v176, v168, v169
	v_cvt_pk_bf16_f32 v177, v170, v171
	global_store_dwordx4 v1, v[174:177], s[22:23] offset:-3840
	s_waitcnt vmcnt(14)
	v_lshlrev_b32_e32 v164, 16, v182
	v_and_b32_e32 v165, 0xffff0000, v182
	v_lshlrev_b32_e32 v166, 16, v183
	v_and_b32_e32 v167, 0xffff0000, v183
	v_lshlrev_b32_e32 v168, 16, v184
	v_and_b32_e32 v169, 0xffff0000, v184
	v_lshlrev_b32_e32 v170, 16, v185
	v_and_b32_e32 v171, 0xffff0000, v185
	v_add_u32_e32 v2, s46, v158
	v_mad_u32_u24 v2, v2, s29, v0
	global_load_dwordx4 v[182:185], v2, s[96:97] offset:2304
	v_add_u32_e32 v1, s46, v146
	v_lshl_add_u32 v1, v1, 11, v0
	v_med3_f32 v164, v164, s34, v227
	v_med3_f32 v165, v165, s34, v227
	v_med3_f32 v166, v166, s34, v227
	v_med3_f32 v167, v167, s34, v227
	v_med3_f32 v168, v168, s34, v227
	v_med3_f32 v169, v169, s34, v227
	v_med3_f32 v170, v170, s34, v227
	v_med3_f32 v171, v171, s34, v227
	v_pk_mul_f32 v[164:165], v[164:165], s[44:45]
	v_pk_mul_f32 v[166:167], v[166:167], s[44:45]
	v_pk_mul_f32 v[168:169], v[168:169], s[44:45]
	v_pk_mul_f32 v[170:171], v[170:171], s[44:45]
	v_exp_f32_e32 v164, v164
	v_exp_f32_e32 v165, v165
	v_exp_f32_e32 v166, v166
	v_exp_f32_e32 v167, v167
	v_exp_f32_e32 v168, v168
	v_exp_f32_e32 v169, v169
	v_exp_f32_e32 v170, v170
	v_exp_f32_e32 v171, v171
	v_pk_add_f32 v[164:165], v[164:165], 1.0 op_sel_hi:[1,0]
	v_pk_add_f32 v[166:167], v[166:167], 1.0 op_sel_hi:[1,0]
	v_pk_add_f32 v[168:169], v[168:169], 1.0 op_sel_hi:[1,0]
	v_pk_add_f32 v[170:171], v[170:171], 1.0 op_sel_hi:[1,0]
	v_rcp_f32_e32 v164, v164
	v_rcp_f32_e32 v165, v165
	v_rcp_f32_e32 v166, v166
	v_rcp_f32_e32 v167, v167
	v_rcp_f32_e32 v168, v168
	v_rcp_f32_e32 v169, v169
	v_rcp_f32_e32 v170, v170
	v_rcp_f32_e32 v171, v171
	v_pk_mul_f32 v[164:165], v[128:129], v[164:165]
	v_pk_mul_f32 v[166:167], v[130:131], v[166:167]
	v_pk_mul_f32 v[168:169], v[124:125], v[168:169]
	v_pk_mul_f32 v[170:171], v[126:127], v[170:171]
	v_cvt_pk_bf16_f32 v174, v164, v165
	v_cvt_pk_bf16_f32 v175, v166, v167
	v_cvt_pk_bf16_f32 v176, v168, v169
	v_cvt_pk_bf16_f32 v177, v170, v171
	global_store_dwordx4 v1, v[174:177], s[22:23] offset:-4096
	s_waitcnt vmcnt(15)
	v_lshlrev_b32_e32 v164, 16, v186
	v_and_b32_e32 v165, 0xffff0000, v186
	v_lshlrev_b32_e32 v166, 16, v187
	v_and_b32_e32 v167, 0xffff0000, v187
	v_lshlrev_b32_e32 v168, 16, v188
	v_and_b32_e32 v169, 0xffff0000, v188
	v_lshlrev_b32_e32 v170, 16, v189
	v_and_b32_e32 v171, 0xffff0000, v189
	v_med3_f32 v164, v164, s34, v227
	v_med3_f32 v165, v165, s34, v227
	v_med3_f32 v166, v166, s34, v227
	v_med3_f32 v167, v167, s34, v227
	v_med3_f32 v168, v168, s34, v227
	v_med3_f32 v169, v169, s34, v227
	v_med3_f32 v170, v170, s34, v227
	v_med3_f32 v171, v171, s34, v227
	v_pk_mul_f32 v[164:165], v[164:165], s[44:45]
	v_pk_mul_f32 v[166:167], v[166:167], s[44:45]
	v_pk_mul_f32 v[168:169], v[168:169], s[44:45]
	v_pk_mul_f32 v[170:171], v[170:171], s[44:45]
	v_exp_f32_e32 v164, v164
	v_exp_f32_e32 v165, v165
	v_exp_f32_e32 v166, v166
	v_exp_f32_e32 v167, v167
	v_exp_f32_e32 v168, v168
	v_exp_f32_e32 v169, v169
	v_exp_f32_e32 v170, v170
	v_exp_f32_e32 v171, v171
	v_pk_add_f32 v[164:165], v[164:165], 1.0 op_sel_hi:[1,0]
	v_pk_add_f32 v[166:167], v[166:167], 1.0 op_sel_hi:[1,0]
	v_pk_add_f32 v[168:169], v[168:169], 1.0 op_sel_hi:[1,0]
	v_pk_add_f32 v[170:171], v[170:171], 1.0 op_sel_hi:[1,0]
	v_rcp_f32_e32 v164, v164
	v_rcp_f32_e32 v165, v165
	v_rcp_f32_e32 v166, v166
	v_rcp_f32_e32 v167, v167
	v_rcp_f32_e32 v168, v168
	v_rcp_f32_e32 v169, v169
	v_rcp_f32_e32 v170, v170
	v_rcp_f32_e32 v171, v171
	v_pk_mul_f32 v[164:165], v[104:105], v[164:165]
	v_pk_mul_f32 v[166:167], v[106:107], v[166:167]
	v_pk_mul_f32 v[168:169], v[100:101], v[168:169]
	v_pk_mul_f32 v[170:171], v[102:103], v[170:171]
	v_cvt_pk_bf16_f32 v174, v164, v165
	v_cvt_pk_bf16_f32 v175, v166, v167
	v_cvt_pk_bf16_f32 v176, v168, v169
	v_cvt_pk_bf16_f32 v177, v170, v171
	global_store_dwordx4 v1, v[174:177], s[22:23] offset:-3840
	s_waitcnt vmcnt(15)
	v_lshlrev_b32_e32 v164, 16, v190
	v_and_b32_e32 v165, 0xffff0000, v190
	v_lshlrev_b32_e32 v166, 16, v191
	v_and_b32_e32 v167, 0xffff0000, v191
	v_lshlrev_b32_e32 v168, 16, v192
	v_and_b32_e32 v169, 0xffff0000, v192
	v_lshlrev_b32_e32 v170, 16, v193
	v_and_b32_e32 v171, 0xffff0000, v193
	v_add_u32_e32 v1, s46, v148
	v_lshl_add_u32 v1, v1, 11, v0
	v_med3_f32 v164, v164, s34, v227
	v_med3_f32 v165, v165, s34, v227
	v_med3_f32 v166, v166, s34, v227
	v_med3_f32 v167, v167, s34, v227
	v_med3_f32 v168, v168, s34, v227
	v_med3_f32 v169, v169, s34, v227
	v_med3_f32 v170, v170, s34, v227
	v_med3_f32 v171, v171, s34, v227
	v_pk_mul_f32 v[164:165], v[164:165], s[44:45]
	v_pk_mul_f32 v[166:167], v[166:167], s[44:45]
	v_pk_mul_f32 v[168:169], v[168:169], s[44:45]
	v_pk_mul_f32 v[170:171], v[170:171], s[44:45]
	v_exp_f32_e32 v164, v164
	v_exp_f32_e32 v165, v165
	v_exp_f32_e32 v166, v166
	v_exp_f32_e32 v167, v167
	v_exp_f32_e32 v168, v168
	v_exp_f32_e32 v169, v169
	v_exp_f32_e32 v170, v170
	v_exp_f32_e32 v171, v171
	v_pk_add_f32 v[164:165], v[164:165], 1.0 op_sel_hi:[1,0]
	v_pk_add_f32 v[166:167], v[166:167], 1.0 op_sel_hi:[1,0]
	v_pk_add_f32 v[168:169], v[168:169], 1.0 op_sel_hi:[1,0]
	v_pk_add_f32 v[170:171], v[170:171], 1.0 op_sel_hi:[1,0]
	v_rcp_f32_e32 v164, v164
	v_rcp_f32_e32 v165, v165
	v_rcp_f32_e32 v166, v166
	v_rcp_f32_e32 v167, v167
	v_rcp_f32_e32 v168, v168
	v_rcp_f32_e32 v169, v169
	v_rcp_f32_e32 v170, v170
	v_rcp_f32_e32 v171, v171
	v_pk_mul_f32 v[164:165], v[120:121], v[164:165]
	v_pk_mul_f32 v[166:167], v[122:123], v[166:167]
	v_pk_mul_f32 v[168:169], v[116:117], v[168:169]
	v_pk_mul_f32 v[170:171], v[118:119], v[170:171]
	v_cvt_pk_bf16_f32 v174, v164, v165
	v_cvt_pk_bf16_f32 v175, v166, v167
	v_cvt_pk_bf16_f32 v176, v168, v169
	v_cvt_pk_bf16_f32 v177, v170, v171
	global_store_dwordx4 v1, v[174:177], s[22:23] offset:-4096
	s_waitcnt vmcnt(15)
	v_lshlrev_b32_e32 v164, 16, v202
	v_and_b32_e32 v165, 0xffff0000, v202
	v_lshlrev_b32_e32 v166, 16, v203
	v_and_b32_e32 v167, 0xffff0000, v203
	v_lshlrev_b32_e32 v168, 16, v204
	v_and_b32_e32 v169, 0xffff0000, v204
	v_lshlrev_b32_e32 v170, 16, v205
	v_and_b32_e32 v171, 0xffff0000, v205
	v_med3_f32 v164, v164, s34, v227
	v_med3_f32 v165, v165, s34, v227
	v_med3_f32 v166, v166, s34, v227
	v_med3_f32 v167, v167, s34, v227
	v_med3_f32 v168, v168, s34, v227
	v_med3_f32 v169, v169, s34, v227
	v_med3_f32 v170, v170, s34, v227
	v_med3_f32 v171, v171, s34, v227
	v_pk_mul_f32 v[164:165], v[164:165], s[44:45]
	v_pk_mul_f32 v[166:167], v[166:167], s[44:45]
	v_pk_mul_f32 v[168:169], v[168:169], s[44:45]
	v_pk_mul_f32 v[170:171], v[170:171], s[44:45]
	v_exp_f32_e32 v164, v164
	v_exp_f32_e32 v165, v165
	v_exp_f32_e32 v166, v166
	v_exp_f32_e32 v167, v167
	v_exp_f32_e32 v168, v168
	v_exp_f32_e32 v169, v169
	v_exp_f32_e32 v170, v170
	v_exp_f32_e32 v171, v171
	v_pk_add_f32 v[164:165], v[164:165], 1.0 op_sel_hi:[1,0]
	v_pk_add_f32 v[166:167], v[166:167], 1.0 op_sel_hi:[1,0]
	v_pk_add_f32 v[168:169], v[168:169], 1.0 op_sel_hi:[1,0]
	v_pk_add_f32 v[170:171], v[170:171], 1.0 op_sel_hi:[1,0]
	v_rcp_f32_e32 v164, v164
	v_rcp_f32_e32 v165, v165
	v_rcp_f32_e32 v166, v166
	v_rcp_f32_e32 v167, v167
	v_rcp_f32_e32 v168, v168
	v_rcp_f32_e32 v169, v169
	v_rcp_f32_e32 v170, v170
	v_rcp_f32_e32 v171, v171
	v_pk_mul_f32 v[164:165], v[96:97], v[164:165]
	v_pk_mul_f32 v[166:167], v[98:99], v[166:167]
	v_pk_mul_f32 v[168:169], v[92:93], v[168:169]
	v_pk_mul_f32 v[170:171], v[94:95], v[170:171]
	v_cvt_pk_bf16_f32 v174, v164, v165
	v_cvt_pk_bf16_f32 v175, v166, v167
	v_cvt_pk_bf16_f32 v176, v168, v169
	v_cvt_pk_bf16_f32 v177, v170, v171
	global_store_dwordx4 v1, v[174:177], s[22:23] offset:-3840
	s_waitcnt vmcnt(15)
	v_lshlrev_b32_e32 v164, 16, v206
	v_and_b32_e32 v165, 0xffff0000, v206
	v_lshlrev_b32_e32 v166, 16, v207
	v_and_b32_e32 v167, 0xffff0000, v207
	v_lshlrev_b32_e32 v168, 16, v208
	v_and_b32_e32 v169, 0xffff0000, v208
	v_lshlrev_b32_e32 v170, 16, v209
	v_and_b32_e32 v171, 0xffff0000, v209
	v_add_u32_e32 v1, s46, v150
	v_lshl_add_u32 v1, v1, 11, v0
	v_med3_f32 v164, v164, s34, v227
	v_med3_f32 v165, v165, s34, v227
	v_med3_f32 v166, v166, s34, v227
	v_med3_f32 v167, v167, s34, v227
	v_med3_f32 v168, v168, s34, v227
	v_med3_f32 v169, v169, s34, v227
	v_med3_f32 v170, v170, s34, v227
	v_med3_f32 v171, v171, s34, v227
	v_pk_mul_f32 v[164:165], v[164:165], s[44:45]
	v_pk_mul_f32 v[166:167], v[166:167], s[44:45]
	v_pk_mul_f32 v[168:169], v[168:169], s[44:45]
	v_pk_mul_f32 v[170:171], v[170:171], s[44:45]
	v_exp_f32_e32 v164, v164
	v_exp_f32_e32 v165, v165
	v_exp_f32_e32 v166, v166
	v_exp_f32_e32 v167, v167
	v_exp_f32_e32 v168, v168
	v_exp_f32_e32 v169, v169
	v_exp_f32_e32 v170, v170
	v_exp_f32_e32 v171, v171
	v_pk_add_f32 v[164:165], v[164:165], 1.0 op_sel_hi:[1,0]
	v_pk_add_f32 v[166:167], v[166:167], 1.0 op_sel_hi:[1,0]
	v_pk_add_f32 v[168:169], v[168:169], 1.0 op_sel_hi:[1,0]
	v_pk_add_f32 v[170:171], v[170:171], 1.0 op_sel_hi:[1,0]
	v_rcp_f32_e32 v164, v164
	v_rcp_f32_e32 v165, v165
	v_rcp_f32_e32 v166, v166
	v_rcp_f32_e32 v167, v167
	v_rcp_f32_e32 v168, v168
	v_rcp_f32_e32 v169, v169
	v_rcp_f32_e32 v170, v170
	v_rcp_f32_e32 v171, v171
	v_pk_mul_f32 v[164:165], v[112:113], v[164:165]
	v_pk_mul_f32 v[166:167], v[114:115], v[166:167]
	v_pk_mul_f32 v[168:169], v[108:109], v[168:169]
	v_pk_mul_f32 v[170:171], v[110:111], v[170:171]
	v_cvt_pk_bf16_f32 v174, v164, v165
	v_cvt_pk_bf16_f32 v175, v166, v167
	v_cvt_pk_bf16_f32 v176, v168, v169
	v_cvt_pk_bf16_f32 v177, v170, v171
	global_store_dwordx4 v1, v[174:177], s[22:23] offset:-4096
	s_waitcnt vmcnt(15)
	v_lshlrev_b32_e32 v164, 16, v210
	v_and_b32_e32 v165, 0xffff0000, v210
	v_lshlrev_b32_e32 v166, 16, v211
	v_and_b32_e32 v167, 0xffff0000, v211
	v_lshlrev_b32_e32 v168, 16, v212
	v_and_b32_e32 v169, 0xffff0000, v212
	v_lshlrev_b32_e32 v170, 16, v213
	v_and_b32_e32 v171, 0xffff0000, v213
	v_med3_f32 v164, v164, s34, v227
	v_med3_f32 v165, v165, s34, v227
	v_med3_f32 v166, v166, s34, v227
	v_med3_f32 v167, v167, s34, v227
	v_med3_f32 v168, v168, s34, v227
	v_med3_f32 v169, v169, s34, v227
	v_med3_f32 v170, v170, s34, v227
	v_med3_f32 v171, v171, s34, v227
	v_pk_mul_f32 v[164:165], v[164:165], s[44:45]
	v_pk_mul_f32 v[166:167], v[166:167], s[44:45]
	v_pk_mul_f32 v[168:169], v[168:169], s[44:45]
	v_pk_mul_f32 v[170:171], v[170:171], s[44:45]
	v_exp_f32_e32 v164, v164
	v_exp_f32_e32 v165, v165
	v_exp_f32_e32 v166, v166
	v_exp_f32_e32 v167, v167
	v_exp_f32_e32 v168, v168
	v_exp_f32_e32 v169, v169
	v_exp_f32_e32 v170, v170
	v_exp_f32_e32 v171, v171
	v_pk_add_f32 v[164:165], v[164:165], 1.0 op_sel_hi:[1,0]
	v_pk_add_f32 v[166:167], v[166:167], 1.0 op_sel_hi:[1,0]
	v_pk_add_f32 v[168:169], v[168:169], 1.0 op_sel_hi:[1,0]
	v_pk_add_f32 v[170:171], v[170:171], 1.0 op_sel_hi:[1,0]
	v_rcp_f32_e32 v164, v164
	v_rcp_f32_e32 v165, v165
	v_rcp_f32_e32 v166, v166
	v_rcp_f32_e32 v167, v167
	v_rcp_f32_e32 v168, v168
	v_rcp_f32_e32 v169, v169
	v_rcp_f32_e32 v170, v170
	v_rcp_f32_e32 v171, v171
	v_pk_mul_f32 v[164:165], v[88:89], v[164:165]
	v_pk_mul_f32 v[166:167], v[90:91], v[166:167]
	v_pk_mul_f32 v[168:169], v[84:85], v[168:169]
	v_pk_mul_f32 v[170:171], v[86:87], v[170:171]
	v_cvt_pk_bf16_f32 v174, v164, v165
	v_cvt_pk_bf16_f32 v175, v166, v167
	v_cvt_pk_bf16_f32 v176, v168, v169
	v_cvt_pk_bf16_f32 v177, v170, v171
	global_store_dwordx4 v1, v[174:177], s[22:23] offset:-3840
	s_waitcnt vmcnt(15)
	v_lshlrev_b32_e32 v164, 16, v214
	v_and_b32_e32 v165, 0xffff0000, v214
	v_lshlrev_b32_e32 v166, 16, v215
	v_and_b32_e32 v167, 0xffff0000, v215
	v_lshlrev_b32_e32 v168, 16, v216
	v_and_b32_e32 v169, 0xffff0000, v216
	v_lshlrev_b32_e32 v170, 16, v217
	v_and_b32_e32 v171, 0xffff0000, v217
	v_add_u32_e32 v1, s46, v152
	v_lshl_add_u32 v1, v1, 11, v0
	v_med3_f32 v164, v164, s34, v227
	v_med3_f32 v165, v165, s34, v227
	v_med3_f32 v166, v166, s34, v227
	v_med3_f32 v167, v167, s34, v227
	v_med3_f32 v168, v168, s34, v227
	v_med3_f32 v169, v169, s34, v227
	v_med3_f32 v170, v170, s34, v227
	v_med3_f32 v171, v171, s34, v227
	v_pk_mul_f32 v[164:165], v[164:165], s[44:45]
	v_pk_mul_f32 v[166:167], v[166:167], s[44:45]
	v_pk_mul_f32 v[168:169], v[168:169], s[44:45]
	v_pk_mul_f32 v[170:171], v[170:171], s[44:45]
	v_exp_f32_e32 v164, v164
	v_exp_f32_e32 v165, v165
	v_exp_f32_e32 v166, v166
	v_exp_f32_e32 v167, v167
	v_exp_f32_e32 v168, v168
	v_exp_f32_e32 v169, v169
	v_exp_f32_e32 v170, v170
	v_exp_f32_e32 v171, v171
	v_pk_add_f32 v[164:165], v[164:165], 1.0 op_sel_hi:[1,0]
	v_pk_add_f32 v[166:167], v[166:167], 1.0 op_sel_hi:[1,0]
	v_pk_add_f32 v[168:169], v[168:169], 1.0 op_sel_hi:[1,0]
	v_pk_add_f32 v[170:171], v[170:171], 1.0 op_sel_hi:[1,0]
	v_rcp_f32_e32 v164, v164
	v_rcp_f32_e32 v165, v165
	v_rcp_f32_e32 v166, v166
	v_rcp_f32_e32 v167, v167
	v_rcp_f32_e32 v168, v168
	v_rcp_f32_e32 v169, v169
	v_rcp_f32_e32 v170, v170
	v_rcp_f32_e32 v171, v171
	v_pk_mul_f32 v[164:165], v[80:81], v[164:165]
	v_pk_mul_f32 v[166:167], v[82:83], v[166:167]
	v_pk_mul_f32 v[168:169], v[76:77], v[168:169]
	v_pk_mul_f32 v[170:171], v[78:79], v[170:171]
	v_cvt_pk_bf16_f32 v174, v164, v165
	v_cvt_pk_bf16_f32 v175, v166, v167
	v_cvt_pk_bf16_f32 v176, v168, v169
	v_cvt_pk_bf16_f32 v177, v170, v171
	global_store_dwordx4 v1, v[174:177], s[22:23] offset:-4096
	s_waitcnt vmcnt(15)
	v_lshlrev_b32_e32 v164, 16, v236
	v_and_b32_e32 v165, 0xffff0000, v236
	v_lshlrev_b32_e32 v166, 16, v237
	v_and_b32_e32 v167, 0xffff0000, v237
	v_lshlrev_b32_e32 v168, 16, v238
	v_and_b32_e32 v169, 0xffff0000, v238
	v_lshlrev_b32_e32 v170, 16, v239
	v_and_b32_e32 v171, 0xffff0000, v239
	v_med3_f32 v164, v164, s34, v227
	v_med3_f32 v165, v165, s34, v227
	v_med3_f32 v166, v166, s34, v227
	v_med3_f32 v167, v167, s34, v227
	v_med3_f32 v168, v168, s34, v227
	v_med3_f32 v169, v169, s34, v227
	v_med3_f32 v170, v170, s34, v227
	v_med3_f32 v171, v171, s34, v227
	v_pk_mul_f32 v[164:165], v[164:165], s[44:45]
	v_pk_mul_f32 v[166:167], v[166:167], s[44:45]
	v_pk_mul_f32 v[168:169], v[168:169], s[44:45]
	v_pk_mul_f32 v[170:171], v[170:171], s[44:45]
	v_exp_f32_e32 v164, v164
	v_exp_f32_e32 v165, v165
	v_exp_f32_e32 v166, v166
	v_exp_f32_e32 v167, v167
	v_exp_f32_e32 v168, v168
	v_exp_f32_e32 v169, v169
	v_exp_f32_e32 v170, v170
	v_exp_f32_e32 v171, v171
	v_pk_add_f32 v[164:165], v[164:165], 1.0 op_sel_hi:[1,0]
	v_pk_add_f32 v[166:167], v[166:167], 1.0 op_sel_hi:[1,0]
	v_pk_add_f32 v[168:169], v[168:169], 1.0 op_sel_hi:[1,0]
	v_pk_add_f32 v[170:171], v[170:171], 1.0 op_sel_hi:[1,0]
	v_rcp_f32_e32 v164, v164
	v_rcp_f32_e32 v165, v165
	v_rcp_f32_e32 v166, v166
	v_rcp_f32_e32 v167, v167
	v_rcp_f32_e32 v168, v168
	v_rcp_f32_e32 v169, v169
	v_rcp_f32_e32 v170, v170
	v_rcp_f32_e32 v171, v171
	v_pk_mul_f32 v[164:165], v[48:49], v[164:165]
	v_pk_mul_f32 v[166:167], v[50:51], v[166:167]
	v_pk_mul_f32 v[168:169], v[44:45], v[168:169]
	v_pk_mul_f32 v[170:171], v[46:47], v[170:171]
	v_cvt_pk_bf16_f32 v174, v164, v165
	v_cvt_pk_bf16_f32 v175, v166, v167
	v_cvt_pk_bf16_f32 v176, v168, v169
	v_cvt_pk_bf16_f32 v177, v170, v171
	global_store_dwordx4 v1, v[174:177], s[22:23] offset:-3840
	s_waitcnt vmcnt(15)
	v_lshlrev_b32_e32 v164, 16, v240
	v_and_b32_e32 v165, 0xffff0000, v240
	v_lshlrev_b32_e32 v166, 16, v241
	v_and_b32_e32 v167, 0xffff0000, v241
	v_lshlrev_b32_e32 v168, 16, v242
	v_and_b32_e32 v169, 0xffff0000, v242
	v_lshlrev_b32_e32 v170, 16, v243
	v_and_b32_e32 v171, 0xffff0000, v243
	v_add_u32_e32 v1, s46, v154
	v_lshl_add_u32 v1, v1, 11, v0
	v_med3_f32 v164, v164, s34, v227
	v_med3_f32 v165, v165, s34, v227
	v_med3_f32 v166, v166, s34, v227
	v_med3_f32 v167, v167, s34, v227
	v_med3_f32 v168, v168, s34, v227
	v_med3_f32 v169, v169, s34, v227
	v_med3_f32 v170, v170, s34, v227
	v_med3_f32 v171, v171, s34, v227
	v_pk_mul_f32 v[164:165], v[164:165], s[44:45]
	v_pk_mul_f32 v[166:167], v[166:167], s[44:45]
	v_pk_mul_f32 v[168:169], v[168:169], s[44:45]
	v_pk_mul_f32 v[170:171], v[170:171], s[44:45]
	v_exp_f32_e32 v164, v164
	v_exp_f32_e32 v165, v165
	v_exp_f32_e32 v166, v166
	v_exp_f32_e32 v167, v167
	v_exp_f32_e32 v168, v168
	v_exp_f32_e32 v169, v169
	v_exp_f32_e32 v170, v170
	v_exp_f32_e32 v171, v171
	v_pk_add_f32 v[164:165], v[164:165], 1.0 op_sel_hi:[1,0]
	v_pk_add_f32 v[166:167], v[166:167], 1.0 op_sel_hi:[1,0]
	v_pk_add_f32 v[168:169], v[168:169], 1.0 op_sel_hi:[1,0]
	v_pk_add_f32 v[170:171], v[170:171], 1.0 op_sel_hi:[1,0]
	v_rcp_f32_e32 v164, v164
	v_rcp_f32_e32 v165, v165
	v_rcp_f32_e32 v166, v166
	v_rcp_f32_e32 v167, v167
	v_rcp_f32_e32 v168, v168
	v_rcp_f32_e32 v169, v169
	v_rcp_f32_e32 v170, v170
	v_rcp_f32_e32 v171, v171
	v_pk_mul_f32 v[164:165], v[72:73], v[164:165]
	v_pk_mul_f32 v[166:167], v[74:75], v[166:167]
	v_pk_mul_f32 v[168:169], v[68:69], v[168:169]
	v_pk_mul_f32 v[170:171], v[70:71], v[170:171]
	v_cvt_pk_bf16_f32 v174, v164, v165
	v_cvt_pk_bf16_f32 v175, v166, v167
	v_cvt_pk_bf16_f32 v176, v168, v169
	v_cvt_pk_bf16_f32 v177, v170, v171
	global_store_dwordx4 v1, v[174:177], s[22:23] offset:-4096
	s_waitcnt vmcnt(15)
	v_lshlrev_b32_e32 v164, 16, v244
	v_and_b32_e32 v165, 0xffff0000, v244
	v_lshlrev_b32_e32 v166, 16, v245
	v_and_b32_e32 v167, 0xffff0000, v245
	v_lshlrev_b32_e32 v168, 16, v246
	v_and_b32_e32 v169, 0xffff0000, v246
	v_lshlrev_b32_e32 v170, 16, v247
	v_and_b32_e32 v171, 0xffff0000, v247
	v_med3_f32 v164, v164, s34, v227
	v_med3_f32 v165, v165, s34, v227
	v_med3_f32 v166, v166, s34, v227
	v_med3_f32 v167, v167, s34, v227
	v_med3_f32 v168, v168, s34, v227
	v_med3_f32 v169, v169, s34, v227
	v_med3_f32 v170, v170, s34, v227
	v_med3_f32 v171, v171, s34, v227
	v_pk_mul_f32 v[164:165], v[164:165], s[44:45]
	v_pk_mul_f32 v[166:167], v[166:167], s[44:45]
	v_pk_mul_f32 v[168:169], v[168:169], s[44:45]
	v_pk_mul_f32 v[170:171], v[170:171], s[44:45]
	v_exp_f32_e32 v164, v164
	v_exp_f32_e32 v165, v165
	v_exp_f32_e32 v166, v166
	v_exp_f32_e32 v167, v167
	v_exp_f32_e32 v168, v168
	v_exp_f32_e32 v169, v169
	v_exp_f32_e32 v170, v170
	v_exp_f32_e32 v171, v171
	v_pk_add_f32 v[164:165], v[164:165], 1.0 op_sel_hi:[1,0]
	v_pk_add_f32 v[166:167], v[166:167], 1.0 op_sel_hi:[1,0]
	v_pk_add_f32 v[168:169], v[168:169], 1.0 op_sel_hi:[1,0]
	v_pk_add_f32 v[170:171], v[170:171], 1.0 op_sel_hi:[1,0]
	v_rcp_f32_e32 v164, v164
	v_rcp_f32_e32 v165, v165
	v_rcp_f32_e32 v166, v166
	v_rcp_f32_e32 v167, v167
	v_rcp_f32_e32 v168, v168
	v_rcp_f32_e32 v169, v169
	v_rcp_f32_e32 v170, v170
	v_rcp_f32_e32 v171, v171
	v_pk_mul_f32 v[164:165], v[40:41], v[164:165]
	v_pk_mul_f32 v[166:167], v[42:43], v[166:167]
	v_pk_mul_f32 v[168:169], v[36:37], v[168:169]
	v_pk_mul_f32 v[170:171], v[38:39], v[170:171]
	v_cvt_pk_bf16_f32 v174, v164, v165
	v_cvt_pk_bf16_f32 v175, v166, v167
	v_cvt_pk_bf16_f32 v176, v168, v169
	v_cvt_pk_bf16_f32 v177, v170, v171
	global_store_dwordx4 v1, v[174:177], s[22:23] offset:-3840
	s_waitcnt vmcnt(15)
	v_lshlrev_b32_e32 v164, 16, v248
	v_and_b32_e32 v165, 0xffff0000, v248
	v_lshlrev_b32_e32 v166, 16, v249
	v_and_b32_e32 v167, 0xffff0000, v249
	v_lshlrev_b32_e32 v168, 16, v250
	v_and_b32_e32 v169, 0xffff0000, v250
	v_lshlrev_b32_e32 v170, 16, v251
	v_and_b32_e32 v171, 0xffff0000, v251
	v_add_u32_e32 v1, s46, v156
	v_lshl_add_u32 v1, v1, 11, v0
	v_med3_f32 v164, v164, s34, v227
	v_med3_f32 v165, v165, s34, v227
	v_med3_f32 v166, v166, s34, v227
	v_med3_f32 v167, v167, s34, v227
	v_med3_f32 v168, v168, s34, v227
	v_med3_f32 v169, v169, s34, v227
	v_med3_f32 v170, v170, s34, v227
	v_med3_f32 v171, v171, s34, v227
	v_pk_mul_f32 v[164:165], v[164:165], s[44:45]
	v_pk_mul_f32 v[166:167], v[166:167], s[44:45]
	v_pk_mul_f32 v[168:169], v[168:169], s[44:45]
	v_pk_mul_f32 v[170:171], v[170:171], s[44:45]
	v_exp_f32_e32 v164, v164
	v_exp_f32_e32 v165, v165
	v_exp_f32_e32 v166, v166
	v_exp_f32_e32 v167, v167
	v_exp_f32_e32 v168, v168
	v_exp_f32_e32 v169, v169
	v_exp_f32_e32 v170, v170
	v_exp_f32_e32 v171, v171
	v_pk_add_f32 v[164:165], v[164:165], 1.0 op_sel_hi:[1,0]
	v_pk_add_f32 v[166:167], v[166:167], 1.0 op_sel_hi:[1,0]
	v_pk_add_f32 v[168:169], v[168:169], 1.0 op_sel_hi:[1,0]
	v_pk_add_f32 v[170:171], v[170:171], 1.0 op_sel_hi:[1,0]
	v_rcp_f32_e32 v164, v164
	v_rcp_f32_e32 v165, v165
	v_rcp_f32_e32 v166, v166
	v_rcp_f32_e32 v167, v167
	v_rcp_f32_e32 v168, v168
	v_rcp_f32_e32 v169, v169
	v_rcp_f32_e32 v170, v170
	v_rcp_f32_e32 v171, v171
	v_pk_mul_f32 v[164:165], v[64:65], v[164:165]
	v_pk_mul_f32 v[166:167], v[66:67], v[166:167]
	v_pk_mul_f32 v[168:169], v[60:61], v[168:169]
	v_pk_mul_f32 v[170:171], v[62:63], v[170:171]
	v_cvt_pk_bf16_f32 v174, v164, v165
	v_cvt_pk_bf16_f32 v175, v166, v167
	v_cvt_pk_bf16_f32 v176, v168, v169
	v_cvt_pk_bf16_f32 v177, v170, v171
	global_store_dwordx4 v1, v[174:177], s[22:23] offset:-4096
	s_waitcnt vmcnt(15)
	v_lshlrev_b32_e32 v164, 16, v132
	v_and_b32_e32 v165, 0xffff0000, v132
	v_lshlrev_b32_e32 v166, 16, v133
	v_and_b32_e32 v167, 0xffff0000, v133
	v_lshlrev_b32_e32 v168, 16, v134
	v_and_b32_e32 v169, 0xffff0000, v134
	v_lshlrev_b32_e32 v170, 16, v135
	v_and_b32_e32 v171, 0xffff0000, v135
	v_med3_f32 v164, v164, s34, v227
	v_med3_f32 v165, v165, s34, v227
	v_med3_f32 v166, v166, s34, v227
	v_med3_f32 v167, v167, s34, v227
	v_med3_f32 v168, v168, s34, v227
	v_med3_f32 v169, v169, s34, v227
	v_med3_f32 v170, v170, s34, v227
	v_med3_f32 v171, v171, s34, v227
	v_pk_mul_f32 v[164:165], v[164:165], s[44:45]
	v_pk_mul_f32 v[166:167], v[166:167], s[44:45]
	v_pk_mul_f32 v[168:169], v[168:169], s[44:45]
	v_pk_mul_f32 v[170:171], v[170:171], s[44:45]
	v_exp_f32_e32 v164, v164
	v_exp_f32_e32 v165, v165
	v_exp_f32_e32 v166, v166
	v_exp_f32_e32 v167, v167
	v_exp_f32_e32 v168, v168
	v_exp_f32_e32 v169, v169
	v_exp_f32_e32 v170, v170
	v_exp_f32_e32 v171, v171
	v_pk_add_f32 v[164:165], v[164:165], 1.0 op_sel_hi:[1,0]
	v_pk_add_f32 v[166:167], v[166:167], 1.0 op_sel_hi:[1,0]
	v_pk_add_f32 v[168:169], v[168:169], 1.0 op_sel_hi:[1,0]
	v_pk_add_f32 v[170:171], v[170:171], 1.0 op_sel_hi:[1,0]
	v_rcp_f32_e32 v164, v164
	v_rcp_f32_e32 v165, v165
	v_rcp_f32_e32 v166, v166
	v_rcp_f32_e32 v167, v167
	v_rcp_f32_e32 v168, v168
	v_rcp_f32_e32 v169, v169
	v_rcp_f32_e32 v170, v170
	v_rcp_f32_e32 v171, v171
	v_pk_mul_f32 v[164:165], v[32:33], v[164:165]
	v_pk_mul_f32 v[166:167], v[34:35], v[166:167]
	v_pk_mul_f32 v[168:169], v[28:29], v[168:169]
	v_pk_mul_f32 v[170:171], v[30:31], v[170:171]
	v_cvt_pk_bf16_f32 v174, v164, v165
	v_cvt_pk_bf16_f32 v175, v166, v167
	v_cvt_pk_bf16_f32 v176, v168, v169
	v_cvt_pk_bf16_f32 v177, v170, v171
	global_store_dwordx4 v1, v[174:177], s[22:23] offset:-3840
	s_waitcnt vmcnt(14)
	v_lshlrev_b32_e32 v164, 16, v178
	v_and_b32_e32 v165, 0xffff0000, v178
	v_lshlrev_b32_e32 v166, 16, v179
	v_and_b32_e32 v167, 0xffff0000, v179
	v_lshlrev_b32_e32 v168, 16, v180
	v_and_b32_e32 v169, 0xffff0000, v180
	v_lshlrev_b32_e32 v170, 16, v181
	v_and_b32_e32 v171, 0xffff0000, v181
	v_add_u32_e32 v1, s46, v158
	v_lshl_add_u32 v1, v1, 11, v0
	v_med3_f32 v164, v164, s34, v227
	v_med3_f32 v165, v165, s34, v227
	v_med3_f32 v166, v166, s34, v227
	v_med3_f32 v167, v167, s34, v227
	v_med3_f32 v168, v168, s34, v227
	v_med3_f32 v169, v169, s34, v227
	v_med3_f32 v170, v170, s34, v227
	v_med3_f32 v171, v171, s34, v227
	v_pk_mul_f32 v[164:165], v[164:165], s[44:45]
	v_pk_mul_f32 v[166:167], v[166:167], s[44:45]
	v_pk_mul_f32 v[168:169], v[168:169], s[44:45]
	v_pk_mul_f32 v[170:171], v[170:171], s[44:45]
	v_exp_f32_e32 v164, v164
	v_exp_f32_e32 v165, v165
	v_exp_f32_e32 v166, v166
	v_exp_f32_e32 v167, v167
	v_exp_f32_e32 v168, v168
	v_exp_f32_e32 v169, v169
	v_exp_f32_e32 v170, v170
	v_exp_f32_e32 v171, v171
	v_pk_add_f32 v[164:165], v[164:165], 1.0 op_sel_hi:[1,0]
	v_pk_add_f32 v[166:167], v[166:167], 1.0 op_sel_hi:[1,0]
	v_pk_add_f32 v[168:169], v[168:169], 1.0 op_sel_hi:[1,0]
	v_pk_add_f32 v[170:171], v[170:171], 1.0 op_sel_hi:[1,0]
	v_rcp_f32_e32 v164, v164
	v_rcp_f32_e32 v165, v165
	v_rcp_f32_e32 v166, v166
	v_rcp_f32_e32 v167, v167
	v_rcp_f32_e32 v168, v168
	v_rcp_f32_e32 v169, v169
	v_rcp_f32_e32 v170, v170
	v_rcp_f32_e32 v171, v171
	v_pk_mul_f32 v[164:165], v[56:57], v[164:165]
	v_pk_mul_f32 v[166:167], v[58:59], v[166:167]
	v_pk_mul_f32 v[168:169], v[52:53], v[168:169]
	v_pk_mul_f32 v[170:171], v[54:55], v[170:171]
	v_cvt_pk_bf16_f32 v174, v164, v165
	v_cvt_pk_bf16_f32 v175, v166, v167
	v_cvt_pk_bf16_f32 v176, v168, v169
	v_cvt_pk_bf16_f32 v177, v170, v171
	global_store_dwordx4 v1, v[174:177], s[22:23] offset:-4096
	s_waitcnt vmcnt(13)
	v_lshlrev_b32_e32 v164, 16, v182
	v_and_b32_e32 v165, 0xffff0000, v182
	v_lshlrev_b32_e32 v166, 16, v183
	v_and_b32_e32 v167, 0xffff0000, v183
	v_lshlrev_b32_e32 v168, 16, v184
	v_and_b32_e32 v169, 0xffff0000, v184
	v_lshlrev_b32_e32 v170, 16, v185
	v_and_b32_e32 v171, 0xffff0000, v185
	v_med3_f32 v164, v164, s34, v227
	v_med3_f32 v165, v165, s34, v227
	v_med3_f32 v166, v166, s34, v227
	v_med3_f32 v167, v167, s34, v227
	v_med3_f32 v168, v168, s34, v227
	v_med3_f32 v169, v169, s34, v227
	v_med3_f32 v170, v170, s34, v227
	v_med3_f32 v171, v171, s34, v227
	v_pk_mul_f32 v[164:165], v[164:165], s[44:45]
	v_pk_mul_f32 v[166:167], v[166:167], s[44:45]
	v_pk_mul_f32 v[168:169], v[168:169], s[44:45]
	v_pk_mul_f32 v[170:171], v[170:171], s[44:45]
	v_exp_f32_e32 v164, v164
	v_exp_f32_e32 v165, v165
	v_exp_f32_e32 v166, v166
	v_exp_f32_e32 v167, v167
	v_exp_f32_e32 v168, v168
	v_exp_f32_e32 v169, v169
	v_exp_f32_e32 v170, v170
	v_exp_f32_e32 v171, v171
	v_pk_add_f32 v[164:165], v[164:165], 1.0 op_sel_hi:[1,0]
	v_pk_add_f32 v[166:167], v[166:167], 1.0 op_sel_hi:[1,0]
	v_pk_add_f32 v[168:169], v[168:169], 1.0 op_sel_hi:[1,0]
	v_pk_add_f32 v[170:171], v[170:171], 1.0 op_sel_hi:[1,0]
	v_rcp_f32_e32 v164, v164
	v_rcp_f32_e32 v165, v165
	v_rcp_f32_e32 v166, v166
	v_rcp_f32_e32 v167, v167
	v_rcp_f32_e32 v168, v168
	v_rcp_f32_e32 v169, v169
	v_rcp_f32_e32 v170, v170
	v_rcp_f32_e32 v171, v171
	v_pk_mul_f32 v[164:165], v[24:25], v[164:165]
	v_pk_mul_f32 v[166:167], v[26:27], v[166:167]
	v_pk_mul_f32 v[168:169], v[20:21], v[168:169]
	v_pk_mul_f32 v[170:171], v[22:23], v[170:171]
	v_cvt_pk_bf16_f32 v174, v164, v165
	v_cvt_pk_bf16_f32 v175, v166, v167
	v_cvt_pk_bf16_f32 v176, v168, v169
	v_cvt_pk_bf16_f32 v177, v170, v171
	global_store_dwordx4 v1, v[174:177], s[22:23] offset:-3840
	s_mov_b64 s[40:41], 0
	s_branch .LBB0_206

.LBB0_242:
	s_add_u32 s23, s0, 0xfffc0080
	s_addc_u32 s24, s1, -1
	ds_read_b128 v[132:135], v216
	ds_read_b128 v[136:139], v216 offset:1024
	ds_read_b128 v[140:143], v216 offset:2048
	ds_read_b128 v[144:147], v216 offset:3072
	s_cmp_eq_u32 s22, 12
	s_cselect_b32 s47, s57, s24
	s_cselect_b32 s46, s56, s23
	s_cselect_b32 s45, s59, s21
	s_cselect_b32 s44, s58, s20
	s_add_i32 m0, s67, 0xc000
	ds_read_b128 v[148:151], v240
	ds_read_b128 v[152:155], v240 offset:1024
	ds_read_b128 v[156:159], v240 offset:2048
	ds_read_b128 v[160:163], v240 offset:3072
	ds_read_b128 v[164:167], v240 offset:4096
	ds_read_b128 v[168:171], v240 offset:5120
	ds_read_b128 v[172:175], v240 offset:6144
	global_load_lds_dwordx4 v194, s[0:1]
	s_add_i32 m0, s67, 0xe000
	ds_read_b128 v[204:207], v240 offset:7168
	global_load_lds_dwordx4 v202, s[0:1]
	s_waitcnt lgkmcnt(8)
	s_barrier
	s_waitcnt lgkmcnt(0)
	v_mfma_f32_16x16x32_bf16 v[128:131], v[132:135], v[148:151], v[128:131]
	v_mfma_f32_16x16x32_bf16 v[124:127], v[140:143], v[148:151], v[124:127]
	v_mfma_f32_16x16x32_bf16 v[120:123], v[132:135], v[156:159], v[120:123]
	v_mfma_f32_16x16x32_bf16 v[116:119], v[140:143], v[156:159], v[116:119]
	v_mfma_f32_16x16x32_bf16 v[112:115], v[132:135], v[164:167], v[112:115]
	v_mfma_f32_16x16x32_bf16 v[108:111], v[140:143], v[164:167], v[108:111]
	v_mfma_f32_16x16x32_bf16 v[104:107], v[132:135], v[172:175], v[104:107]
	v_mfma_f32_16x16x32_bf16 v[100:103], v[140:143], v[172:175], v[100:103]
	v_mfma_f32_16x16x32_bf16 v[128:131], v[136:139], v[152:155], v[128:131]
	v_mfma_f32_16x16x32_bf16 v[124:127], v[144:147], v[152:155], v[124:127]
	v_mfma_f32_16x16x32_bf16 v[120:123], v[136:139], v[160:163], v[120:123]
	v_mfma_f32_16x16x32_bf16 v[116:119], v[144:147], v[160:163], v[116:119]
	v_mfma_f32_16x16x32_bf16 v[112:115], v[136:139], v[168:171], v[112:115]
	v_mfma_f32_16x16x32_bf16 v[108:111], v[144:147], v[168:171], v[108:111]
	v_mfma_f32_16x16x32_bf16 v[104:107], v[136:139], v[204:207], v[104:107]
	v_mfma_f32_16x16x32_bf16 v[100:103], v[144:147], v[204:207], v[100:103]
	s_barrier
	s_add_i32 m0, s61, 0x10000
	ds_read_b128 v[208:211], v216 offset:16384
	ds_read_b128 v[212:215], v216 offset:17408
	ds_read_b128 v[242:245], v216 offset:18432
	global_load_lds_dwordx4 v176, s[44:45]
	s_add_i32 m0, s61, 0x12000
	ds_read_b128 v[246:249], v216 offset:19456
	global_load_lds_dwordx4 v180, s[44:45]
	s_barrier
	s_waitcnt lgkmcnt(0)
	v_mfma_f32_16x16x32_bf16 v[64:67], v[208:211], v[148:151], v[64:67]
	v_mfma_f32_16x16x32_bf16 v[60:63], v[242:245], v[148:151], v[60:63]
	v_mfma_f32_16x16x32_bf16 v[56:59], v[208:211], v[156:159], v[56:59]
	v_mfma_f32_16x16x32_bf16 v[52:55], v[242:245], v[156:159], v[52:55]
	v_mfma_f32_16x16x32_bf16 v[48:51], v[208:211], v[164:167], v[48:51]
	v_mfma_f32_16x16x32_bf16 v[44:47], v[242:245], v[164:167], v[44:47]
	v_mfma_f32_16x16x32_bf16 v[40:43], v[208:211], v[172:175], v[40:43]
	v_mfma_f32_16x16x32_bf16 v[36:39], v[242:245], v[172:175], v[36:39]
	v_mfma_f32_16x16x32_bf16 v[64:67], v[212:215], v[152:155], v[64:67]
	v_mfma_f32_16x16x32_bf16 v[60:63], v[246:249], v[152:155], v[60:63]
	v_mfma_f32_16x16x32_bf16 v[56:59], v[212:215], v[160:163], v[56:59]
	v_mfma_f32_16x16x32_bf16 v[52:55], v[246:249], v[160:163], v[52:55]
	v_mfma_f32_16x16x32_bf16 v[48:51], v[212:215], v[168:171], v[48:51]
	v_mfma_f32_16x16x32_bf16 v[44:47], v[246:249], v[168:171], v[44:47]
	v_mfma_f32_16x16x32_bf16 v[40:43], v[212:215], v[204:207], v[40:43]
	v_mfma_f32_16x16x32_bf16 v[36:39], v[246:249], v[204:207], v[36:39]
	s_mov_b32 m0, s67
	s_barrier
	ds_read_b128 v[148:151], v240 offset:16384
	ds_read_b128 v[152:155], v240 offset:17408
	ds_read_b128 v[156:159], v240 offset:18432
	ds_read_b128 v[160:163], v240 offset:19456
	ds_read_b128 v[164:167], v240 offset:20480
	ds_read_b128 v[168:171], v240 offset:21504
	ds_read_b128 v[172:175], v240 offset:22528
	global_load_lds_dwordx4 v0, s[46:47]
	s_mov_b32 m0, s74
	ds_read_b128 v[204:207], v240 offset:23552
	global_load_lds_dwordx4 v178, s[46:47]
	s_barrier
	s_waitcnt lgkmcnt(0)
	v_mfma_f32_16x16x32_bf16 v[96:99], v[132:135], v[148:151], v[96:99]
	v_mfma_f32_16x16x32_bf16 v[92:95], v[140:143], v[148:151], v[92:95]
	v_mfma_f32_16x16x32_bf16 v[88:91], v[132:135], v[156:159], v[88:91]
	v_mfma_f32_16x16x32_bf16 v[84:87], v[140:143], v[156:159], v[84:87]
	v_mfma_f32_16x16x32_bf16 v[80:83], v[132:135], v[164:167], v[80:83]
	v_mfma_f32_16x16x32_bf16 v[76:79], v[140:143], v[164:167], v[76:79]
	v_mfma_f32_16x16x32_bf16 v[72:75], v[132:135], v[172:175], v[72:75]
	v_mfma_f32_16x16x32_bf16 v[68:71], v[140:143], v[172:175], v[68:71]
	v_mfma_f32_16x16x32_bf16 v[96:99], v[136:139], v[152:155], v[96:99]
	v_mfma_f32_16x16x32_bf16 v[92:95], v[144:147], v[152:155], v[92:95]
	v_mfma_f32_16x16x32_bf16 v[88:91], v[136:139], v[160:163], v[88:91]
	v_mfma_f32_16x16x32_bf16 v[84:87], v[144:147], v[160:163], v[84:87]
	v_mfma_f32_16x16x32_bf16 v[80:83], v[136:139], v[168:171], v[80:83]
	v_mfma_f32_16x16x32_bf16 v[76:79], v[144:147], v[168:171], v[76:79]
	v_mfma_f32_16x16x32_bf16 v[72:75], v[136:139], v[204:207], v[72:75]
	v_mfma_f32_16x16x32_bf16 v[68:71], v[144:147], v[204:207], v[68:71]
	s_barrier
	s_add_i32 m0, s61, 0x14000
	s_add_u32 s24, s44, 0x40000
	s_addc_u32 s25, s45, 0
	global_load_lds_dwordx4 v176, s[24:25]
	s_add_i32 m0, s61, 0x16000
	s_waitcnt vmcnt(5)
	global_load_lds_dwordx4 v180, s[24:25]
	s_barrier
	v_mfma_f32_16x16x32_bf16 v[32:35], v[208:211], v[148:151], v[32:35]
	v_mfma_f32_16x16x32_bf16 v[28:31], v[242:245], v[148:151], v[28:31]
	v_mfma_f32_16x16x32_bf16 v[24:27], v[208:211], v[156:159], v[24:27]
	v_mfma_f32_16x16x32_bf16 v[20:23], v[242:245], v[156:159], v[20:23]
	v_mfma_f32_16x16x32_bf16 v[16:19], v[208:211], v[164:167], v[16:19]
	v_mfma_f32_16x16x32_bf16 v[12:15], v[242:245], v[164:167], v[12:15]
	v_mfma_f32_16x16x32_bf16 v[8:11], v[208:211], v[172:175], v[8:11]
	v_mfma_f32_16x16x32_bf16 v[4:7], v[242:245], v[172:175], v[4:7]
	v_mfma_f32_16x16x32_bf16 v[32:35], v[212:215], v[152:155], v[32:35]
	v_mfma_f32_16x16x32_bf16 v[28:31], v[246:249], v[152:155], v[28:31]
	v_mfma_f32_16x16x32_bf16 v[24:27], v[212:215], v[160:163], v[24:27]
	v_mfma_f32_16x16x32_bf16 v[20:23], v[246:249], v[160:163], v[20:23]
	v_mfma_f32_16x16x32_bf16 v[16:19], v[212:215], v[168:171], v[16:19]
	v_mfma_f32_16x16x32_bf16 v[12:15], v[246:249], v[168:171], v[12:15]
	v_mfma_f32_16x16x32_bf16 v[8:11], v[212:215], v[204:207], v[8:11]
	v_mfma_f32_16x16x32_bf16 v[4:7], v[246:249], v[204:207], v[4:7]
	s_barrier
	ds_read_b128 v[132:135], v216 offset:32768
	ds_read_b128 v[136:139], v216 offset:33792
	ds_read_b128 v[140:143], v216 offset:34816
	ds_read_b128 v[144:147], v216 offset:35840
	s_add_u32 s24, s46, 0x40000
	s_addc_u32 s25, s47, 0
	s_mov_b32 m0, s75
	ds_read_b128 v[148:151], v240 offset:32768
	ds_read_b128 v[152:155], v240 offset:33792
	ds_read_b128 v[156:159], v240 offset:34816
	ds_read_b128 v[160:163], v240 offset:35840
	ds_read_b128 v[164:167], v240 offset:36864
	ds_read_b128 v[168:171], v240 offset:37888
	ds_read_b128 v[172:175], v240 offset:38912
	global_load_lds_dwordx4 v0, s[24:25]
	s_mov_b32 m0, s82
	ds_read_b128 v[204:207], v240 offset:39936
	global_load_lds_dwordx4 v178, s[24:25]
	s_waitcnt lgkmcnt(8)
	s_barrier
	s_waitcnt lgkmcnt(0)
	v_mfma_f32_16x16x32_bf16 v[128:131], v[132:135], v[148:151], v[128:131]
	v_mfma_f32_16x16x32_bf16 v[124:127], v[140:143], v[148:151], v[124:127]
	v_mfma_f32_16x16x32_bf16 v[120:123], v[132:135], v[156:159], v[120:123]
	v_mfma_f32_16x16x32_bf16 v[116:119], v[140:143], v[156:159], v[116:119]
	v_mfma_f32_16x16x32_bf16 v[112:115], v[132:135], v[164:167], v[112:115]
	v_mfma_f32_16x16x32_bf16 v[108:111], v[140:143], v[164:167], v[108:111]
	v_mfma_f32_16x16x32_bf16 v[104:107], v[132:135], v[172:175], v[104:107]
	v_mfma_f32_16x16x32_bf16 v[100:103], v[140:143], v[172:175], v[100:103]
	v_mfma_f32_16x16x32_bf16 v[128:131], v[136:139], v[152:155], v[128:131]
	v_mfma_f32_16x16x32_bf16 v[124:127], v[144:147], v[152:155], v[124:127]
	v_mfma_f32_16x16x32_bf16 v[120:123], v[136:139], v[160:163], v[120:123]
	v_mfma_f32_16x16x32_bf16 v[116:119], v[144:147], v[160:163], v[116:119]
	v_mfma_f32_16x16x32_bf16 v[112:115], v[136:139], v[168:171], v[112:115]
	v_mfma_f32_16x16x32_bf16 v[108:111], v[144:147], v[168:171], v[108:111]
	v_mfma_f32_16x16x32_bf16 v[104:107], v[136:139], v[204:207], v[104:107]
	v_mfma_f32_16x16x32_bf16 v[100:103], v[144:147], v[204:207], v[100:103]
	s_barrier
	s_add_i32 m0, s61, 0x18000
	ds_read_b128 v[208:211], v216 offset:49152
	ds_read_b128 v[212:215], v216 offset:50176
	ds_read_b128 v[242:245], v216 offset:51200
	s_add_u32 s98, s44, 0x80
	s_addc_u32 s99, s45, 0
	global_load_lds_dwordx4 v176, s[98:99]
	s_add_i32 m0, s61, 0x1a000
	ds_read_b128 v[246:249], v216 offset:52224
	global_load_lds_dwordx4 v180, s[98:99]
	s_barrier
	s_waitcnt lgkmcnt(0)
	v_mfma_f32_16x16x32_bf16 v[64:67], v[208:211], v[148:151], v[64:67]
	v_mfma_f32_16x16x32_bf16 v[60:63], v[242:245], v[148:151], v[60:63]
	v_mfma_f32_16x16x32_bf16 v[56:59], v[208:211], v[156:159], v[56:59]
	v_mfma_f32_16x16x32_bf16 v[52:55], v[242:245], v[156:159], v[52:55]
	v_mfma_f32_16x16x32_bf16 v[48:51], v[208:211], v[164:167], v[48:51]
	v_mfma_f32_16x16x32_bf16 v[44:47], v[242:245], v[164:167], v[44:47]
	v_mfma_f32_16x16x32_bf16 v[40:43], v[208:211], v[172:175], v[40:43]
	v_mfma_f32_16x16x32_bf16 v[36:39], v[242:245], v[172:175], v[36:39]
	v_mfma_f32_16x16x32_bf16 v[64:67], v[212:215], v[152:155], v[64:67]
	v_mfma_f32_16x16x32_bf16 v[60:63], v[246:249], v[152:155], v[60:63]
	v_mfma_f32_16x16x32_bf16 v[56:59], v[212:215], v[160:163], v[56:59]
	v_mfma_f32_16x16x32_bf16 v[52:55], v[246:249], v[160:163], v[52:55]
	v_mfma_f32_16x16x32_bf16 v[48:51], v[212:215], v[168:171], v[48:51]
	v_mfma_f32_16x16x32_bf16 v[44:47], v[246:249], v[168:171], v[44:47]
	v_mfma_f32_16x16x32_bf16 v[40:43], v[212:215], v[204:207], v[40:43]
	v_mfma_f32_16x16x32_bf16 v[36:39], v[246:249], v[204:207], v[36:39]
	s_mov_b32 m0, s48
	s_barrier
	ds_read_b128 v[148:151], v240 offset:49152
	ds_read_b128 v[152:155], v240 offset:50176
	ds_read_b128 v[156:159], v240 offset:51200
	ds_read_b128 v[160:163], v240 offset:52224
	ds_read_b128 v[164:167], v240 offset:53248
	ds_read_b128 v[168:171], v240 offset:54272
	ds_read_b128 v[172:175], v240 offset:55296
	s_add_u32 s98, s46, 0x80
	s_addc_u32 s99, s47, 0
	global_load_lds_dwordx4 v0, s[98:99]
	s_mov_b32 m0, s50
	ds_read_b128 v[204:207], v240 offset:56320
	global_load_lds_dwordx4 v178, s[98:99]
	s_barrier
	s_waitcnt lgkmcnt(0)
	v_mfma_f32_16x16x32_bf16 v[96:99], v[132:135], v[148:151], v[96:99]
	v_mfma_f32_16x16x32_bf16 v[92:95], v[140:143], v[148:151], v[92:95]
	v_mfma_f32_16x16x32_bf16 v[88:91], v[132:135], v[156:159], v[88:91]
	v_mfma_f32_16x16x32_bf16 v[84:87], v[140:143], v[156:159], v[84:87]
	v_mfma_f32_16x16x32_bf16 v[80:83], v[132:135], v[164:167], v[80:83]
	v_mfma_f32_16x16x32_bf16 v[76:79], v[140:143], v[164:167], v[76:79]
	v_mfma_f32_16x16x32_bf16 v[72:75], v[132:135], v[172:175], v[72:75]
	v_mfma_f32_16x16x32_bf16 v[68:71], v[140:143], v[172:175], v[68:71]
	v_mfma_f32_16x16x32_bf16 v[96:99], v[136:139], v[152:155], v[96:99]
	v_mfma_f32_16x16x32_bf16 v[92:95], v[144:147], v[152:155], v[92:95]
	v_mfma_f32_16x16x32_bf16 v[88:91], v[136:139], v[160:163], v[88:91]
	v_mfma_f32_16x16x32_bf16 v[84:87], v[144:147], v[160:163], v[84:87]
	v_mfma_f32_16x16x32_bf16 v[80:83], v[136:139], v[168:171], v[80:83]
	v_mfma_f32_16x16x32_bf16 v[76:79], v[144:147], v[168:171], v[76:79]
	v_mfma_f32_16x16x32_bf16 v[72:75], v[136:139], v[204:207], v[72:75]
	v_mfma_f32_16x16x32_bf16 v[68:71], v[144:147], v[204:207], v[68:71]
	s_barrier
	s_add_i32 m0, s61, 0x1c000
	s_add_u32 s24, s44, 0x40080
	s_addc_u32 s25, s45, 0
	global_load_lds_dwordx4 v176, s[24:25]
	s_add_i32 m0, s61, 0x1e000
	s_waitcnt vmcnt(5)
	global_load_lds_dwordx4 v180, s[24:25]
	s_barrier
	v_mfma_f32_16x16x32_bf16 v[32:35], v[208:211], v[148:151], v[32:35]
	v_mfma_f32_16x16x32_bf16 v[28:31], v[242:245], v[148:151], v[28:31]
	v_mfma_f32_16x16x32_bf16 v[24:27], v[208:211], v[156:159], v[24:27]
	v_mfma_f32_16x16x32_bf16 v[20:23], v[242:245], v[156:159], v[20:23]
	v_mfma_f32_16x16x32_bf16 v[16:19], v[208:211], v[164:167], v[16:19]
	v_mfma_f32_16x16x32_bf16 v[12:15], v[242:245], v[164:167], v[12:15]
	v_mfma_f32_16x16x32_bf16 v[8:11], v[208:211], v[172:175], v[8:11]
	v_mfma_f32_16x16x32_bf16 v[4:7], v[242:245], v[172:175], v[4:7]
	v_mfma_f32_16x16x32_bf16 v[32:35], v[212:215], v[152:155], v[32:35]
	v_mfma_f32_16x16x32_bf16 v[28:31], v[246:249], v[152:155], v[28:31]
	v_mfma_f32_16x16x32_bf16 v[24:27], v[212:215], v[160:163], v[24:27]
	v_mfma_f32_16x16x32_bf16 v[20:23], v[246:249], v[160:163], v[20:23]
	v_mfma_f32_16x16x32_bf16 v[16:19], v[212:215], v[168:171], v[16:19]
	v_mfma_f32_16x16x32_bf16 v[12:15], v[246:249], v[168:171], v[12:15]
	v_mfma_f32_16x16x32_bf16 v[8:11], v[212:215], v[204:207], v[8:11]
	v_mfma_f32_16x16x32_bf16 v[4:7], v[246:249], v[204:207], v[4:7]
	s_add_i32 s22, s22, 2
	s_add_u32 s0, s0, 0x100
	s_addc_u32 s1, s1, 0
	s_add_u32 s20, s20, 0x100
	s_addc_u32 s21, s21, 0
	s_cmp_gt_u32 s22, 13
	s_barrier
	s_cbranch_scc0 .LBB0_242
	s_add_i32 s0, s66, -8
	s_cmp_lt_u32 s0, 12
	s_mov_b64 s[0:1], -1
	s_cbranch_scc1 .LBB0_266
	s_cmp_gt_i32 s66, 33
	s_cselect_b64 s[64:65], -1, 0
	s_lshl_b32 s0, s66, 8
	s_lshl_b32 s53, s60, 8
	s_add_i32 s1, s0, 0xffffee00
	s_cmp_lt_i32 s66, 26
	v_cndmask_b32_e64 v2, 0, 1, s[80:81]
	s_cselect_b32 s62, s0, s1
	s_mov_b64 s[0:1], -1
	s_and_b64 vcc, exec, s[64:65]
	v_cmp_ne_u32_e64 s[44:45], 1, v2
	s_cbranch_vccz .LBB0_248
	s_and_b64 vcc, exec, s[44:45]
	s_cbranch_vccnz .LBB0_247
	v_add_u32_e32 v132, s53, v185
	v_ashrrev_i32_e32 v133, 31, v132
	v_lshlrev_b64 v[140:141], 7, v[132:133]
	global_load_dwordx4 v[132:135], v[188:189], off offset:16
	global_load_dwordx4 v[136:139], v[188:189], off
	s_mov_b32 s3, 0xbfb8aa3b
	s_mov_b32 s2, 0x800000
	s_mov_b32 s5, 0x3f317217
	s_mov_b32 s6, 0x7f800000
	s_waitcnt vmcnt(0)
	v_add_f32_e32 v147, v126, v134
	v_add_f32_e32 v2, v128, v136
	v_max_f32_e32 v142, 0, v2
	v_mul_f32_e64 v2, |v2|, s3
	v_exp_f32_e32 v2, v2
	v_add_f32_e32 v136, v124, v132
	v_add_f32_e32 v149, v127, v135
	v_add_f32_e32 v2, 1.0, v2
	v_cmp_gt_f32_e32 vcc, s2, v2
	s_nop 1
	v_cndmask_b32_e64 v132, 0, 32, vcc
	v_ldexp_f32 v2, v2, v132
	v_log_f32_e32 v2, v2
	s_nop 0
	v_mul_f32_e32 v132, 0x3f317217, v2
	v_fma_f32 v132, v2, s5, -v132
	v_fmac_f32_e32 v132, 0x3377d1cf, v2
	v_fmac_f32_e32 v132, 0x3f317217, v2
	v_cmp_lt_f32_e64 s[0:1], |v2|, s6
	s_nop 1
	v_cndmask_b32_e64 v2, v2, v132, s[0:1]
	v_cndmask_b32_e32 v132, 0, v228, vcc
	v_sub_f32_e32 v144, v2, v132
	v_mul_f32_e64 v2, |v136|, s3
	v_exp_f32_e32 v2, v2
	v_max_f32_e32 v132, 0, v136
	v_add_f32_e32 v2, 1.0, v2
	v_cmp_gt_f32_e32 vcc, s2, v2
	s_nop 1
	v_cndmask_b32_e64 v136, 0, 32, vcc
	v_ldexp_f32 v2, v2, v136
	v_log_f32_e32 v2, v2
	s_nop 0
	v_mul_f32_e32 v136, 0x3f317217, v2
	v_fma_f32 v136, v2, s5, -v136
	v_fmac_f32_e32 v136, 0x3377d1cf, v2
	v_fmac_f32_e32 v136, 0x3f317217, v2
	v_cmp_lt_f32_e64 s[0:1], |v2|, s6
	s_nop 1
	v_cndmask_b32_e64 v2, v2, v136, s[0:1]
	v_cndmask_b32_e32 v136, 0, v228, vcc
	v_sub_f32_e32 v136, v2, v136
	v_add_f32_e32 v2, v129, v137
	v_max_f32_e32 v143, 0, v2
	v_mul_f32_e64 v2, |v2|, s3
	v_exp_f32_e32 v2, v2
	v_add_f32_e32 v137, v125, v133
	v_add_f32_e32 v2, 1.0, v2
	v_cmp_gt_f32_e32 vcc, s2, v2
	s_nop 1
	v_cndmask_b32_e64 v133, 0, 32, vcc
	v_ldexp_f32 v2, v2, v133
	v_log_f32_e32 v2, v2
	s_nop 0
	v_mul_f32_e32 v133, 0x3f317217, v2
	v_fma_f32 v133, v2, s5, -v133
	v_fmac_f32_e32 v133, 0x3377d1cf, v2
	v_fmac_f32_e32 v133, 0x3f317217, v2
	v_cmp_lt_f32_e64 s[0:1], |v2|, s6
	s_nop 1
	v_cndmask_b32_e64 v2, v2, v133, s[0:1]
	v_cndmask_b32_e32 v133, 0, v228, vcc
	v_sub_f32_e32 v145, v2, v133
	v_mul_f32_e64 v2, |v137|, s3
	v_exp_f32_e32 v2, v2
	v_max_f32_e32 v133, 0, v137
	v_pk_add_f32 v[142:143], v[142:143], v[144:145]
	v_add_f32_e32 v2, 1.0, v2
	v_cmp_gt_f32_e32 vcc, s2, v2
	s_nop 1
	v_cndmask_b32_e64 v137, 0, 32, vcc
	v_ldexp_f32 v2, v2, v137
	v_log_f32_e32 v2, v2
	s_nop 0
	v_mul_f32_e32 v137, 0x3f317217, v2
	v_fma_f32 v137, v2, s5, -v137
	v_fmac_f32_e32 v137, 0x3377d1cf, v2
	v_fmac_f32_e32 v137, 0x3f317217, v2
	v_cmp_lt_f32_e64 s[0:1], |v2|, s6
	s_nop 1
	v_cndmask_b32_e64 v2, v2, v137, s[0:1]
	v_cndmask_b32_e32 v137, 0, v228, vcc
	v_sub_f32_e32 v137, v2, v137
	v_add_f32_e32 v2, v130, v138
	v_max_f32_e32 v138, 0, v2
	v_mul_f32_e64 v2, |v2|, s3
	v_exp_f32_e32 v2, v2
	v_pk_add_f32 v[132:133], v[132:133], v[136:137]
	v_lshl_add_u64 v[136:137], v[190:191], 0, v[140:141]
	v_add_f32_e32 v2, 1.0, v2
	v_cmp_gt_f32_e32 vcc, s2, v2
	s_nop 1
	v_cndmask_b32_e64 v134, 0, 32, vcc
	v_ldexp_f32 v2, v2, v134
	v_log_f32_e32 v2, v2
	s_nop 0
	v_mul_f32_e32 v134, 0x3f317217, v2
	v_fma_f32 v134, v2, s5, -v134
	v_fmac_f32_e32 v134, 0x3377d1cf, v2
	v_fmac_f32_e32 v134, 0x3f317217, v2
	v_cmp_lt_f32_e64 s[0:1], |v2|, s6
	s_nop 1
	v_cndmask_b32_e64 v2, v2, v134, s[0:1]
	v_cndmask_b32_e32 v134, 0, v228, vcc
	v_sub_f32_e32 v146, v2, v134
	v_mul_f32_e64 v2, |v147|, s3
	v_exp_f32_e32 v2, v2
	v_max_f32_e32 v134, 0, v147
	v_add_f32_e32 v2, 1.0, v2
	v_cmp_gt_f32_e32 vcc, s2, v2
	s_nop 1
	v_cndmask_b32_e64 v147, 0, 32, vcc
	v_ldexp_f32 v2, v2, v147
	v_log_f32_e32 v2, v2
	s_nop 0
	v_mul_f32_e32 v147, 0x3f317217, v2
	v_fma_f32 v147, v2, s5, -v147
	v_fmac_f32_e32 v147, 0x3377d1cf, v2
	v_fmac_f32_e32 v147, 0x3f317217, v2
	v_cmp_lt_f32_e64 s[0:1], |v2|, s6
	s_nop 1
	v_cndmask_b32_e64 v2, v2, v147, s[0:1]
	v_cndmask_b32_e32 v147, 0, v228, vcc
	v_sub_f32_e32 v148, v2, v147
	v_add_f32_e32 v2, v131, v139
	v_max_f32_e32 v139, 0, v2
	v_mul_f32_e64 v2, |v2|, s3
	v_exp_f32_e32 v2, v2
	s_nop 0
	v_add_f32_e32 v2, 1.0, v2
	v_cmp_gt_f32_e32 vcc, s2, v2
	s_nop 1
	v_cndmask_b32_e64 v135, 0, 32, vcc
	v_ldexp_f32 v2, v2, v135
	v_log_f32_e32 v2, v2
	s_nop 0
	v_mul_f32_e32 v135, 0x3f317217, v2
	v_fma_f32 v135, v2, s5, -v135
	v_fmac_f32_e32 v135, 0x3377d1cf, v2
	v_fmac_f32_e32 v135, 0x3f317217, v2
	v_cmp_lt_f32_e64 s[0:1], |v2|, s6
	s_nop 1
	v_cndmask_b32_e64 v2, v2, v135, s[0:1]
	v_cndmask_b32_e32 v135, 0, v228, vcc
	v_sub_f32_e32 v147, v2, v135
	v_mul_f32_e64 v2, |v149|, s3
	v_exp_f32_e32 v2, v2
	v_pk_add_f32 v[144:145], v[138:139], v[146:147]
	v_max_f32_e32 v135, 0, v149
	v_add_f32_e32 v2, 1.0, v2
	v_cmp_gt_f32_e32 vcc, s2, v2
	s_nop 1
	v_cndmask_b32_e64 v138, 0, 32, vcc
	v_ldexp_f32 v2, v2, v138
	v_log_f32_e32 v2, v2
	s_nop 0
	v_mul_f32_e32 v138, 0x3f317217, v2
	v_fma_f32 v138, v2, s5, -v138
	v_fmac_f32_e32 v138, 0x3377d1cf, v2
	v_fmac_f32_e32 v138, 0x3f317217, v2
	v_cmp_lt_f32_e64 s[0:1], |v2|, s6
	s_nop 1
	v_cndmask_b32_e64 v2, v2, v138, s[0:1]
	v_cndmask_b32_e32 v138, 0, v228, vcc
	v_sub_f32_e32 v149, v2, v138
	v_pk_add_f32 v[134:135], v[134:135], v[148:149]
	global_store_dwordx4 v[136:137], v[142:145], off
	global_store_dwordx4 v[136:137], v[132:135], off offset:16

.LBB0_427:
	s_add_u32 s23, s0, 0xfffc0080
	s_addc_u32 s24, s1, -1
	ds_read_b128 v[132:135], v216
	ds_read_b128 v[136:139], v216 offset:1024
	ds_read_b128 v[140:143], v216 offset:2048
	ds_read_b128 v[144:147], v216 offset:3072
	s_cmp_eq_u32 s22, 12
	s_cselect_b32 s47, s57, s24
	s_cselect_b32 s46, s56, s23
	s_cselect_b32 s45, s59, s21
	s_cselect_b32 s44, s58, s20
	s_add_i32 m0, s74, 0xc000
	ds_read_b128 v[148:151], v240
	ds_read_b128 v[152:155], v240 offset:1024
	ds_read_b128 v[156:159], v240 offset:2048
	ds_read_b128 v[160:163], v240 offset:3072
	ds_read_b128 v[164:167], v240 offset:4096
	ds_read_b128 v[168:171], v240 offset:5120
	ds_read_b128 v[172:175], v240 offset:6144
	global_load_lds_dwordx4 v194, s[0:1]
	s_add_i32 m0, s74, 0xe000
	ds_read_b128 v[204:207], v240 offset:7168
	global_load_lds_dwordx4 v202, s[0:1]
	s_waitcnt lgkmcnt(8)
	s_barrier
	s_waitcnt lgkmcnt(0)
	v_mfma_f32_16x16x32_bf16 v[128:131], v[132:135], v[148:151], v[128:131]
	v_mfma_f32_16x16x32_bf16 v[124:127], v[140:143], v[148:151], v[124:127]
	v_mfma_f32_16x16x32_bf16 v[120:123], v[132:135], v[156:159], v[120:123]
	v_mfma_f32_16x16x32_bf16 v[116:119], v[140:143], v[156:159], v[116:119]
	v_mfma_f32_16x16x32_bf16 v[112:115], v[132:135], v[164:167], v[112:115]
	v_mfma_f32_16x16x32_bf16 v[108:111], v[140:143], v[164:167], v[108:111]
	v_mfma_f32_16x16x32_bf16 v[104:107], v[132:135], v[172:175], v[104:107]
	v_mfma_f32_16x16x32_bf16 v[100:103], v[140:143], v[172:175], v[100:103]
	v_mfma_f32_16x16x32_bf16 v[128:131], v[136:139], v[152:155], v[128:131]
	v_mfma_f32_16x16x32_bf16 v[124:127], v[144:147], v[152:155], v[124:127]
	v_mfma_f32_16x16x32_bf16 v[120:123], v[136:139], v[160:163], v[120:123]
	v_mfma_f32_16x16x32_bf16 v[116:119], v[144:147], v[160:163], v[116:119]
	v_mfma_f32_16x16x32_bf16 v[112:115], v[136:139], v[168:171], v[112:115]
	v_mfma_f32_16x16x32_bf16 v[108:111], v[144:147], v[168:171], v[108:111]
	v_mfma_f32_16x16x32_bf16 v[104:107], v[136:139], v[204:207], v[104:107]
	v_mfma_f32_16x16x32_bf16 v[100:103], v[144:147], v[204:207], v[100:103]
	s_barrier
	s_add_i32 m0, s67, 0x10000
	ds_read_b128 v[208:211], v216 offset:16384
	ds_read_b128 v[212:215], v216 offset:17408
	ds_read_b128 v[242:245], v216 offset:18432
	global_load_lds_dwordx4 v176, s[44:45]
	s_add_i32 m0, s67, 0x12000
	ds_read_b128 v[246:249], v216 offset:19456
	global_load_lds_dwordx4 v180, s[44:45]
	s_barrier
	s_waitcnt lgkmcnt(0)
	v_mfma_f32_16x16x32_bf16 v[64:67], v[208:211], v[148:151], v[64:67]
	v_mfma_f32_16x16x32_bf16 v[60:63], v[242:245], v[148:151], v[60:63]
	v_mfma_f32_16x16x32_bf16 v[56:59], v[208:211], v[156:159], v[56:59]
	v_mfma_f32_16x16x32_bf16 v[52:55], v[242:245], v[156:159], v[52:55]
	v_mfma_f32_16x16x32_bf16 v[48:51], v[208:211], v[164:167], v[48:51]
	v_mfma_f32_16x16x32_bf16 v[44:47], v[242:245], v[164:167], v[44:47]
	v_mfma_f32_16x16x32_bf16 v[40:43], v[208:211], v[172:175], v[40:43]
	v_mfma_f32_16x16x32_bf16 v[36:39], v[242:245], v[172:175], v[36:39]
	v_mfma_f32_16x16x32_bf16 v[64:67], v[212:215], v[152:155], v[64:67]
	v_mfma_f32_16x16x32_bf16 v[60:63], v[246:249], v[152:155], v[60:63]
	v_mfma_f32_16x16x32_bf16 v[56:59], v[212:215], v[160:163], v[56:59]
	v_mfma_f32_16x16x32_bf16 v[52:55], v[246:249], v[160:163], v[52:55]
	v_mfma_f32_16x16x32_bf16 v[48:51], v[212:215], v[168:171], v[48:51]
	v_mfma_f32_16x16x32_bf16 v[44:47], v[246:249], v[168:171], v[44:47]
	v_mfma_f32_16x16x32_bf16 v[40:43], v[212:215], v[204:207], v[40:43]
	v_mfma_f32_16x16x32_bf16 v[36:39], v[246:249], v[204:207], v[36:39]
	s_mov_b32 m0, s74
	s_barrier
	ds_read_b128 v[148:151], v240 offset:16384
	ds_read_b128 v[152:155], v240 offset:17408
	ds_read_b128 v[156:159], v240 offset:18432
	ds_read_b128 v[160:163], v240 offset:19456
	ds_read_b128 v[164:167], v240 offset:20480
	ds_read_b128 v[168:171], v240 offset:21504
	ds_read_b128 v[172:175], v240 offset:22528
	global_load_lds_dwordx4 v0, s[46:47]
	s_mov_b32 m0, s75
	ds_read_b128 v[204:207], v240 offset:23552
	global_load_lds_dwordx4 v178, s[46:47]
	s_barrier
	s_waitcnt lgkmcnt(0)
	v_mfma_f32_16x16x32_bf16 v[96:99], v[132:135], v[148:151], v[96:99]
	v_mfma_f32_16x16x32_bf16 v[92:95], v[140:143], v[148:151], v[92:95]
	v_mfma_f32_16x16x32_bf16 v[88:91], v[132:135], v[156:159], v[88:91]
	v_mfma_f32_16x16x32_bf16 v[84:87], v[140:143], v[156:159], v[84:87]
	v_mfma_f32_16x16x32_bf16 v[80:83], v[132:135], v[164:167], v[80:83]
	v_mfma_f32_16x16x32_bf16 v[76:79], v[140:143], v[164:167], v[76:79]
	v_mfma_f32_16x16x32_bf16 v[72:75], v[132:135], v[172:175], v[72:75]
	v_mfma_f32_16x16x32_bf16 v[68:71], v[140:143], v[172:175], v[68:71]
	v_mfma_f32_16x16x32_bf16 v[96:99], v[136:139], v[152:155], v[96:99]
	v_mfma_f32_16x16x32_bf16 v[92:95], v[144:147], v[152:155], v[92:95]
	v_mfma_f32_16x16x32_bf16 v[88:91], v[136:139], v[160:163], v[88:91]
	v_mfma_f32_16x16x32_bf16 v[84:87], v[144:147], v[160:163], v[84:87]
	v_mfma_f32_16x16x32_bf16 v[80:83], v[136:139], v[168:171], v[80:83]
	v_mfma_f32_16x16x32_bf16 v[76:79], v[144:147], v[168:171], v[76:79]
	v_mfma_f32_16x16x32_bf16 v[72:75], v[136:139], v[204:207], v[72:75]
	v_mfma_f32_16x16x32_bf16 v[68:71], v[144:147], v[204:207], v[68:71]
	s_barrier
	s_add_i32 m0, s67, 0x14000
	s_add_u32 s24, s44, 0x40000
	s_addc_u32 s25, s45, 0
	global_load_lds_dwordx4 v176, s[24:25]
	s_add_i32 m0, s67, 0x16000
	s_waitcnt vmcnt(5)
	global_load_lds_dwordx4 v180, s[24:25]
	s_barrier
	v_mfma_f32_16x16x32_bf16 v[32:35], v[208:211], v[148:151], v[32:35]
	v_mfma_f32_16x16x32_bf16 v[28:31], v[242:245], v[148:151], v[28:31]
	v_mfma_f32_16x16x32_bf16 v[24:27], v[208:211], v[156:159], v[24:27]
	v_mfma_f32_16x16x32_bf16 v[20:23], v[242:245], v[156:159], v[20:23]
	v_mfma_f32_16x16x32_bf16 v[16:19], v[208:211], v[164:167], v[16:19]
	v_mfma_f32_16x16x32_bf16 v[12:15], v[242:245], v[164:167], v[12:15]
	v_mfma_f32_16x16x32_bf16 v[8:11], v[208:211], v[172:175], v[8:11]
	v_mfma_f32_16x16x32_bf16 v[4:7], v[242:245], v[172:175], v[4:7]
	v_mfma_f32_16x16x32_bf16 v[32:35], v[212:215], v[152:155], v[32:35]
	v_mfma_f32_16x16x32_bf16 v[28:31], v[246:249], v[152:155], v[28:31]
	v_mfma_f32_16x16x32_bf16 v[24:27], v[212:215], v[160:163], v[24:27]
	v_mfma_f32_16x16x32_bf16 v[20:23], v[246:249], v[160:163], v[20:23]
	v_mfma_f32_16x16x32_bf16 v[16:19], v[212:215], v[168:171], v[16:19]
	v_mfma_f32_16x16x32_bf16 v[12:15], v[246:249], v[168:171], v[12:15]
	v_mfma_f32_16x16x32_bf16 v[8:11], v[212:215], v[204:207], v[8:11]
	v_mfma_f32_16x16x32_bf16 v[4:7], v[246:249], v[204:207], v[4:7]
	s_barrier
	ds_read_b128 v[132:135], v216 offset:32768
	ds_read_b128 v[136:139], v216 offset:33792
	ds_read_b128 v[140:143], v216 offset:34816
	ds_read_b128 v[144:147], v216 offset:35840
	s_add_u32 s24, s46, 0x40000
	s_addc_u32 s25, s47, 0
	s_mov_b32 m0, s82
	ds_read_b128 v[148:151], v240 offset:32768
	ds_read_b128 v[152:155], v240 offset:33792
	ds_read_b128 v[156:159], v240 offset:34816
	ds_read_b128 v[160:163], v240 offset:35840
	ds_read_b128 v[164:167], v240 offset:36864
	ds_read_b128 v[168:171], v240 offset:37888
	ds_read_b128 v[172:175], v240 offset:38912
	global_load_lds_dwordx4 v0, s[24:25]
	s_mov_b32 m0, s83
	ds_read_b128 v[204:207], v240 offset:39936
	global_load_lds_dwordx4 v178, s[24:25]
	s_waitcnt lgkmcnt(8)
	s_barrier
	s_waitcnt lgkmcnt(0)
	v_mfma_f32_16x16x32_bf16 v[128:131], v[132:135], v[148:151], v[128:131]
	v_mfma_f32_16x16x32_bf16 v[124:127], v[140:143], v[148:151], v[124:127]
	v_mfma_f32_16x16x32_bf16 v[120:123], v[132:135], v[156:159], v[120:123]
	v_mfma_f32_16x16x32_bf16 v[116:119], v[140:143], v[156:159], v[116:119]
	v_mfma_f32_16x16x32_bf16 v[112:115], v[132:135], v[164:167], v[112:115]
	v_mfma_f32_16x16x32_bf16 v[108:111], v[140:143], v[164:167], v[108:111]
	v_mfma_f32_16x16x32_bf16 v[104:107], v[132:135], v[172:175], v[104:107]
	v_mfma_f32_16x16x32_bf16 v[100:103], v[140:143], v[172:175], v[100:103]
	v_mfma_f32_16x16x32_bf16 v[128:131], v[136:139], v[152:155], v[128:131]
	v_mfma_f32_16x16x32_bf16 v[124:127], v[144:147], v[152:155], v[124:127]
	v_mfma_f32_16x16x32_bf16 v[120:123], v[136:139], v[160:163], v[120:123]
	v_mfma_f32_16x16x32_bf16 v[116:119], v[144:147], v[160:163], v[116:119]
	v_mfma_f32_16x16x32_bf16 v[112:115], v[136:139], v[168:171], v[112:115]
	v_mfma_f32_16x16x32_bf16 v[108:111], v[144:147], v[168:171], v[108:111]
	v_mfma_f32_16x16x32_bf16 v[104:107], v[136:139], v[204:207], v[104:107]
	v_mfma_f32_16x16x32_bf16 v[100:103], v[144:147], v[204:207], v[100:103]
	s_barrier
	s_add_i32 m0, s67, 0x18000
	ds_read_b128 v[208:211], v216 offset:49152
	ds_read_b128 v[212:215], v216 offset:50176
	ds_read_b128 v[242:245], v216 offset:51200
	s_add_u32 s98, s44, 0x80
	s_addc_u32 s99, s45, 0
	global_load_lds_dwordx4 v176, s[98:99]
	s_add_i32 m0, s67, 0x1a000
	ds_read_b128 v[246:249], v216 offset:52224
	global_load_lds_dwordx4 v180, s[98:99]
	s_barrier
	s_waitcnt lgkmcnt(0)
	v_mfma_f32_16x16x32_bf16 v[64:67], v[208:211], v[148:151], v[64:67]
	v_mfma_f32_16x16x32_bf16 v[60:63], v[242:245], v[148:151], v[60:63]
	v_mfma_f32_16x16x32_bf16 v[56:59], v[208:211], v[156:159], v[56:59]
	v_mfma_f32_16x16x32_bf16 v[52:55], v[242:245], v[156:159], v[52:55]
	v_mfma_f32_16x16x32_bf16 v[48:51], v[208:211], v[164:167], v[48:51]
	v_mfma_f32_16x16x32_bf16 v[44:47], v[242:245], v[164:167], v[44:47]
	v_mfma_f32_16x16x32_bf16 v[40:43], v[208:211], v[172:175], v[40:43]
	v_mfma_f32_16x16x32_bf16 v[36:39], v[242:245], v[172:175], v[36:39]
	v_mfma_f32_16x16x32_bf16 v[64:67], v[212:215], v[152:155], v[64:67]
	v_mfma_f32_16x16x32_bf16 v[60:63], v[246:249], v[152:155], v[60:63]
	v_mfma_f32_16x16x32_bf16 v[56:59], v[212:215], v[160:163], v[56:59]
	v_mfma_f32_16x16x32_bf16 v[52:55], v[246:249], v[160:163], v[52:55]
	v_mfma_f32_16x16x32_bf16 v[48:51], v[212:215], v[168:171], v[48:51]
	v_mfma_f32_16x16x32_bf16 v[44:47], v[246:249], v[168:171], v[44:47]
	v_mfma_f32_16x16x32_bf16 v[40:43], v[212:215], v[204:207], v[40:43]
	v_mfma_f32_16x16x32_bf16 v[36:39], v[246:249], v[204:207], v[36:39]
	s_mov_b32 m0, s48
	s_barrier
	ds_read_b128 v[148:151], v240 offset:49152
	ds_read_b128 v[152:155], v240 offset:50176
	ds_read_b128 v[156:159], v240 offset:51200
	ds_read_b128 v[160:163], v240 offset:52224
	ds_read_b128 v[164:167], v240 offset:53248
	ds_read_b128 v[168:171], v240 offset:54272
	ds_read_b128 v[172:175], v240 offset:55296
	s_add_u32 s98, s46, 0x80
	s_addc_u32 s99, s47, 0
	global_load_lds_dwordx4 v0, s[98:99]
	s_mov_b32 m0, s50
	ds_read_b128 v[204:207], v240 offset:56320
	global_load_lds_dwordx4 v178, s[98:99]
	s_barrier
	s_waitcnt lgkmcnt(0)
	v_mfma_f32_16x16x32_bf16 v[96:99], v[132:135], v[148:151], v[96:99]
	v_mfma_f32_16x16x32_bf16 v[92:95], v[140:143], v[148:151], v[92:95]
	v_mfma_f32_16x16x32_bf16 v[88:91], v[132:135], v[156:159], v[88:91]
	v_mfma_f32_16x16x32_bf16 v[84:87], v[140:143], v[156:159], v[84:87]
	v_mfma_f32_16x16x32_bf16 v[80:83], v[132:135], v[164:167], v[80:83]
	v_mfma_f32_16x16x32_bf16 v[76:79], v[140:143], v[164:167], v[76:79]
	v_mfma_f32_16x16x32_bf16 v[72:75], v[132:135], v[172:175], v[72:75]
	v_mfma_f32_16x16x32_bf16 v[68:71], v[140:143], v[172:175], v[68:71]
	v_mfma_f32_16x16x32_bf16 v[96:99], v[136:139], v[152:155], v[96:99]
	v_mfma_f32_16x16x32_bf16 v[92:95], v[144:147], v[152:155], v[92:95]
	v_mfma_f32_16x16x32_bf16 v[88:91], v[136:139], v[160:163], v[88:91]
	v_mfma_f32_16x16x32_bf16 v[84:87], v[144:147], v[160:163], v[84:87]
	v_mfma_f32_16x16x32_bf16 v[80:83], v[136:139], v[168:171], v[80:83]
	v_mfma_f32_16x16x32_bf16 v[76:79], v[144:147], v[168:171], v[76:79]
	v_mfma_f32_16x16x32_bf16 v[72:75], v[136:139], v[204:207], v[72:75]
	v_mfma_f32_16x16x32_bf16 v[68:71], v[144:147], v[204:207], v[68:71]
	s_barrier
	s_add_i32 m0, s67, 0x1c000
	s_add_u32 s24, s44, 0x40080
	s_addc_u32 s25, s45, 0
	global_load_lds_dwordx4 v176, s[24:25]
	s_add_i32 m0, s67, 0x1e000
	s_waitcnt vmcnt(5)
	global_load_lds_dwordx4 v180, s[24:25]
	s_barrier
	v_mfma_f32_16x16x32_bf16 v[32:35], v[208:211], v[148:151], v[32:35]
	v_mfma_f32_16x16x32_bf16 v[28:31], v[242:245], v[148:151], v[28:31]
	v_mfma_f32_16x16x32_bf16 v[24:27], v[208:211], v[156:159], v[24:27]
	v_mfma_f32_16x16x32_bf16 v[20:23], v[242:245], v[156:159], v[20:23]
	v_mfma_f32_16x16x32_bf16 v[16:19], v[208:211], v[164:167], v[16:19]
	v_mfma_f32_16x16x32_bf16 v[12:15], v[242:245], v[164:167], v[12:15]
	v_mfma_f32_16x16x32_bf16 v[8:11], v[208:211], v[172:175], v[8:11]
	v_mfma_f32_16x16x32_bf16 v[4:7], v[242:245], v[172:175], v[4:7]
	v_mfma_f32_16x16x32_bf16 v[32:35], v[212:215], v[152:155], v[32:35]
	v_mfma_f32_16x16x32_bf16 v[28:31], v[246:249], v[152:155], v[28:31]
	v_mfma_f32_16x16x32_bf16 v[24:27], v[212:215], v[160:163], v[24:27]
	v_mfma_f32_16x16x32_bf16 v[20:23], v[246:249], v[160:163], v[20:23]
	v_mfma_f32_16x16x32_bf16 v[16:19], v[212:215], v[168:171], v[16:19]
	v_mfma_f32_16x16x32_bf16 v[12:15], v[246:249], v[168:171], v[12:15]
	v_mfma_f32_16x16x32_bf16 v[8:11], v[212:215], v[204:207], v[8:11]
	v_mfma_f32_16x16x32_bf16 v[4:7], v[246:249], v[204:207], v[4:7]
	s_add_i32 s22, s22, 2
	s_add_u32 s0, s0, 0x100
	s_addc_u32 s1, s1, 0
	s_add_u32 s20, s20, 0x100
	s_addc_u32 s21, s21, 0
	s_cmp_gt_u32 s22, 13
	s_barrier
	s_cbranch_scc0 .LBB0_427
	s_add_i32 s0, s61, -8
	s_cmp_lt_u32 s0, 12
	s_mov_b64 s[0:1], -1
	s_cbranch_scc1 .LBB0_451
	s_cmp_gt_i32 s61, 33
	s_cselect_b64 s[64:65], -1, 0
	s_lshl_b32 s0, s61, 8
	s_lshl_b32 s53, s60, 8
	s_add_i32 s1, s0, 0xffffee00
	s_cmp_lt_i32 s61, 26
	v_cndmask_b32_e64 v2, 0, 1, s[36:37]
	s_cselect_b32 s62, s0, s1
	s_mov_b64 s[0:1], -1
	s_and_b64 vcc, exec, s[64:65]
	v_cmp_ne_u32_e64 s[44:45], 1, v2
	s_cbranch_vccz .LBB0_433
	s_and_b64 vcc, exec, s[44:45]
	s_cbranch_vccnz .LBB0_432
	v_add_u32_e32 v132, s53, v185
	v_ashrrev_i32_e32 v133, 31, v132
	v_lshlrev_b64 v[140:141], 7, v[132:133]
	global_load_dwordx4 v[204:207], v[188:189], off offset:16
	global_load_dwordx4 v[208:211], v[188:189], off
	s_mov_b32 s3, 0xbfb8aa3b
	s_mov_b32 s2, 0x800000
	s_mov_b32 s4, 0x3f317217
	s_mov_b32 s5, 0x7f800000
	s_waitcnt vmcnt(0)
	v_mov_b32_e32 v132, v204
	v_mov_b32_e32 v133, v205
	v_mov_b32_e32 v134, v206
	v_mov_b32_e32 v135, v207
	v_mov_b32_e32 v136, v208
	v_mov_b32_e32 v137, v209
	v_mov_b32_e32 v138, v210
	v_mov_b32_e32 v139, v211
	v_add_f32_e32 v147, v126, v134
	v_add_f32_e32 v2, v128, v136
	v_max_f32_e32 v142, 0, v2
	v_mul_f32_e64 v2, |v2|, s3
	v_exp_f32_e32 v2, v2
	v_add_f32_e32 v136, v124, v132
	v_add_f32_e32 v149, v127, v135
	v_add_f32_e32 v2, 1.0, v2
	v_cmp_gt_f32_e32 vcc, s2, v2
	s_nop 1
	v_cndmask_b32_e64 v132, 0, 32, vcc
	v_ldexp_f32 v2, v2, v132
	v_log_f32_e32 v2, v2
	s_nop 0
	v_mul_f32_e32 v132, 0x3f317217, v2
	v_fma_f32 v132, v2, s4, -v132
	v_fmac_f32_e32 v132, 0x3377d1cf, v2
	v_fmac_f32_e32 v132, 0x3f317217, v2
	v_cmp_lt_f32_e64 s[0:1], |v2|, s5
	s_nop 1
	v_cndmask_b32_e64 v2, v2, v132, s[0:1]
	v_cndmask_b32_e32 v132, 0, v228, vcc
	v_sub_f32_e32 v144, v2, v132
	v_mul_f32_e64 v2, |v136|, s3
	v_exp_f32_e32 v2, v2
	v_max_f32_e32 v132, 0, v136
	v_add_f32_e32 v2, 1.0, v2
	v_cmp_gt_f32_e32 vcc, s2, v2
	s_nop 1
	v_cndmask_b32_e64 v136, 0, 32, vcc
	v_ldexp_f32 v2, v2, v136
	v_log_f32_e32 v2, v2
	s_nop 0
	v_mul_f32_e32 v136, 0x3f317217, v2
	v_fma_f32 v136, v2, s4, -v136
	v_fmac_f32_e32 v136, 0x3377d1cf, v2
	v_fmac_f32_e32 v136, 0x3f317217, v2
	v_cmp_lt_f32_e64 s[0:1], |v2|, s5
	s_nop 1
	v_cndmask_b32_e64 v2, v2, v136, s[0:1]
	v_cndmask_b32_e32 v136, 0, v228, vcc
	v_sub_f32_e32 v136, v2, v136
	v_add_f32_e32 v2, v129, v137
	v_max_f32_e32 v143, 0, v2
	v_mul_f32_e64 v2, |v2|, s3
	v_exp_f32_e32 v2, v2
	v_add_f32_e32 v137, v125, v133
	v_add_f32_e32 v2, 1.0, v2
	v_cmp_gt_f32_e32 vcc, s2, v2
	s_nop 1
	v_cndmask_b32_e64 v133, 0, 32, vcc
	v_ldexp_f32 v2, v2, v133
	v_log_f32_e32 v2, v2
	s_nop 0
	v_mul_f32_e32 v133, 0x3f317217, v2
	v_fma_f32 v133, v2, s4, -v133
	v_fmac_f32_e32 v133, 0x3377d1cf, v2
	v_fmac_f32_e32 v133, 0x3f317217, v2
	v_cmp_lt_f32_e64 s[0:1], |v2|, s5
	s_nop 1
	v_cndmask_b32_e64 v2, v2, v133, s[0:1]
	v_cndmask_b32_e32 v133, 0, v228, vcc
	v_sub_f32_e32 v145, v2, v133
	v_mul_f32_e64 v2, |v137|, s3
	v_exp_f32_e32 v2, v2
	v_max_f32_e32 v133, 0, v137
	v_pk_add_f32 v[142:143], v[142:143], v[144:145]
	v_add_f32_e32 v2, 1.0, v2
	v_cmp_gt_f32_e32 vcc, s2, v2
	s_nop 1
	v_cndmask_b32_e64 v137, 0, 32, vcc
	v_ldexp_f32 v2, v2, v137
	v_log_f32_e32 v2, v2
	s_nop 0
	v_mul_f32_e32 v137, 0x3f317217, v2
	v_fma_f32 v137, v2, s4, -v137
	v_fmac_f32_e32 v137, 0x3377d1cf, v2
	v_fmac_f32_e32 v137, 0x3f317217, v2
	v_cmp_lt_f32_e64 s[0:1], |v2|, s5
	s_nop 1
	v_cndmask_b32_e64 v2, v2, v137, s[0:1]
	v_cndmask_b32_e32 v137, 0, v228, vcc
	v_sub_f32_e32 v137, v2, v137
	v_add_f32_e32 v2, v130, v138
	v_max_f32_e32 v138, 0, v2
	v_mul_f32_e64 v2, |v2|, s3
	v_exp_f32_e32 v2, v2
	v_pk_add_f32 v[132:133], v[132:133], v[136:137]
	v_lshl_add_u64 v[136:137], v[190:191], 0, v[140:141]
	v_add_f32_e32 v2, 1.0, v2
	v_cmp_gt_f32_e32 vcc, s2, v2
	s_nop 1
	v_cndmask_b32_e64 v134, 0, 32, vcc
	v_ldexp_f32 v2, v2, v134
	v_log_f32_e32 v2, v2
	s_nop 0
	v_mul_f32_e32 v134, 0x3f317217, v2
	v_fma_f32 v134, v2, s4, -v134
	v_fmac_f32_e32 v134, 0x3377d1cf, v2
	v_fmac_f32_e32 v134, 0x3f317217, v2
	v_cmp_lt_f32_e64 s[0:1], |v2|, s5
	s_nop 1
	v_cndmask_b32_e64 v2, v2, v134, s[0:1]
	v_cndmask_b32_e32 v134, 0, v228, vcc
	v_sub_f32_e32 v146, v2, v134
	v_mul_f32_e64 v2, |v147|, s3
	v_exp_f32_e32 v2, v2
	v_max_f32_e32 v134, 0, v147
	v_add_f32_e32 v2, 1.0, v2
	v_cmp_gt_f32_e32 vcc, s2, v2
	s_nop 1
	v_cndmask_b32_e64 v147, 0, 32, vcc
	v_ldexp_f32 v2, v2, v147
	v_log_f32_e32 v2, v2
	s_nop 0
	v_mul_f32_e32 v147, 0x3f317217, v2
	v_fma_f32 v147, v2, s4, -v147
	v_fmac_f32_e32 v147, 0x3377d1cf, v2
	v_fmac_f32_e32 v147, 0x3f317217, v2
	v_cmp_lt_f32_e64 s[0:1], |v2|, s5
	s_nop 1
	v_cndmask_b32_e64 v2, v2, v147, s[0:1]
	v_cndmask_b32_e32 v147, 0, v228, vcc
	v_sub_f32_e32 v148, v2, v147
	v_add_f32_e32 v2, v131, v139
	v_max_f32_e32 v139, 0, v2
	v_mul_f32_e64 v2, |v2|, s3
	v_exp_f32_e32 v2, v2
	s_nop 0
	v_add_f32_e32 v2, 1.0, v2
	v_cmp_gt_f32_e32 vcc, s2, v2
	s_nop 1
	v_cndmask_b32_e64 v135, 0, 32, vcc
	v_ldexp_f32 v2, v2, v135
	v_log_f32_e32 v2, v2
	s_nop 0
	v_mul_f32_e32 v135, 0x3f317217, v2
	v_fma_f32 v135, v2, s4, -v135
	v_fmac_f32_e32 v135, 0x3377d1cf, v2
	v_fmac_f32_e32 v135, 0x3f317217, v2
	v_cmp_lt_f32_e64 s[0:1], |v2|, s5
	s_nop 1
	v_cndmask_b32_e64 v2, v2, v135, s[0:1]
	v_cndmask_b32_e32 v135, 0, v228, vcc
	v_sub_f32_e32 v147, v2, v135
	v_mul_f32_e64 v2, |v149|, s3
	v_exp_f32_e32 v2, v2
	v_pk_add_f32 v[144:145], v[138:139], v[146:147]
	v_max_f32_e32 v135, 0, v149
	v_add_f32_e32 v2, 1.0, v2
	v_cmp_gt_f32_e32 vcc, s2, v2
	s_nop 1
	v_cndmask_b32_e64 v138, 0, 32, vcc
	v_ldexp_f32 v2, v2, v138
	v_log_f32_e32 v2, v2
	s_nop 0
	v_mul_f32_e32 v138, 0x3f317217, v2
	v_fma_f32 v138, v2, s4, -v138
	v_fmac_f32_e32 v138, 0x3377d1cf, v2
	v_fmac_f32_e32 v138, 0x3f317217, v2
	v_cmp_lt_f32_e64 s[0:1], |v2|, s5
	s_nop 1
	v_cndmask_b32_e64 v2, v2, v138, s[0:1]
	v_cndmask_b32_e32 v138, 0, v228, vcc
	v_sub_f32_e32 v149, v2, v138
	v_pk_add_f32 v[134:135], v[134:135], v[148:149]
	global_store_dwordx4 v[136:137], v[142:145], off
	global_store_dwordx4 v[136:137], v[132:135], off offset:16
